# accumulator zeroing with v_pk_mov_b32 pairs + duplicate lgkmcnt waits removed (on top of setprio removal, rebalanced reads, vmcnt(10) guards, Mx rewrite)
# speedup vs baseline: 1.0191x; 1.0106x over previous
; #define PG8_STAGE(bufoff, gbase, voff) do { _Pragma("unroll") for (int _i = 0; _i < 2; ++_i) \
;         __builtin_amdgcn_global_load_lds((const unsigned*)((const char*)(gbase) + (voff)[_i]), (LAS unsigned*)(lds + (bufoff) + ldsw + _i * 8192), 16, 0, 0); } while (0)
; #define PG8_STAGE_A(bufoff, ptr, half, rev) do { if (REVA && (rev)) { const char* _p = (ptr) - ((half) ? hstepA : 0); PG8_STAGE(bufoff, _p, voffAr); } else { const char* _p = (ptr) + ((half) ? hstepA : 0); PG8_STAGE(bufoff, _p, voffA); } } while (0)
; #define PG8_LDA(dst, b, h) do { _Pragma("unroll") for (int m = 0; m < 4; ++m) _Pragma("unroll") for (int k = 0; k < 2; ++k) dst[m][k] = *(const LAS bf16x8*)(lds + PG8_SA(b, h) + aoff + m * 2048 + k * 1024); } while (0)
; #define PG8_LDB(dst, b, h) do { _Pragma("unroll") for (int n = 0; n < 2; ++n) _Pragma("unroll") for (int k = 0; k < 2; ++k) dst[n][k] = *(const LAS bf16x8*)(lds + PG8_SB(b, h) + boff + n * 2048 + k * 1024); } while (0)
; #define PG8_WAIT_L(n) asm volatile("s_waitcnt lgkmcnt(" #n ")" ::: "memory")
; #define PG8_BAR __builtin_amdgcn_s_barrier()
; #define PG8_SCHED __builtin_amdgcn_sched_barrier(0)
;     ...
;         for (int t = 0; t < nt; t += 2) {
;             const bool last = (t == nt - 2);
;             const char* a1 = PG8_APTR(cA, cAr, t + 1); const bool r1 = REVA && ((t + 1) & 4);
;             const char* a2 = last ? nA : PG8_APTR(cA, cAr, t + 2); const bool r2 = REVA && !last && ((t + 2) & 4);
;             const char* a3 = last ? nA + kstep : PG8_APTR(cA, cAr, t + 3); const bool r3 = REVA && !last && ((t + 3) & 4);
;             const char* b2 = last ? nB : cB + (size_t)(t + 2) * kstep; const char* b3 = b2 + kstep; const size_t hb2 = last ? nHb : cHb;
;             PG8_LDB(B0, 0, 0); PG8_SCHED; PG8_LDA(At, 0, 0); PG8_STAGE_A(PG8_SA(1, 1), a1, 1, r1);
;             PG8_WAIT_L(8); PG8_BAR; PG8_WAIT_L(0); PG8_MMA(0, 0, At, B0); PG8_BAR; PG8_SCHED;
;             PG8_LDB(B1, 0, 1); PG8_STAGE(PG8_SB(0, 0), b2, voffB);
;             PG8_BAR; PG8_WAIT_L(0); PG8_MMA(0, 1, At, B1); PG8_BAR;
;     ...
; #pragma unroll
;         for (int a = 0; a < 2; ++a)
; #pragma unroll
;             for (int b = 0; b < 2; ++b)
; #pragma unroll
;                 for (int m = 0; m < 4; ++m)
; #pragma unroll
;                     for (int n = 0; n < 2; ++n) acc[a][b][m][n] = (f32x4){0.f, 0.f, 0.f, 0.f};
.LBB0_233:
	s_add_u32 s3, s0, 0x80
	s_addc_u32 s6, s1, 0
	s_add_u32 s8, s38, 0x80080
	s_addc_u32 s9, s39, 0
	s_add_u32 s7, s20, 0x100
	v_mov_b32_e32 v0, 0
	v_lshl_add_u64 v[88:89], s[8:9], 0, v[150:151]
	v_lshl_add_u64 v[90:91], s[8:9], 0, v[152:153]
	s_addc_u32 s8, s21, 0
	s_mov_b32 s9, -2
	s_mov_b64 vcc, 0
	v_mov_b32_e32 v1, v0
	v_pk_mov_b32 v[2:3], v[0:1], v[0:1]
	v_pk_mov_b32 v[4:5], v[0:1], v[0:1]
	v_pk_mov_b32 v[6:7], v[0:1], v[0:1]
	v_pk_mov_b32 v[8:9], v[0:1], v[0:1]
	v_pk_mov_b32 v[10:11], v[0:1], v[0:1]
	v_pk_mov_b32 v[12:13], v[0:1], v[0:1]
	v_pk_mov_b32 v[14:15], v[0:1], v[0:1]
	v_pk_mov_b32 v[16:17], v[0:1], v[0:1]
	v_pk_mov_b32 v[18:19], v[0:1], v[0:1]
	v_pk_mov_b32 v[20:21], v[0:1], v[0:1]
	v_pk_mov_b32 v[22:23], v[0:1], v[0:1]
	v_pk_mov_b32 v[24:25], v[0:1], v[0:1]
	v_pk_mov_b32 v[26:27], v[0:1], v[0:1]
	v_pk_mov_b32 v[28:29], v[0:1], v[0:1]
	v_pk_mov_b32 v[30:31], v[0:1], v[0:1]
	v_pk_mov_b32 v[32:33], v[0:1], v[0:1]
	v_pk_mov_b32 v[34:35], v[0:1], v[0:1]
	v_pk_mov_b32 v[36:37], v[0:1], v[0:1]
	v_pk_mov_b32 v[38:39], v[0:1], v[0:1]
	v_pk_mov_b32 v[40:41], v[0:1], v[0:1]
	v_pk_mov_b32 v[42:43], v[0:1], v[0:1]
	v_pk_mov_b32 v[44:45], v[0:1], v[0:1]
	v_pk_mov_b32 v[46:47], v[0:1], v[0:1]
	v_pk_mov_b32 v[48:49], v[0:1], v[0:1]
	v_pk_mov_b32 v[50:51], v[0:1], v[0:1]
	v_pk_mov_b32 v[52:53], v[0:1], v[0:1]
	v_pk_mov_b32 v[54:55], v[0:1], v[0:1]
	v_pk_mov_b32 v[56:57], v[0:1], v[0:1]
	v_pk_mov_b32 v[58:59], v[0:1], v[0:1]
	v_pk_mov_b32 v[60:61], v[0:1], v[0:1]
	v_pk_mov_b32 v[62:63], v[0:1], v[0:1]
	v_pk_mov_b32 v[64:65], v[0:1], v[0:1]
	v_pk_mov_b32 v[66:67], v[0:1], v[0:1]
	v_pk_mov_b32 v[68:69], v[0:1], v[0:1]
	v_pk_mov_b32 v[70:71], v[0:1], v[0:1]
	v_pk_mov_b32 v[72:73], v[0:1], v[0:1]
	v_pk_mov_b32 v[74:75], v[0:1], v[0:1]
	v_pk_mov_b32 v[76:77], v[0:1], v[0:1]
	v_pk_mov_b32 v[78:79], v[0:1], v[0:1]
	v_pk_mov_b32 v[80:81], v[0:1], v[0:1]
	v_pk_mov_b32 v[82:83], v[0:1], v[0:1]
	v_pk_mov_b32 v[84:85], v[0:1], v[0:1]
	v_pk_mov_b32 v[86:87], v[0:1], v[0:1]
	v_pk_mov_b32 v[100:101], v[0:1], v[0:1]
	v_pk_mov_b32 v[102:103], v[0:1], v[0:1]
	v_pk_mov_b32 v[104:105], v[0:1], v[0:1]
	v_pk_mov_b32 v[106:107], v[0:1], v[0:1]
	v_pk_mov_b32 v[108:109], v[0:1], v[0:1]
	v_pk_mov_b32 v[110:111], v[0:1], v[0:1]
	v_pk_mov_b32 v[112:113], v[0:1], v[0:1]
	v_pk_mov_b32 v[114:115], v[0:1], v[0:1]
	v_pk_mov_b32 v[116:117], v[0:1], v[0:1]
	v_pk_mov_b32 v[118:119], v[0:1], v[0:1]
	v_pk_mov_b32 v[120:121], v[0:1], v[0:1]
	v_pk_mov_b32 v[122:123], v[0:1], v[0:1]
	v_pk_mov_b32 v[124:125], v[0:1], v[0:1]
	v_pk_mov_b32 v[126:127], v[0:1], v[0:1]
	v_pk_mov_b32 v[128:129], v[0:1], v[0:1]
	v_pk_mov_b32 v[130:131], v[0:1], v[0:1]
	v_pk_mov_b32 v[132:133], v[0:1], v[0:1]
	v_pk_mov_b32 v[134:135], v[0:1], v[0:1]
	v_pk_mov_b32 v[136:137], v[0:1], v[0:1]
	v_pk_mov_b32 v[138:139], v[0:1], v[0:1]
	s_nop 0
	v_add_u32_e32 v154, 0x10000, v156
	ds_read_b128 v[92:95], v154
	ds_read_b128 v[96:99], v154 offset:1024
	ds_read_b128 v[172:175], v154 offset:2048
	ds_read_b128 v[176:179], v154 offset:3072
.LBB0_234:
	s_add_u32 s10, s38, vcc_lo
	s_addc_u32 s11, s39, vcc_hi
	s_add_u32 s16, s10, 0x100
	s_addc_u32 s17, s11, 0
	s_add_u32 s10, s10, 0x180
	s_addc_u32 s11, s11, 0
	s_add_u32 s14, s7, vcc_lo
	s_addc_u32 s15, s8, vcc_hi
	s_add_i32 s27, 0, 0x10000
	s_cmpk_eq_i32 vcc_lo, 0xf00
	s_cselect_b32 s15, s71, s15
	s_cselect_b32 s14, s70, s14
	s_cselect_b32 s21, s1, s17
	s_cselect_b32 s20, s0, s16
	s_cselect_b32 s17, s6, s11
	s_cselect_b32 s16, s3, s10
	v_lshl_add_u64 v[154:155], v[88:89], 0, vcc
	s_add_i32 m0, s91, 0xc000
	ds_read_b128 v[180:183], v171
	ds_read_b128 v[204:207], v171 offset:1024
	ds_read_b128 v[208:211], v171 offset:2048
	ds_read_b128 v[212:215], v171 offset:3072
	ds_read_b128 v[216:219], v171 offset:4096
	ds_read_b128 v[220:223], v171 offset:5120
	ds_read_b128 v[224:227], v171 offset:6144
	ds_read_b128 v[228:231], v171 offset:7168
	global_load_lds_dwordx4 v[154:155], off
	v_lshl_add_u64 v[154:155], v[90:91], 0, vcc
	s_add_i32 m0, s91, 0xe000
	s_nop 0
	global_load_lds_dwordx4 v[154:155], off
	s_waitcnt lgkmcnt(8)
	s_waitcnt vmcnt(10)
	s_barrier
	s_waitcnt lgkmcnt(0)
	v_mfma_f32_16x16x32_bf16 v[104:107], v[92:95], v[180:183], v[104:107]
	v_mfma_f32_16x16x32_bf16 v[136:139], v[172:175], v[180:183], v[136:139]
	v_mfma_f32_16x16x32_bf16 v[84:87], v[92:95], v[208:211], v[84:87]
	v_mfma_f32_16x16x32_bf16 v[128:131], v[172:175], v[208:211], v[128:131]
	v_mfma_f32_16x16x32_bf16 v[76:79], v[92:95], v[216:219], v[76:79]
	v_mfma_f32_16x16x32_bf16 v[120:123], v[172:175], v[216:219], v[120:123]
	v_mfma_f32_16x16x32_bf16 v[68:71], v[92:95], v[224:227], v[68:71]
	v_mfma_f32_16x16x32_bf16 v[112:115], v[172:175], v[224:227], v[112:115]
	v_mfma_f32_16x16x32_bf16 v[104:107], v[96:99], v[204:207], v[104:107]
	v_mfma_f32_16x16x32_bf16 v[136:139], v[176:179], v[204:207], v[136:139]
	v_mfma_f32_16x16x32_bf16 v[84:87], v[96:99], v[212:215], v[84:87]
	v_mfma_f32_16x16x32_bf16 v[128:131], v[176:179], v[212:215], v[128:131]
	v_mfma_f32_16x16x32_bf16 v[76:79], v[96:99], v[220:223], v[76:79]
	v_mfma_f32_16x16x32_bf16 v[120:123], v[176:179], v[220:223], v[120:123]
	v_mfma_f32_16x16x32_bf16 v[68:71], v[96:99], v[228:231], v[68:71]
	v_mfma_f32_16x16x32_bf16 v[112:115], v[176:179], v[228:231], v[112:115]
	s_barrier
	s_add_i32 s37, 0, 0x14000
	v_add_u32_e32 v154, s37, v156
	s_add_i32 s10, s27, s90
	ds_read_b128 v[232:235], v154
	ds_read_b128 v[236:239], v154 offset:1024
	ds_read_b128 v[240:243], v154 offset:2048
	ds_read_b128 v[244:247], v154 offset:3072
	v_lshl_add_u64 v[154:155], s[14:15], 0, v[160:161]
	s_mov_b32 m0, s10
	v_lshl_add_u64 v[184:185], s[14:15], 0, v[140:141]
	global_load_lds_dwordx4 v[154:155], off
	s_add_i32 m0, s10, 0x2000
	s_nop 0
	global_load_lds_dwordx4 v[184:185], off
	s_waitcnt vmcnt(10)
	s_barrier
; #define PG8_STAGE(bufoff, gbase, voff) do { _Pragma("unroll") for (int _i = 0; _i < 2; ++_i) \
;         __builtin_amdgcn_global_load_lds((const unsigned*)((const char*)(gbase) + (voff)[_i]), (LAS unsigned*)(lds + (bufoff) + ldsw + _i * 8192), 16, 0, 0); } while (0)
; #define PG8_STAGE_A(bufoff, ptr, half, rev) do { if (REVA && (rev)) { const char* _p = (ptr) - ((half) ? hstepA : 0); PG8_STAGE(bufoff, _p, voffAr); } else { const char* _p = (ptr) + ((half) ? hstepA : 0); PG8_STAGE(bufoff, _p, voffA); } } while (0)
; #define PG8_LDA(dst, b, h) do { _Pragma("unroll") for (int m = 0; m < 4; ++m) _Pragma("unroll") for (int k = 0; k < 2; ++k) dst[m][k] = *(const LAS bf16x8*)(lds + PG8_SA(b, h) + aoff + m * 2048 + k * 1024); } while (0)
; #define PG8_LDB(dst, b, h) do { _Pragma("unroll") for (int n = 0; n < 2; ++n) _Pragma("unroll") for (int k = 0; k < 2; ++k) dst[n][k] = *(const LAS bf16x8*)(lds + PG8_SB(b, h) + boff + n * 2048 + k * 1024); } while (0)
; #define PG8_MMA(ai, bj, At, Bt) do { __builtin_amdgcn_s_setprio(1); _Pragma("unroll") for (int m = 0; m < 4; ++m) _Pragma("unroll") for (int n = 0; n < 2; ++n) _Pragma("unroll") for (int k = 0; k < 2; ++k) \
;         acc[ai][bj][m][n] = __builtin_amdgcn_mfma_f32_16x16x32_bf16(Bt[n][k], At[m][k], acc[ai][bj][m][n], 0, 0, 0); __builtin_amdgcn_s_setprio(0); } while (0)
; #define PG8_WAIT_V(n) asm volatile("s_waitcnt vmcnt(" #n ")" ::: "memory")
; #define PG8_WAIT_L(n) asm volatile("s_waitcnt lgkmcnt(" #n ")" ::: "memory")
; #define PG8_BAR __builtin_amdgcn_s_barrier()
; #define PG8_SCHED __builtin_amdgcn_sched_barrier(0)
;     ...
;             PG8_BAR; PG8_WAIT_L(0); PG8_MMA(0, 1, At, B1); PG8_BAR;
;             PG8_LDA(At, 0, 1); PG8_STAGE_A(PG8_SA(0, 0), a2, 0, r2);
;             PG8_BAR; PG8_WAIT_L(0); PG8_MMA(1, 0, At, B0); PG8_BAR; PG8_SCHED;
;             PG8_STAGE(PG8_SB(0, 1), b2 + hb2, voffB);
;             PG8_WAIT_V(6); PG8_BAR; PG8_MMA(1, 1, At, B1); PG8_BAR;
;             PG8_LDB(B0, 1, 0); PG8_SCHED; PG8_LDA(At, 1, 0); PG8_STAGE_A(PG8_SA(0, 1), a2, 1, r2);
;             PG8_WAIT_L(8); PG8_BAR; PG8_WAIT_L(0); PG8_MMA(0, 0, At, B0); PG8_BAR; PG8_SCHED;
	s_waitcnt lgkmcnt(0)
	v_mfma_f32_16x16x32_bf16 v[132:135], v[232:235], v[180:183], v[132:135]
	v_mfma_f32_16x16x32_bf16 v[100:103], v[240:243], v[180:183], v[100:103]
	v_mfma_f32_16x16x32_bf16 v[124:127], v[232:235], v[208:211], v[124:127]
	v_mfma_f32_16x16x32_bf16 v[80:83], v[240:243], v[208:211], v[80:83]
	v_mfma_f32_16x16x32_bf16 v[116:119], v[232:235], v[216:219], v[116:119]
	v_mfma_f32_16x16x32_bf16 v[72:75], v[240:243], v[216:219], v[72:75]
	v_mfma_f32_16x16x32_bf16 v[108:111], v[232:235], v[224:227], v[108:111]
	v_mfma_f32_16x16x32_bf16 v[64:67], v[240:243], v[224:227], v[64:67]
	v_mfma_f32_16x16x32_bf16 v[132:135], v[236:239], v[204:207], v[132:135]
	v_mfma_f32_16x16x32_bf16 v[100:103], v[244:247], v[204:207], v[100:103]
	v_mfma_f32_16x16x32_bf16 v[124:127], v[236:239], v[212:215], v[124:127]
	v_mfma_f32_16x16x32_bf16 v[80:83], v[244:247], v[212:215], v[80:83]
	v_mfma_f32_16x16x32_bf16 v[116:119], v[236:239], v[220:223], v[116:119]
	v_mfma_f32_16x16x32_bf16 v[72:75], v[244:247], v[220:223], v[72:75]
	v_mfma_f32_16x16x32_bf16 v[108:111], v[236:239], v[228:231], v[108:111]
	v_mfma_f32_16x16x32_bf16 v[64:67], v[244:247], v[228:231], v[64:67]
	s_mov_b32 m0, s91
	v_lshl_add_u64 v[190:191], s[20:21], 0, v[160:161]
	s_barrier
	ds_read_b128 v[180:183], v171 offset:16384
	ds_read_b128 v[204:207], v171 offset:17408
	ds_read_b128 v[208:211], v171 offset:18432
	ds_read_b128 v[212:215], v171 offset:19456
	ds_read_b128 v[216:219], v171 offset:20480
	ds_read_b128 v[220:223], v171 offset:21504
	ds_read_b128 v[224:227], v171 offset:22528
	ds_read_b128 v[228:231], v171 offset:23552
	global_load_lds_dwordx4 v[190:191], off
	v_lshl_add_u64 v[190:191], s[20:21], 0, v[140:141]
	s_mov_b32 m0, s92
	s_nop 0
	global_load_lds_dwordx4 v[190:191], off
	s_waitcnt vmcnt(10)
	s_barrier
	s_waitcnt lgkmcnt(0)
	v_mfma_f32_16x16x32_bf16 v[28:31], v[92:95], v[180:183], v[28:31]
	v_mfma_f32_16x16x32_bf16 v[60:63], v[172:175], v[180:183], v[60:63]
	v_mfma_f32_16x16x32_bf16 v[20:23], v[92:95], v[208:211], v[20:23]
	v_mfma_f32_16x16x32_bf16 v[52:55], v[172:175], v[208:211], v[52:55]
	v_mfma_f32_16x16x32_bf16 v[12:15], v[92:95], v[216:219], v[12:15]
	v_mfma_f32_16x16x32_bf16 v[44:47], v[172:175], v[216:219], v[44:47]
	v_mfma_f32_16x16x32_bf16 v[4:7], v[92:95], v[224:227], v[4:7]
	v_mfma_f32_16x16x32_bf16 v[36:39], v[172:175], v[224:227], v[36:39]
	v_mfma_f32_16x16x32_bf16 v[28:31], v[96:99], v[204:207], v[28:31]
	v_mfma_f32_16x16x32_bf16 v[60:63], v[176:179], v[204:207], v[60:63]
	v_mfma_f32_16x16x32_bf16 v[20:23], v[96:99], v[212:215], v[20:23]
	v_mfma_f32_16x16x32_bf16 v[52:55], v[176:179], v[212:215], v[52:55]
	v_mfma_f32_16x16x32_bf16 v[12:15], v[96:99], v[220:223], v[12:15]
	v_mfma_f32_16x16x32_bf16 v[44:47], v[176:179], v[220:223], v[44:47]
	v_mfma_f32_16x16x32_bf16 v[4:7], v[96:99], v[228:231], v[4:7]
	v_mfma_f32_16x16x32_bf16 v[36:39], v[176:179], v[228:231], v[36:39]
	s_barrier
	s_add_u32 s10, s14, 0x80000
	s_addc_u32 s11, s15, 0
	s_add_i32 s27, s37, s90
	v_lshl_add_u64 v[92:93], s[10:11], 0, v[160:161]
	s_mov_b32 m0, s27
	s_nop 0
	global_load_lds_dwordx4 v[92:93], off
	v_lshl_add_u64 v[92:93], s[10:11], 0, v[140:141]
	s_add_i32 m0, s27, 0x2000
	s_nop 0
	global_load_lds_dwordx4 v[92:93], off
	v_add_u32_e32 v176, 0x18000, v156
	ds_read_b128 v[92:95], v176
	ds_read_b128 v[96:99], v176 offset:1024
	ds_read_b128 v[172:175], v176 offset:2048
	ds_read_b128 v[176:179], v176 offset:3072
	s_waitcnt vmcnt(10)
	s_barrier
	v_mfma_f32_16x16x32_bf16 v[56:59], v[232:235], v[180:183], v[56:59]
	v_mfma_f32_16x16x32_bf16 v[24:27], v[240:243], v[180:183], v[24:27]
	v_mfma_f32_16x16x32_bf16 v[48:51], v[232:235], v[208:211], v[48:51]
	v_mfma_f32_16x16x32_bf16 v[16:19], v[240:243], v[208:211], v[16:19]
	v_mfma_f32_16x16x32_bf16 v[40:43], v[232:235], v[216:219], v[40:43]
	v_mfma_f32_16x16x32_bf16 v[8:11], v[240:243], v[216:219], v[8:11]
	v_mfma_f32_16x16x32_bf16 v[32:35], v[232:235], v[224:227], v[32:35]
	v_mfma_f32_16x16x32_bf16 v[0:3], v[240:243], v[224:227], v[0:3]
	v_mfma_f32_16x16x32_bf16 v[56:59], v[236:239], v[204:207], v[56:59]
	v_mfma_f32_16x16x32_bf16 v[24:27], v[244:247], v[204:207], v[24:27]
	v_mfma_f32_16x16x32_bf16 v[48:51], v[236:239], v[212:215], v[48:51]
	v_mfma_f32_16x16x32_bf16 v[16:19], v[244:247], v[212:215], v[16:19]
	v_mfma_f32_16x16x32_bf16 v[40:43], v[236:239], v[220:223], v[40:43]
	v_mfma_f32_16x16x32_bf16 v[8:11], v[244:247], v[220:223], v[8:11]
	v_mfma_f32_16x16x32_bf16 v[32:35], v[236:239], v[228:231], v[32:35]
	v_mfma_f32_16x16x32_bf16 v[0:3], v[244:247], v[228:231], v[0:3]
	s_add_i32 s27, 0, 0x18000
	s_barrier
	s_add_u32 s10, s20, 0x80000
	s_addc_u32 s11, s21, 0
	s_mov_b32 m0, s93
	v_lshl_add_u64 v[190:191], s[10:11], 0, v[160:161]
	ds_read_b128 v[180:183], v171 offset:32768
	ds_read_b128 v[204:207], v171 offset:33792
	ds_read_b128 v[208:211], v171 offset:34816
	ds_read_b128 v[212:215], v171 offset:35840
	ds_read_b128 v[216:219], v171 offset:36864
	ds_read_b128 v[220:223], v171 offset:37888
	ds_read_b128 v[224:227], v171 offset:38912
	ds_read_b128 v[228:231], v171 offset:39936
	global_load_lds_dwordx4 v[190:191], off
	v_lshl_add_u64 v[190:191], s[10:11], 0, v[140:141]
	s_mov_b32 m0, s94
	s_nop 0
	global_load_lds_dwordx4 v[190:191], off
	s_waitcnt lgkmcnt(8)
	s_waitcnt vmcnt(10)
	s_barrier
; #define PG8_STAGE(bufoff, gbase, voff) do { _Pragma("unroll") for (int _i = 0; _i < 2; ++_i) \
;         __builtin_amdgcn_global_load_lds((const unsigned*)((const char*)(gbase) + (voff)[_i]), (LAS unsigned*)(lds + (bufoff) + ldsw + _i * 8192), 16, 0, 0); } while (0)
; #define PG8_STAGE_A(bufoff, ptr, half, rev) do { if (REVA && (rev)) { const char* _p = (ptr) - ((half) ? hstepA : 0); PG8_STAGE(bufoff, _p, voffAr); } else { const char* _p = (ptr) + ((half) ? hstepA : 0); PG8_STAGE(bufoff, _p, voffA); } } while (0)
; #define PG8_LDA(dst, b, h) do { _Pragma("unroll") for (int m = 0; m < 4; ++m) _Pragma("unroll") for (int k = 0; k < 2; ++k) dst[m][k] = *(const LAS bf16x8*)(lds + PG8_SA(b, h) + aoff + m * 2048 + k * 1024); } while (0)
; #define PG8_LDB(dst, b, h) do { _Pragma("unroll") for (int n = 0; n < 2; ++n) _Pragma("unroll") for (int k = 0; k < 2; ++k) dst[n][k] = *(const LAS bf16x8*)(lds + PG8_SB(b, h) + boff + n * 2048 + k * 1024); } while (0)
; #define PG8_MMA(ai, bj, At, Bt) do { __builtin_amdgcn_s_setprio(1); _Pragma("unroll") for (int m = 0; m < 4; ++m) _Pragma("unroll") for (int n = 0; n < 2; ++n) _Pragma("unroll") for (int k = 0; k < 2; ++k) \
;         acc[ai][bj][m][n] = __builtin_amdgcn_mfma_f32_16x16x32_bf16(Bt[n][k], At[m][k], acc[ai][bj][m][n], 0, 0, 0); __builtin_amdgcn_s_setprio(0); } while (0)
; #define PG8_WAIT_V(n) asm volatile("s_waitcnt vmcnt(" #n ")" ::: "memory")
; #define PG8_WAIT_L(n) asm volatile("s_waitcnt lgkmcnt(" #n ")" ::: "memory")
; #define PG8_BAR __builtin_amdgcn_s_barrier()
; #define PG8_SCHED __builtin_amdgcn_sched_barrier(0)
;     ...
;             PG8_WAIT_L(8); PG8_BAR; PG8_WAIT_L(0); PG8_MMA(0, 0, At, B0); PG8_BAR; PG8_SCHED;
;             PG8_LDB(B1, 1, 1); PG8_STAGE(PG8_SB(1, 0), b3, voffB);
;             PG8_BAR; PG8_WAIT_L(0); PG8_MMA(0, 1, At, B1); PG8_BAR;
;             PG8_LDA(At, 1, 1); PG8_STAGE_A(PG8_SA(1, 0), a3, 0, r3);
;             PG8_BAR; PG8_WAIT_L(0); PG8_MMA(1, 0, At, B0); PG8_BAR; PG8_SCHED;
;             PG8_STAGE(PG8_SB(1, 1), b3 + hb2, voffB);
;             PG8_WAIT_V(6); PG8_BAR; PG8_MMA(1, 1, At, B1); PG8_BAR;
	s_waitcnt lgkmcnt(0)
	v_mfma_f32_16x16x32_bf16 v[104:107], v[92:95], v[180:183], v[104:107]
	v_mfma_f32_16x16x32_bf16 v[136:139], v[172:175], v[180:183], v[136:139]
	v_mfma_f32_16x16x32_bf16 v[84:87], v[92:95], v[208:211], v[84:87]
	v_mfma_f32_16x16x32_bf16 v[128:131], v[172:175], v[208:211], v[128:131]
	v_mfma_f32_16x16x32_bf16 v[76:79], v[92:95], v[216:219], v[76:79]
	v_mfma_f32_16x16x32_bf16 v[120:123], v[172:175], v[216:219], v[120:123]
	v_mfma_f32_16x16x32_bf16 v[68:71], v[92:95], v[224:227], v[68:71]
	v_mfma_f32_16x16x32_bf16 v[112:115], v[172:175], v[224:227], v[112:115]
	v_mfma_f32_16x16x32_bf16 v[104:107], v[96:99], v[204:207], v[104:107]
	v_mfma_f32_16x16x32_bf16 v[136:139], v[176:179], v[204:207], v[136:139]
	v_mfma_f32_16x16x32_bf16 v[84:87], v[96:99], v[212:215], v[84:87]
	v_mfma_f32_16x16x32_bf16 v[128:131], v[176:179], v[212:215], v[128:131]
	v_mfma_f32_16x16x32_bf16 v[76:79], v[96:99], v[220:223], v[76:79]
	v_mfma_f32_16x16x32_bf16 v[120:123], v[176:179], v[220:223], v[120:123]
	v_mfma_f32_16x16x32_bf16 v[68:71], v[96:99], v[228:231], v[68:71]
	v_mfma_f32_16x16x32_bf16 v[112:115], v[176:179], v[228:231], v[112:115]
	s_barrier
	s_add_i32 s20, 0, 0x1c000
	s_add_i32 s10, s27, s90
	v_add_u32_e32 v190, s20, v156
	v_lshl_add_u64 v[154:155], v[154:155], 0, s[28:29]
	s_mov_b32 m0, s10
	ds_read_b128 v[232:235], v190
	ds_read_b128 v[236:239], v190 offset:1024
	ds_read_b128 v[240:243], v190 offset:2048
	ds_read_b128 v[244:247], v190 offset:3072
	global_load_lds_dwordx4 v[154:155], off
	v_lshl_add_u64 v[154:155], v[184:185], 0, s[28:29]
	s_add_i32 m0, s10, 0x2000
	s_nop 0
	global_load_lds_dwordx4 v[154:155], off
	s_waitcnt vmcnt(10)
	s_barrier
	s_waitcnt lgkmcnt(0)
	v_mfma_f32_16x16x32_bf16 v[132:135], v[232:235], v[180:183], v[132:135]
	v_mfma_f32_16x16x32_bf16 v[100:103], v[240:243], v[180:183], v[100:103]
	v_mfma_f32_16x16x32_bf16 v[124:127], v[232:235], v[208:211], v[124:127]
	v_mfma_f32_16x16x32_bf16 v[80:83], v[240:243], v[208:211], v[80:83]
	v_mfma_f32_16x16x32_bf16 v[116:119], v[232:235], v[216:219], v[116:119]
	v_mfma_f32_16x16x32_bf16 v[72:75], v[240:243], v[216:219], v[72:75]
	v_mfma_f32_16x16x32_bf16 v[108:111], v[232:235], v[224:227], v[108:111]
	v_mfma_f32_16x16x32_bf16 v[64:67], v[240:243], v[224:227], v[64:67]
	v_mfma_f32_16x16x32_bf16 v[132:135], v[236:239], v[204:207], v[132:135]
	v_mfma_f32_16x16x32_bf16 v[100:103], v[244:247], v[204:207], v[100:103]
	v_mfma_f32_16x16x32_bf16 v[124:127], v[236:239], v[212:215], v[124:127]
	v_mfma_f32_16x16x32_bf16 v[80:83], v[244:247], v[212:215], v[80:83]
	v_mfma_f32_16x16x32_bf16 v[116:119], v[236:239], v[220:223], v[116:119]
	v_mfma_f32_16x16x32_bf16 v[72:75], v[244:247], v[220:223], v[72:75]
	v_mfma_f32_16x16x32_bf16 v[108:111], v[236:239], v[228:231], v[108:111]
	v_mfma_f32_16x16x32_bf16 v[64:67], v[244:247], v[228:231], v[64:67]
	s_mov_b32 m0, s95
	v_lshl_add_u64 v[154:155], s[16:17], 0, v[160:161]
	s_barrier
	ds_read_b128 v[180:183], v171 offset:49152
	ds_read_b128 v[204:207], v171 offset:50176
	ds_read_b128 v[208:211], v171 offset:51200
	ds_read_b128 v[212:215], v171 offset:52224
	ds_read_b128 v[216:219], v171 offset:53248
	ds_read_b128 v[220:223], v171 offset:54272
	ds_read_b128 v[224:227], v171 offset:55296
	ds_read_b128 v[228:231], v171 offset:56320
	global_load_lds_dwordx4 v[154:155], off
	v_lshl_add_u64 v[154:155], s[16:17], 0, v[140:141]
	s_mov_b32 m0, s96
	s_nop 0
	global_load_lds_dwordx4 v[154:155], off
	s_waitcnt vmcnt(10)
	s_barrier
	s_waitcnt lgkmcnt(0)
	v_mfma_f32_16x16x32_bf16 v[28:31], v[92:95], v[180:183], v[28:31]
	v_mfma_f32_16x16x32_bf16 v[60:63], v[172:175], v[180:183], v[60:63]
	v_mfma_f32_16x16x32_bf16 v[20:23], v[92:95], v[208:211], v[20:23]
	v_mfma_f32_16x16x32_bf16 v[52:55], v[172:175], v[208:211], v[52:55]
	v_mfma_f32_16x16x32_bf16 v[12:15], v[92:95], v[216:219], v[12:15]
	v_mfma_f32_16x16x32_bf16 v[44:47], v[172:175], v[216:219], v[44:47]
	v_mfma_f32_16x16x32_bf16 v[4:7], v[92:95], v[224:227], v[4:7]
	v_mfma_f32_16x16x32_bf16 v[36:39], v[172:175], v[224:227], v[36:39]
	v_mfma_f32_16x16x32_bf16 v[28:31], v[96:99], v[204:207], v[28:31]
	v_mfma_f32_16x16x32_bf16 v[60:63], v[176:179], v[204:207], v[60:63]
	v_mfma_f32_16x16x32_bf16 v[20:23], v[96:99], v[212:215], v[20:23]
	v_mfma_f32_16x16x32_bf16 v[52:55], v[176:179], v[212:215], v[52:55]
	v_mfma_f32_16x16x32_bf16 v[12:15], v[96:99], v[220:223], v[12:15]
	v_mfma_f32_16x16x32_bf16 v[44:47], v[176:179], v[220:223], v[44:47]
	v_mfma_f32_16x16x32_bf16 v[4:7], v[96:99], v[228:231], v[4:7]
	v_mfma_f32_16x16x32_bf16 v[36:39], v[176:179], v[228:231], v[36:39]
	s_barrier
	s_add_u32 s10, s14, 0x80080
	s_addc_u32 s11, s15, 0
	s_add_i32 s14, s20, s90
	v_lshl_add_u64 v[92:93], s[10:11], 0, v[160:161]
	s_mov_b32 m0, s14
	s_nop 0
	global_load_lds_dwordx4 v[92:93], off
	v_lshl_add_u64 v[92:93], s[10:11], 0, v[140:141]
	s_add_i32 m0, s14, 0x2000
	s_nop 0
	global_load_lds_dwordx4 v[92:93], off
	v_add_u32_e32 v154, 0x10000, v156
	ds_read_b128 v[92:95], v154
	ds_read_b128 v[96:99], v154 offset:1024
	ds_read_b128 v[172:175], v154 offset:2048
	ds_read_b128 v[176:179], v154 offset:3072
	s_waitcnt vmcnt(10)
	s_barrier
; #define PG8_MMA(ai, bj, At, Bt) do { __builtin_amdgcn_s_setprio(1); _Pragma("unroll") for (int m = 0; m < 4; ++m) _Pragma("unroll") for (int n = 0; n < 2; ++n) _Pragma("unroll") for (int k = 0; k < 2; ++k) \
;         acc[ai][bj][m][n] = __builtin_amdgcn_mfma_f32_16x16x32_bf16(Bt[n][k], At[m][k], acc[ai][bj][m][n], 0, 0, 0); __builtin_amdgcn_s_setprio(0); } while (0)
; #define PG8_WAIT_V(n) asm volatile("s_waitcnt vmcnt(" #n ")" ::: "memory")
; #define PG8_BAR __builtin_amdgcn_s_barrier()
;     ...
;             PG8_WAIT_V(6); PG8_BAR; PG8_MMA(1, 1, At, B1); PG8_BAR;
;         }
;         E(acc, cur, wr, wc, fr, fq, lane);
;     __device__ __forceinline__ void operator()(const f32x4 (&acc)[2][2][4][2], const Unit& u, int wr, int wc, int fr, int fq, int lane) const {
;         const int ch = u.pn * 64 + wc * 16 + 4 * fq;
;         const f32x4 w0 = *(const f32x4*)(cw + ch), w1 = *(const f32x4*)(cw + 4096 + ch), w2 = *(const f32x4*)(cw + 8192 + ch);
; #pragma unroll
;         for (int ai = 0; ai < 2; ++ai) {
;             f32x4 z[4], up[4], dn[4];
; #pragma unroll
;             for (int m = 0; m < 4; ++m) {
;                 z[m] = acc[ai][0][m][1] * acc[ai][1][m][0];
; #pragma unroll
;                 for (int j = 0; j < 4; ++j) { up[m][j] = __int_as_float(__builtin_amdgcn_update_dpp(0, __float_as_int(z[m][j]), 0x121, 0xF, 0xF, false));
;                                               dn[m][j] = __int_as_float(__builtin_amdgcn_update_dpp(0, __float_as_int(z[m][j]), 0x12F, 0xF, 0xF, false)); }
;             }
;             u32x2 wv[4];
; #pragma unroll
;             for (int m = 0; m < 4; ++m) {
;                 f32x4 zp, zn;
; #pragma unroll
;                 for (int j = 0; j < 4; ++j) {
;                     zp[j] = (fr > 0) ? up[m][j] : (m > 0 ? up[m > 0 ? m - 1 : 0][j] : 0.f);
;                     zn[j] = (fr < 15) ? dn[m][j] : (m < 3 ? dn[m < 3 ? m + 1 : 3][j] : 0.f);
;                 }
	v_mfma_f32_16x16x32_bf16 v[56:59], v[232:235], v[180:183], v[56:59]
	v_mfma_f32_16x16x32_bf16 v[24:27], v[240:243], v[180:183], v[24:27]
	v_mfma_f32_16x16x32_bf16 v[48:51], v[232:235], v[208:211], v[48:51]
	v_mfma_f32_16x16x32_bf16 v[16:19], v[240:243], v[208:211], v[16:19]
	v_mfma_f32_16x16x32_bf16 v[40:43], v[232:235], v[216:219], v[40:43]
	v_mfma_f32_16x16x32_bf16 v[8:11], v[240:243], v[216:219], v[8:11]
	v_mfma_f32_16x16x32_bf16 v[32:35], v[232:235], v[224:227], v[32:35]
	v_mfma_f32_16x16x32_bf16 v[0:3], v[240:243], v[224:227], v[0:3]
	v_mfma_f32_16x16x32_bf16 v[56:59], v[236:239], v[204:207], v[56:59]
	v_mfma_f32_16x16x32_bf16 v[24:27], v[244:247], v[204:207], v[24:27]
	v_mfma_f32_16x16x32_bf16 v[48:51], v[236:239], v[212:215], v[48:51]
	v_mfma_f32_16x16x32_bf16 v[16:19], v[244:247], v[212:215], v[16:19]
	v_mfma_f32_16x16x32_bf16 v[40:43], v[236:239], v[220:223], v[40:43]
	v_mfma_f32_16x16x32_bf16 v[8:11], v[244:247], v[220:223], v[8:11]
	v_mfma_f32_16x16x32_bf16 v[32:35], v[236:239], v[228:231], v[32:35]
	v_mfma_f32_16x16x32_bf16 v[0:3], v[244:247], v[228:231], v[0:3]
	s_add_i32 s9, s9, 2
	s_add_u32 vcc_lo, vcc_lo, 0x100
	s_addc_u32 vcc_hi, vcc_hi, 0
	s_cmp_gt_u32 s9, 29
	s_barrier
	s_cbranch_scc0 .LBB0_234
	s_waitcnt lgkmcnt(0)
	s_nop 0
	v_lshl_or_b32 v154, s5, 6, v158
	v_ashrrev_i32_e32 v155, 31, v154
	v_lshlrev_b64 v[92:93], 2, v[154:155]
	v_lshl_add_u64 v[88:89], v[142:143], 0, v[92:93]
	v_lshl_add_u64 v[90:91], v[144:145], 0, v[92:93]
	global_load_dwordx4 v[96:99], v[88:89], off
	s_nop 0
	global_load_dwordx4 v[88:91], v[90:91], off
	v_lshl_add_u64 v[92:93], v[146:147], 0, v[92:93]
	global_load_dwordx4 v[92:95], v[92:93], off
	v_pk_mul_f32 v[134:135], v[138:139], v[134:135]
	v_mov_b32_e32 v172, v161
	v_mov_b32_e32 v174, v161
	v_mov_b32_e32 v173, v161
	v_mov_b32_dpp v172, v134 row_ror:1 row_mask:0xf bank_mask:0xf
	v_mov_b32_dpp v174, v135 row_ror:1 row_mask:0xf bank_mask:0xf
	v_mov_b32_e32 v175, v161
	v_pk_mul_f32 v[126:127], v[130:131], v[126:127]
	v_mov_b32_e32 v177, v161
	v_mov_b32_e32 v179, v161
	v_pk_mul_f32 v[116:117], v[120:121], v[116:117]
	v_cndmask_b32_e64 v120, v172, 0, s[42:43]
	v_cndmask_b32_e64 v121, v174, 0, s[42:43]
	v_mov_b32_dpp v173, v134 row_ror:15 row_mask:0xf bank_mask:0xf
	v_mov_b32_dpp v175, v135 row_ror:15 row_mask:0xf bank_mask:0xf
	v_mov_b32_dpp v177, v126 row_ror:15 row_mask:0xf bank_mask:0xf
	v_mov_b32_dpp v179, v127 row_ror:15 row_mask:0xf bank_mask:0xf
	v_pk_mul_f32 v[132:133], v[136:137], v[132:133]
	v_mov_b32_e32 v136, v161
	v_mov_b32_e32 v138, v161
	v_pk_mul_f32 v[118:119], v[122:123], v[118:119]
	v_cndmask_b32_e64 v122, v173, v177, s[44:45]
	v_cndmask_b32_e64 v123, v175, v179, s[44:45]
	v_mov_b32_dpp v136, v132 row_ror:1 row_mask:0xf bank_mask:0xf
	v_mov_b32_dpp v138, v133 row_ror:1 row_mask:0xf bank_mask:0xf
	v_mov_b32_e32 v137, v161
	v_mov_b32_e32 v139, v161
	v_pk_mul_f32 v[124:125], v[128:129], v[124:125]
	v_mov_b32_e32 v129, v161
	v_mov_b32_e32 v131, v161
	v_pk_mul_f32 v[108:109], v[112:113], v[108:109]
	v_cndmask_b32_e64 v112, v136, 0, s[42:43]
	v_cndmask_b32_e64 v113, v138, 0, s[42:43]
	v_mov_b32_dpp v137, v132 row_ror:15 row_mask:0xf bank_mask:0xf
	v_mov_b32_dpp v139, v133 row_ror:15 row_mask:0xf bank_mask:0xf
	v_mov_b32_dpp v129, v124 row_ror:15 row_mask:0xf bank_mask:0xf
	v_mov_b32_dpp v131, v125 row_ror:15 row_mask:0xf bank_mask:0xf
	v_pk_mul_f32 v[110:111], v[114:115], v[110:111]
	v_cndmask_b32_e64 v114, v137, v129, s[44:45]
	v_cndmask_b32_e64 v115, v139, v131, s[44:45]
	v_mov_b32_e32 v176, v161
	v_mov_b32_e32 v178, v161
	v_mov_b32_e32 v185, v161
	v_mov_b32_dpp v176, v126 row_ror:1 row_mask:0xf bank_mask:0xf
	v_mov_b32_dpp v178, v127 row_ror:1 row_mask:0xf bank_mask:0xf
	v_mov_b32_e32 v191, v161
	v_mov_b32_dpp v185, v118 row_ror:15 row_mask:0xf bank_mask:0xf
	v_mov_b32_e32 v128, v161
	v_mov_b32_dpp v191, v119 row_ror:15 row_mask:0xf bank_mask:0xf
	v_mov_b32_e32 v130, v161
	v_mov_b32_dpp v128, v124 row_ror:1 row_mask:0xf bank_mask:0xf
	v_mov_b32_e32 v181, v161
	v_mov_b32_dpp v130, v125 row_ror:1 row_mask:0xf bank_mask:0xf
	v_mov_b32_e32 v183, v161
	v_mov_b32_dpp v181, v116 row_ror:15 row_mask:0xf bank_mask:0xf
	v_mov_b32_e32 v184, v161
	v_mov_b32_dpp v183, v117 row_ror:15 row_mask:0xf bank_mask:0xf
	v_mov_b32_e32 v190, v161
	v_mov_b32_dpp v184, v118 row_ror:1 row_mask:0xf bank_mask:0xf
	v_mov_b32_e32 v209, v161
	v_mov_b32_dpp v190, v119 row_ror:1 row_mask:0xf bank_mask:0xf
	v_mov_b32_e32 v211, v161
	v_mov_b32_dpp v209, v110 row_ror:15 row_mask:0xf bank_mask:0xf
	v_mov_b32_e32 v180, v161
	v_mov_b32_dpp v211, v111 row_ror:15 row_mask:0xf bank_mask:0xf
	v_mov_b32_e32 v182, v161
	v_mov_b32_dpp v180, v116 row_ror:1 row_mask:0xf bank_mask:0xf
	v_mov_b32_e32 v205, v161
	v_mov_b32_dpp v182, v117 row_ror:1 row_mask:0xf bank_mask:0xf
	v_mov_b32_e32 v207, v161
	v_mov_b32_dpp v205, v108 row_ror:15 row_mask:0xf bank_mask:0xf
	v_mov_b32_e32 v208, v161
	v_mov_b32_dpp v207, v109 row_ror:15 row_mask:0xf bank_mask:0xf
	v_mov_b32_e32 v210, v161
	v_mov_b32_dpp v208, v110 row_ror:1 row_mask:0xf bank_mask:0xf
	v_mov_b32_e32 v204, v161
	s_waitcnt vmcnt(0)
; __device__ __forceinline__ unsigned cvt_pk_bf16(float lo, float hi) { unsigned r; asm volatile("v_cvt_pk_bf16_f32 %0, %1, %2" : "=v"(r) : "v"(lo), "v"(hi)); return r; }
; __device__ __forceinline__ float silu_f(float x) { return x * __builtin_amdgcn_rcpf(1.f + __expf(-x)); }
;     __device__ __forceinline__ void operator()(const f32x4 (&acc)[2][2][4][2], const Unit& u, int wr, int wc, int fr, int fq, int lane) const {
;     ...
;             for (int m = 0; m < 4; ++m) {
;                 f32x4 zp, zn;
; #pragma unroll
;                 for (int j = 0; j < 4; ++j) {
;                     zp[j] = (fr > 0) ? up[m][j] : (m > 0 ? up[m > 0 ? m - 1 : 0][j] : 0.f);
;                     zn[j] = (fr < 15) ? dn[m][j] : (m < 3 ? dn[m < 3 ? m + 1 : 3][j] : 0.f);
;                 }
;                 f32x4 y = w0 * zp + w1 * z[m] + w2 * zn;
;                 const f32x4 bg = acc[ai][0][m][0], g = acc[ai][1][m][1];
; #pragma unroll
;                 for (int j = 0; j < 4; ++j) y[j] = y[j] * bg[j] * silu_f(g[j]);
;                 wv[m].x = cvt_pk_bf16(y[0], y[1]); wv[m].y = cvt_pk_bf16(y[2], y[3]);
;             }
;             if (u.pm < 128) {
	v_pk_mul_f32 v[120:121], v[98:99], v[120:121]
	v_pk_mul_f32 v[112:113], v[96:97], v[112:113]
	v_pk_fma_f32 v[120:121], v[134:135], v[90:91], v[120:121]
	v_mul_f32_e32 v134, 0xbfb8aa3b, v100
	v_exp_f32_e32 v134, v134
	v_pk_fma_f32 v[120:121], v[94:95], v[122:123], v[120:121]
	v_mov_b32_e32 v122, v100
	v_mul_f32_e32 v100, 0xbfb8aa3b, v101
	v_exp_f32_e32 v100, v100
	v_pk_fma_f32 v[112:113], v[132:133], v[88:89], v[112:113]
	v_mov_b32_e32 v123, v104
	v_pk_fma_f32 v[112:113], v[92:93], v[114:115], v[112:113]
	v_add_f32_e32 v114, 1.0, v134
	v_rcp_f32_e32 v114, v114
	v_add_f32_e32 v100, 1.0, v100
	v_mov_b32_e32 v115, v112
	v_rcp_f32_e32 v112, v100
	v_pk_mul_f32 v[114:115], v[122:123], v[114:115]
	v_mul_f32_e32 v100, 0xbfb8aa3b, v102
	v_mov_b32_e32 v104, v101
	v_mul_f32_e32 v114, v114, v115
	v_exp_f32_e32 v115, v100
	v_pk_mul_f32 v[100:101], v[104:105], v[112:113]
	v_mov_b32_e32 v104, v102
	v_mul_f32_e32 v112, v100, v101
	v_mul_f32_e32 v101, 0xbfb8aa3b, v103
	v_exp_f32_e32 v113, v101
	v_add_f32_e32 v100, 1.0, v115
	v_rcp_f32_e32 v100, v100
	v_mov_b32_e32 v101, v120
	v_add_f32_e32 v102, 1.0, v113
	v_rcp_f32_e32 v120, v102
	v_mov_b32_e32 v105, v106
	v_pk_mul_f32 v[100:101], v[104:105], v[100:101]
	v_mov_b32_e32 v106, v103
	v_mul_f32_e32 v102, v100, v101
	v_pk_mul_f32 v[100:101], v[106:107], v[120:121]
	v_cndmask_b32_e64 v106, v176, v172, s[42:43]
	v_cndmask_b32_e64 v107, v178, v174, s[42:43]
	v_pk_mul_f32 v[106:107], v[98:99], v[106:107]
	v_mul_f32_e32 v101, v100, v101
	v_cvt_pk_bf16_f32 v100, v114, v112
	v_cndmask_b32_e64 v112, v177, v185, s[44:45]
	v_cndmask_b32_e64 v113, v179, v191, s[44:45]
	v_pk_fma_f32 v[106:107], v[126:127], v[90:91], v[106:107]
	v_mul_f32_e32 v114, 0xbfb8aa3b, v80
	v_exp_f32_e32 v114, v114
	v_pk_fma_f32 v[106:107], v[94:95], v[112:113], v[106:107]
	v_mov_b32_e32 v112, v80
	v_mul_f32_e32 v80, 0xbfb8aa3b, v81
	v_cvt_pk_bf16_f32 v101, v102, v101
	v_cndmask_b32_e64 v102, v128, v136, s[42:43]
	v_cndmask_b32_e64 v103, v130, v138, s[42:43]
	v_exp_f32_e32 v80, v80
	v_pk_mul_f32 v[102:103], v[96:97], v[102:103]
	v_cndmask_b32_e64 v104, v129, v181, s[44:45]
	v_cndmask_b32_e64 v105, v131, v183, s[44:45]
	v_pk_fma_f32 v[102:103], v[124:125], v[88:89], v[102:103]
	v_add_f32_e32 v80, 1.0, v80
	v_pk_fma_f32 v[102:103], v[92:93], v[104:105], v[102:103]
	v_add_f32_e32 v104, 1.0, v114
	v_rcp_f32_e32 v104, v104
	v_mov_b32_e32 v105, v102
	v_rcp_f32_e32 v102, v80
	v_mov_b32_e32 v113, v84
	v_pk_mul_f32 v[104:105], v[112:113], v[104:105]
	v_mul_f32_e32 v80, 0xbfb8aa3b, v82
	v_mov_b32_e32 v84, v81
	v_mul_f32_e32 v104, v104, v105
	v_exp_f32_e32 v105, v80
	v_pk_mul_f32 v[80:81], v[84:85], v[102:103]
	v_mov_b32_e32 v84, v82
	v_mul_f32_e32 v102, v80, v81
	v_mul_f32_e32 v81, 0xbfb8aa3b, v83
	v_exp_f32_e32 v103, v81
	v_add_f32_e32 v80, 1.0, v105
	v_rcp_f32_e32 v80, v80
	v_mov_b32_e32 v81, v106
	v_add_f32_e32 v82, 1.0, v103
	v_rcp_f32_e32 v106, v82
	v_mov_b32_e32 v85, v86
	v_pk_mul_f32 v[80:81], v[84:85], v[80:81]
	v_mov_b32_e32 v86, v83
	v_mul_f32_e32 v82, v80, v81
	v_pk_mul_f32 v[80:81], v[86:87], v[106:107]
	v_cndmask_b32_e64 v86, v184, v176, s[42:43]
	v_cndmask_b32_e64 v87, v190, v178, s[42:43]
	v_pk_mul_f32 v[86:87], v[98:99], v[86:87]
	v_mul_f32_e32 v81, v80, v81
	v_cvt_pk_bf16_f32 v80, v104, v102
	v_cndmask_b32_e64 v102, v185, v209, s[44:45]
	v_cndmask_b32_e64 v103, v191, v211, s[44:45]
	v_pk_fma_f32 v[86:87], v[118:119], v[90:91], v[86:87]
	v_mul_f32_e32 v104, 0xbfb8aa3b, v72
	v_exp_f32_e32 v104, v104
	v_pk_fma_f32 v[86:87], v[94:95], v[102:103], v[86:87]
	v_mov_b32_e32 v102, v72
	v_mul_f32_e32 v72, 0xbfb8aa3b, v73
	v_cvt_pk_bf16_f32 v81, v82, v81
	v_cndmask_b32_e64 v82, v180, v128, s[42:43]
	v_cndmask_b32_e64 v83, v182, v130, s[42:43]
	v_exp_f32_e32 v72, v72
	v_pk_mul_f32 v[82:83], v[96:97], v[82:83]
	v_cndmask_b32_e64 v84, v181, v205, s[44:45]
	v_cndmask_b32_e64 v85, v183, v207, s[44:45]
	v_pk_fma_f32 v[82:83], v[116:117], v[88:89], v[82:83]
	v_add_f32_e32 v72, 1.0, v72
	v_pk_fma_f32 v[82:83], v[92:93], v[84:85], v[82:83]
	v_add_f32_e32 v84, 1.0, v104
	v_rcp_f32_e32 v84, v84
	v_mov_b32_e32 v85, v82
	v_rcp_f32_e32 v82, v72
	v_mov_b32_e32 v103, v76
	v_pk_mul_f32 v[84:85], v[102:103], v[84:85]
	v_mul_f32_e32 v72, 0xbfb8aa3b, v74
	v_mov_b32_e32 v76, v73
	v_mul_f32_e32 v84, v84, v85
	v_exp_f32_e32 v85, v72
	v_pk_mul_f32 v[72:73], v[76:77], v[82:83]
	v_mov_b32_e32 v76, v74
	v_mul_f32_e32 v82, v72, v73
	v_mul_f32_e32 v73, 0xbfb8aa3b, v75
	v_exp_f32_e32 v83, v73
	v_add_f32_e32 v72, 1.0, v85
	v_rcp_f32_e32 v72, v72
	v_mov_b32_e32 v73, v86
	v_add_f32_e32 v74, 1.0, v83
	v_rcp_f32_e32 v86, v74
	v_mov_b32_e32 v77, v78
	v_mov_b32_dpp v210, v111 row_ror:1 row_mask:0xf bank_mask:0xf
	v_pk_mul_f32 v[72:73], v[76:77], v[72:73]
	v_mov_b32_e32 v78, v75
	v_mul_f32_e32 v74, v72, v73
	v_pk_mul_f32 v[72:73], v[78:79], v[86:87]
	v_cndmask_b32_e64 v78, v208, v184, s[42:43]
	v_cndmask_b32_e64 v79, v210, v190, s[42:43]
	v_pk_mul_f32 v[78:79], v[98:99], v[78:79]
	v_mov_b32_e32 v206, v161
	v_mul_f32_e32 v73, v72, v73
	v_cvt_pk_bf16_f32 v72, v84, v82
	v_cndmask_b32_e64 v82, v209, 0, s[44:45]
	v_cndmask_b32_e64 v83, v211, 0, s[44:45]
	v_pk_fma_f32 v[78:79], v[110:111], v[90:91], v[78:79]
	v_mul_f32_e32 v84, 0xbfb8aa3b, v64
	v_mov_b32_dpp v204, v108 row_ror:1 row_mask:0xf bank_mask:0xf
	v_mov_b32_dpp v206, v109 row_ror:1 row_mask:0xf bank_mask:0xf
	v_exp_f32_e32 v84, v84
	v_pk_fma_f32 v[78:79], v[94:95], v[82:83], v[78:79]
	v_mov_b32_e32 v82, v64
	v_mul_f32_e32 v64, 0xbfb8aa3b, v65
	v_cvt_pk_bf16_f32 v73, v74, v73
	v_cndmask_b32_e64 v74, v204, v180, s[42:43]
	v_cndmask_b32_e64 v75, v206, v182, s[42:43]
	v_exp_f32_e32 v64, v64
	v_pk_mul_f32 v[74:75], v[96:97], v[74:75]
	v_cndmask_b32_e64 v76, v205, 0, s[44:45]
	v_cndmask_b32_e64 v77, v207, 0, s[44:45]
	v_pk_fma_f32 v[74:75], v[108:109], v[88:89], v[74:75]
	v_add_f32_e32 v64, 1.0, v64
	v_pk_fma_f32 v[74:75], v[92:93], v[76:77], v[74:75]
	v_add_f32_e32 v76, 1.0, v84
	v_rcp_f32_e32 v76, v76
	v_mov_b32_e32 v77, v74
	v_rcp_f32_e32 v74, v64
	v_mov_b32_e32 v83, v68
	v_pk_mul_f32 v[76:77], v[82:83], v[76:77]
	v_mul_f32_e32 v64, 0xbfb8aa3b, v66
	v_mov_b32_e32 v68, v65
	v_mul_f32_e32 v76, v76, v77
	v_exp_f32_e32 v77, v64
	v_pk_mul_f32 v[64:65], v[68:69], v[74:75]
	v_mov_b32_e32 v68, v66
	v_mul_f32_e32 v74, v64, v65
	v_mul_f32_e32 v65, 0xbfb8aa3b, v67
	v_exp_f32_e32 v75, v65
	v_add_f32_e32 v64, 1.0, v77
	v_rcp_f32_e32 v64, v64
	v_mov_b32_e32 v65, v78
	v_add_f32_e32 v66, 1.0, v75
	v_rcp_f32_e32 v78, v66
	s_cmpk_gt_i32 s36, 0x7f
	v_mov_b32_e32 v69, v70
	s_cselect_b64 s[38:39], -1, 0
	s_lshl_b32 s3, s36, 2
	v_pk_mul_f32 v[64:65], v[68:69], v[64:65]
	v_mov_b32_e32 v70, v67
	s_add_i32 s3, s4, s3
	v_mul_f32_e32 v68, v64, v65
	v_pk_mul_f32 v[64:65], v[70:71], v[78:79]
	s_and_b64 vcc, exec, s[38:39]
	v_mul_f32_e32 v64, v64, v65
	v_cvt_pk_bf16_f32 v66, v76, v74
	v_cvt_pk_bf16_f32 v67, v68, v64
	s_cbranch_vccz .LBB0_241
;     __device__ __forceinline__ void operator()(const f32x4 (&acc)[2][2][4][2], const Unit& u, int wr, int wc, int fr, int fq, int lane) const {
;     ...
;             } else {
;                 const int gidx = (u.pm - 128) * 4 + ai * 2 + wr, b = gidx / 5, g5 = gidx - b * 5, t0 = 62 * g5 - 1;
;                 bf16_t* p = O + ((size_t)(TL + b * 256 + t0 + fr)) * 4096 + ch;
; #pragma unroll
;                 for (int m = 0; m < 4; ++m) { const int i2 = m * 16 + fr; if (i2 >= 1 && i2 <= 62 && t0 + i2 < 256) *(u32x2*)(p + (size_t)(m * 16) * 4096) = wv[m]; }
	s_mul_hi_i32 s5, s3, 0x66666667
	s_lshr_b32 s6, s5, 31
	s_ashr_i32 s5, s5, 1
	s_add_i32 s6, s5, s6
	s_mul_i32 s5, s6, -5
	s_add_i32 s5, s5, s3
	s_mul_i32 s5, s5, 62
	s_lshl_b32 s6, s6, 8
	s_add_i32 s6, s5, s6
	v_add_u32_e32 v64, s6, v170
	v_ashrrev_i32_e32 v65, 31, v64
	v_lshlrev_b64 v[68:69], 13, v[64:65]
	v_lshl_add_u64 v[64:65], s[24:25], 0, v[68:69]
	v_cmp_le_i32_e32 vcc, s5, v157
	v_lshl_add_u64 v[64:65], v[154:155], 1, v[64:65]
	s_and_b64 s[6:7], s[46:47], vcc
	s_and_saveexec_b64 s[14:15], s[6:7]
	s_cbranch_execnz .LBB0_256
	s_or_b64 exec, exec, s[14:15]
	v_cmp_le_i32_e32 vcc, s5, v159
	s_and_saveexec_b64 s[14:15], vcc
	s_cbranch_execnz .LBB0_257

; #define PG8_STAGE(bufoff, gbase, voff) do { _Pragma("unroll") for (int _i = 0; _i < 2; ++_i) \
;         __builtin_amdgcn_global_load_lds((const unsigned*)((const char*)(gbase) + (voff)[_i]), (LAS unsigned*)(lds + (bufoff) + ldsw + _i * 8192), 16, 0, 0); } while (0)
; #define PG8_STAGE_A(bufoff, ptr, half, rev) do { if (REVA && (rev)) { const char* _p = (ptr) - ((half) ? hstepA : 0); PG8_STAGE(bufoff, _p, voffAr); } else { const char* _p = (ptr) + ((half) ? hstepA : 0); PG8_STAGE(bufoff, _p, voffA); } } while (0)
; #define PG8_LDA(dst, b, h) do { _Pragma("unroll") for (int m = 0; m < 4; ++m) _Pragma("unroll") for (int k = 0; k < 2; ++k) dst[m][k] = *(const LAS bf16x8*)(lds + PG8_SA(b, h) + aoff + m * 2048 + k * 1024); } while (0)
; #define PG8_LDB(dst, b, h) do { _Pragma("unroll") for (int n = 0; n < 2; ++n) _Pragma("unroll") for (int k = 0; k < 2; ++k) dst[n][k] = *(const LAS bf16x8*)(lds + PG8_SB(b, h) + boff + n * 2048 + k * 1024); } while (0)
; #define PG8_WAIT_L(n) asm volatile("s_waitcnt lgkmcnt(" #n ")" ::: "memory")
; #define PG8_BAR __builtin_amdgcn_s_barrier()
; #define PG8_SCHED __builtin_amdgcn_sched_barrier(0)
;     ...
;         for (int t = 0; t < nt; t += 2) {
;             const bool last = (t == nt - 2);
;             const char* a1 = PG8_APTR(cA, cAr, t + 1); const bool r1 = REVA && ((t + 1) & 4);
;             const char* a2 = last ? nA : PG8_APTR(cA, cAr, t + 2); const bool r2 = REVA && !last && ((t + 2) & 4);
;             const char* a3 = last ? nA + kstep : PG8_APTR(cA, cAr, t + 3); const bool r3 = REVA && !last && ((t + 3) & 4);
;             const char* b2 = last ? nB : cB + (size_t)(t + 2) * kstep; const char* b3 = b2 + kstep; const size_t hb2 = last ? nHb : cHb;
;             PG8_LDB(B0, 0, 0); PG8_SCHED; PG8_LDA(At, 0, 0); PG8_STAGE_A(PG8_SA(1, 1), a1, 1, r1);
;             PG8_WAIT_L(8); PG8_BAR; PG8_WAIT_L(0); PG8_MMA(0, 0, At, B0); PG8_BAR; PG8_SCHED;
;             PG8_LDB(B1, 0, 1); PG8_STAGE(PG8_SB(0, 0), b2, voffB);
;             PG8_BAR; PG8_WAIT_L(0); PG8_MMA(0, 1, At, B1); PG8_BAR;
;     ...
; #pragma unroll
;         for (int a = 0; a < 2; ++a)
; #pragma unroll
;             for (int b = 0; b < 2; ++b)
; #pragma unroll
;                 for (int m = 0; m < 4; ++m)
; #pragma unroll
;                     for (int n = 0; n < 2; ++n) acc[a][b][m][n] = (f32x4){0.f, 0.f, 0.f, 0.f};
.LBB0_334:
	s_add_u32 s3, s36, 0x80
	s_addc_u32 s9, s37, 0
	s_add_u32 s10, s44, 0x100080
	s_addc_u32 s11, s45, 0
	s_add_u32 s27, s20, 0x100
	v_mov_b32_e32 v0, 0
	v_lshl_add_u64 v[128:129], s[10:11], 0, v[150:151]
	v_lshl_add_u64 v[130:131], s[10:11], 0, v[152:153]
	s_addc_u32 s91, s21, 0
	s_mov_b32 s92, -2
	s_mov_b64 s[46:47], 0
	v_mov_b32_e32 v1, v0
	v_pk_mov_b32 v[2:3], v[0:1], v[0:1]
	v_pk_mov_b32 v[4:5], v[0:1], v[0:1]
	v_pk_mov_b32 v[6:7], v[0:1], v[0:1]
	v_pk_mov_b32 v[8:9], v[0:1], v[0:1]
	v_pk_mov_b32 v[10:11], v[0:1], v[0:1]
	v_pk_mov_b32 v[12:13], v[0:1], v[0:1]
	v_pk_mov_b32 v[14:15], v[0:1], v[0:1]
	v_pk_mov_b32 v[16:17], v[0:1], v[0:1]
	v_pk_mov_b32 v[18:19], v[0:1], v[0:1]
	v_pk_mov_b32 v[20:21], v[0:1], v[0:1]
	v_pk_mov_b32 v[22:23], v[0:1], v[0:1]
	v_pk_mov_b32 v[24:25], v[0:1], v[0:1]
	v_pk_mov_b32 v[26:27], v[0:1], v[0:1]
	v_pk_mov_b32 v[28:29], v[0:1], v[0:1]
	v_pk_mov_b32 v[30:31], v[0:1], v[0:1]
	v_pk_mov_b32 v[32:33], v[0:1], v[0:1]
	v_pk_mov_b32 v[34:35], v[0:1], v[0:1]
	v_pk_mov_b32 v[36:37], v[0:1], v[0:1]
	v_pk_mov_b32 v[38:39], v[0:1], v[0:1]
	v_pk_mov_b32 v[40:41], v[0:1], v[0:1]
	v_pk_mov_b32 v[42:43], v[0:1], v[0:1]
	v_pk_mov_b32 v[44:45], v[0:1], v[0:1]
	v_pk_mov_b32 v[46:47], v[0:1], v[0:1]
	v_pk_mov_b32 v[48:49], v[0:1], v[0:1]
	v_pk_mov_b32 v[50:51], v[0:1], v[0:1]
	v_pk_mov_b32 v[52:53], v[0:1], v[0:1]
	v_pk_mov_b32 v[54:55], v[0:1], v[0:1]
	v_pk_mov_b32 v[56:57], v[0:1], v[0:1]
	v_pk_mov_b32 v[58:59], v[0:1], v[0:1]
	v_pk_mov_b32 v[60:61], v[0:1], v[0:1]
	v_pk_mov_b32 v[62:63], v[0:1], v[0:1]
	v_pk_mov_b32 v[64:65], v[0:1], v[0:1]
	v_pk_mov_b32 v[66:67], v[0:1], v[0:1]
	v_pk_mov_b32 v[68:69], v[0:1], v[0:1]
	v_pk_mov_b32 v[70:71], v[0:1], v[0:1]
	v_pk_mov_b32 v[72:73], v[0:1], v[0:1]
	v_pk_mov_b32 v[74:75], v[0:1], v[0:1]
	v_pk_mov_b32 v[76:77], v[0:1], v[0:1]
	v_pk_mov_b32 v[78:79], v[0:1], v[0:1]
	v_pk_mov_b32 v[80:81], v[0:1], v[0:1]
	v_pk_mov_b32 v[82:83], v[0:1], v[0:1]
	v_pk_mov_b32 v[84:85], v[0:1], v[0:1]
	v_pk_mov_b32 v[86:87], v[0:1], v[0:1]
	v_pk_mov_b32 v[88:89], v[0:1], v[0:1]
	v_pk_mov_b32 v[90:91], v[0:1], v[0:1]
	v_pk_mov_b32 v[92:93], v[0:1], v[0:1]
	v_pk_mov_b32 v[94:95], v[0:1], v[0:1]
	v_pk_mov_b32 v[96:97], v[0:1], v[0:1]
	v_pk_mov_b32 v[98:99], v[0:1], v[0:1]
	v_pk_mov_b32 v[100:101], v[0:1], v[0:1]
	v_pk_mov_b32 v[102:103], v[0:1], v[0:1]
	v_pk_mov_b32 v[104:105], v[0:1], v[0:1]
	v_pk_mov_b32 v[106:107], v[0:1], v[0:1]
	v_pk_mov_b32 v[108:109], v[0:1], v[0:1]
	v_pk_mov_b32 v[110:111], v[0:1], v[0:1]
	v_pk_mov_b32 v[112:113], v[0:1], v[0:1]
	v_pk_mov_b32 v[114:115], v[0:1], v[0:1]
	v_pk_mov_b32 v[116:117], v[0:1], v[0:1]
	v_pk_mov_b32 v[118:119], v[0:1], v[0:1]
	v_pk_mov_b32 v[120:121], v[0:1], v[0:1]
	v_pk_mov_b32 v[122:123], v[0:1], v[0:1]
	v_pk_mov_b32 v[124:125], v[0:1], v[0:1]
	v_pk_mov_b32 v[126:127], v[0:1], v[0:1]
	v_add_u32_e32 v154, 0x10000, v157
	ds_read_b128 v[132:135], v154
	ds_read_b128 v[136:139], v154 offset:1024
	ds_read_b128 v[140:143], v154 offset:2048
	ds_read_b128 v[168:171], v154 offset:3072
.LBB0_335:
	s_add_u32 s10, s44, s46
	s_addc_u32 s11, s45, s47
	s_add_u32 s16, s10, 0x100
	s_addc_u32 s17, s11, 0
	s_add_u32 s10, s10, 0x180
	s_addc_u32 s11, s11, 0
	s_add_u32 s14, s27, s46
	s_addc_u32 s15, s91, s47
	s_add_i32 s93, 0, 0x10000
	s_cmpk_eq_i32 s46, 0x1f00
	s_cselect_b32 s15, s39, s15
	s_cselect_b32 s14, s38, s14
	s_cselect_b32 s21, s37, s17
	s_cselect_b32 s20, s36, s16
	s_cselect_b32 s17, s9, s11
	s_cselect_b32 s16, s3, s10
	v_lshl_add_u64 v[154:155], v[128:129], 0, s[46:47]
	s_add_i32 m0, s1, 0xc000
	ds_read_b128 v[172:175], v158
	ds_read_b128 v[176:179], v158 offset:1024
	ds_read_b128 v[180:183], v158 offset:2048
	ds_read_b128 v[204:207], v158 offset:3072
	ds_read_b128 v[208:211], v158 offset:4096
	ds_read_b128 v[212:215], v158 offset:5120
	ds_read_b128 v[216:219], v158 offset:6144
	ds_read_b128 v[220:223], v158 offset:7168
	global_load_lds_dwordx4 v[154:155], off
	v_lshl_add_u64 v[154:155], v[130:131], 0, s[46:47]
	s_add_i32 m0, s1, 0xe000
	s_nop 0
	global_load_lds_dwordx4 v[154:155], off
	s_waitcnt lgkmcnt(8)
	s_waitcnt vmcnt(10)
	s_barrier
	s_waitcnt lgkmcnt(0)
	v_mfma_f32_16x16x32_bf16 v[124:127], v[132:135], v[172:175], v[124:127]
	v_mfma_f32_16x16x32_bf16 v[120:123], v[140:143], v[172:175], v[120:123]
	v_mfma_f32_16x16x32_bf16 v[116:119], v[132:135], v[180:183], v[116:119]
	v_mfma_f32_16x16x32_bf16 v[108:111], v[140:143], v[180:183], v[108:111]
	v_mfma_f32_16x16x32_bf16 v[92:95], v[132:135], v[208:211], v[92:95]
	v_mfma_f32_16x16x32_bf16 v[88:91], v[140:143], v[208:211], v[88:91]
	v_mfma_f32_16x16x32_bf16 v[84:87], v[132:135], v[216:219], v[84:87]
	v_mfma_f32_16x16x32_bf16 v[76:79], v[140:143], v[216:219], v[76:79]
	v_mfma_f32_16x16x32_bf16 v[124:127], v[136:139], v[176:179], v[124:127]
	v_mfma_f32_16x16x32_bf16 v[120:123], v[168:171], v[176:179], v[120:123]
	v_mfma_f32_16x16x32_bf16 v[116:119], v[136:139], v[204:207], v[116:119]
	v_mfma_f32_16x16x32_bf16 v[108:111], v[168:171], v[204:207], v[108:111]
	v_mfma_f32_16x16x32_bf16 v[92:95], v[136:139], v[212:215], v[92:95]
	v_mfma_f32_16x16x32_bf16 v[88:91], v[168:171], v[212:215], v[88:91]
	v_mfma_f32_16x16x32_bf16 v[84:87], v[136:139], v[220:223], v[84:87]
	v_mfma_f32_16x16x32_bf16 v[76:79], v[168:171], v[220:223], v[76:79]
	s_barrier
	s_add_i32 s94, 0, 0x14000
	v_add_u32_e32 v154, s94, v157
	s_add_i32 s10, s93, s52
	ds_read_b128 v[224:227], v154
	ds_read_b128 v[228:231], v154 offset:1024
	ds_read_b128 v[232:235], v154 offset:2048
	ds_read_b128 v[236:239], v154 offset:3072
	v_lshl_add_u64 v[154:155], s[14:15], 0, v[146:147]
	s_mov_b32 m0, s10
	v_lshl_add_u64 v[184:185], s[14:15], 0, v[144:145]
	global_load_lds_dwordx4 v[154:155], off
	s_add_i32 m0, s10, 0x2000
	s_nop 0
	global_load_lds_dwordx4 v[184:185], off
	s_waitcnt vmcnt(10)
	s_barrier
; #define PG8_STAGE(bufoff, gbase, voff) do { _Pragma("unroll") for (int _i = 0; _i < 2; ++_i) \
;         __builtin_amdgcn_global_load_lds((const unsigned*)((const char*)(gbase) + (voff)[_i]), (LAS unsigned*)(lds + (bufoff) + ldsw + _i * 8192), 16, 0, 0); } while (0)
; #define PG8_STAGE_A(bufoff, ptr, half, rev) do { if (REVA && (rev)) { const char* _p = (ptr) - ((half) ? hstepA : 0); PG8_STAGE(bufoff, _p, voffAr); } else { const char* _p = (ptr) + ((half) ? hstepA : 0); PG8_STAGE(bufoff, _p, voffA); } } while (0)
; #define PG8_LDA(dst, b, h) do { _Pragma("unroll") for (int m = 0; m < 4; ++m) _Pragma("unroll") for (int k = 0; k < 2; ++k) dst[m][k] = *(const LAS bf16x8*)(lds + PG8_SA(b, h) + aoff + m * 2048 + k * 1024); } while (0)
; #define PG8_LDB(dst, b, h) do { _Pragma("unroll") for (int n = 0; n < 2; ++n) _Pragma("unroll") for (int k = 0; k < 2; ++k) dst[n][k] = *(const LAS bf16x8*)(lds + PG8_SB(b, h) + boff + n * 2048 + k * 1024); } while (0)
; #define PG8_MMA(ai, bj, At, Bt) do { __builtin_amdgcn_s_setprio(1); _Pragma("unroll") for (int m = 0; m < 4; ++m) _Pragma("unroll") for (int n = 0; n < 2; ++n) _Pragma("unroll") for (int k = 0; k < 2; ++k) \
;         acc[ai][bj][m][n] = __builtin_amdgcn_mfma_f32_16x16x32_bf16(Bt[n][k], At[m][k], acc[ai][bj][m][n], 0, 0, 0); __builtin_amdgcn_s_setprio(0); } while (0)
; #define PG8_WAIT_V(n) asm volatile("s_waitcnt vmcnt(" #n ")" ::: "memory")
; #define PG8_WAIT_L(n) asm volatile("s_waitcnt lgkmcnt(" #n ")" ::: "memory")
; #define PG8_BAR __builtin_amdgcn_s_barrier()
; #define PG8_SCHED __builtin_amdgcn_sched_barrier(0)
;     ...
;             PG8_BAR; PG8_WAIT_L(0); PG8_MMA(0, 1, At, B1); PG8_BAR;
;             PG8_LDA(At, 0, 1); PG8_STAGE_A(PG8_SA(0, 0), a2, 0, r2);
;             PG8_BAR; PG8_WAIT_L(0); PG8_MMA(1, 0, At, B0); PG8_BAR; PG8_SCHED;
;             PG8_STAGE(PG8_SB(0, 1), b2 + hb2, voffB);
;             PG8_WAIT_V(6); PG8_BAR; PG8_MMA(1, 1, At, B1); PG8_BAR;
;             PG8_LDB(B0, 1, 0); PG8_SCHED; PG8_LDA(At, 1, 0); PG8_STAGE_A(PG8_SA(0, 1), a2, 1, r2);
;             PG8_WAIT_L(8); PG8_BAR; PG8_WAIT_L(0); PG8_MMA(0, 0, At, B0); PG8_BAR; PG8_SCHED;
	s_waitcnt lgkmcnt(0)
	v_mfma_f32_16x16x32_bf16 v[112:115], v[224:227], v[172:175], v[112:115]
	v_mfma_f32_16x16x32_bf16 v[104:107], v[232:235], v[172:175], v[104:107]
	v_mfma_f32_16x16x32_bf16 v[100:103], v[224:227], v[180:183], v[100:103]
	v_mfma_f32_16x16x32_bf16 v[96:99], v[232:235], v[180:183], v[96:99]
	v_mfma_f32_16x16x32_bf16 v[80:83], v[224:227], v[208:211], v[80:83]
	v_mfma_f32_16x16x32_bf16 v[72:75], v[232:235], v[208:211], v[72:75]
	v_mfma_f32_16x16x32_bf16 v[68:71], v[224:227], v[216:219], v[68:71]
	v_mfma_f32_16x16x32_bf16 v[64:67], v[232:235], v[216:219], v[64:67]
	v_mfma_f32_16x16x32_bf16 v[112:115], v[228:231], v[176:179], v[112:115]
	v_mfma_f32_16x16x32_bf16 v[104:107], v[236:239], v[176:179], v[104:107]
	v_mfma_f32_16x16x32_bf16 v[100:103], v[228:231], v[204:207], v[100:103]
	v_mfma_f32_16x16x32_bf16 v[96:99], v[236:239], v[204:207], v[96:99]
	v_mfma_f32_16x16x32_bf16 v[80:83], v[228:231], v[212:215], v[80:83]
	v_mfma_f32_16x16x32_bf16 v[72:75], v[236:239], v[212:215], v[72:75]
	v_mfma_f32_16x16x32_bf16 v[68:71], v[228:231], v[220:223], v[68:71]
	v_mfma_f32_16x16x32_bf16 v[64:67], v[236:239], v[220:223], v[64:67]
	s_mov_b32 m0, s1
	v_lshl_add_u64 v[190:191], s[20:21], 0, v[146:147]
	s_barrier
	ds_read_b128 v[172:175], v158 offset:16384
	ds_read_b128 v[176:179], v158 offset:17408
	ds_read_b128 v[180:183], v158 offset:18432
	ds_read_b128 v[204:207], v158 offset:19456
	ds_read_b128 v[208:211], v158 offset:20480
	ds_read_b128 v[212:215], v158 offset:21504
	ds_read_b128 v[216:219], v158 offset:22528
	ds_read_b128 v[220:223], v158 offset:23552
	global_load_lds_dwordx4 v[190:191], off
	v_lshl_add_u64 v[190:191], s[20:21], 0, v[144:145]
	s_mov_b32 m0, s53
	s_nop 0
	global_load_lds_dwordx4 v[190:191], off
	s_waitcnt vmcnt(10)
	s_barrier
	s_waitcnt lgkmcnt(0)
	v_mfma_f32_16x16x32_bf16 v[60:63], v[132:135], v[172:175], v[60:63]
	v_mfma_f32_16x16x32_bf16 v[56:59], v[140:143], v[172:175], v[56:59]
	v_mfma_f32_16x16x32_bf16 v[52:55], v[132:135], v[180:183], v[52:55]
	v_mfma_f32_16x16x32_bf16 v[44:47], v[140:143], v[180:183], v[44:47]
	v_mfma_f32_16x16x32_bf16 v[28:31], v[132:135], v[208:211], v[28:31]
	v_mfma_f32_16x16x32_bf16 v[24:27], v[140:143], v[208:211], v[24:27]
	v_mfma_f32_16x16x32_bf16 v[20:23], v[132:135], v[216:219], v[20:23]
	v_mfma_f32_16x16x32_bf16 v[12:15], v[140:143], v[216:219], v[12:15]
	v_mfma_f32_16x16x32_bf16 v[60:63], v[136:139], v[176:179], v[60:63]
	v_mfma_f32_16x16x32_bf16 v[56:59], v[168:171], v[176:179], v[56:59]
	v_mfma_f32_16x16x32_bf16 v[52:55], v[136:139], v[204:207], v[52:55]
	v_mfma_f32_16x16x32_bf16 v[44:47], v[168:171], v[204:207], v[44:47]
	v_mfma_f32_16x16x32_bf16 v[28:31], v[136:139], v[212:215], v[28:31]
	v_mfma_f32_16x16x32_bf16 v[24:27], v[168:171], v[212:215], v[24:27]
	v_mfma_f32_16x16x32_bf16 v[20:23], v[136:139], v[220:223], v[20:23]
	v_mfma_f32_16x16x32_bf16 v[12:15], v[168:171], v[220:223], v[12:15]
	s_barrier
	s_add_u32 s10, s14, 0x100000
	s_addc_u32 s11, s15, 0
	s_add_i32 s93, s94, s52
	v_lshl_add_u64 v[132:133], s[10:11], 0, v[146:147]
	s_mov_b32 m0, s93
	s_nop 0
	global_load_lds_dwordx4 v[132:133], off
	v_lshl_add_u64 v[132:133], s[10:11], 0, v[144:145]
	s_add_i32 m0, s93, 0x2000
	s_nop 0
	global_load_lds_dwordx4 v[132:133], off
	v_add_u32_e32 v159, 0x18000, v157
	ds_read_b128 v[132:135], v159
	ds_read_b128 v[136:139], v159 offset:1024
	ds_read_b128 v[140:143], v159 offset:2048
	ds_read_b128 v[168:171], v159 offset:3072
	s_waitcnt vmcnt(10)
	s_barrier
	v_mfma_f32_16x16x32_bf16 v[48:51], v[224:227], v[172:175], v[48:51]
	v_mfma_f32_16x16x32_bf16 v[40:43], v[232:235], v[172:175], v[40:43]
	v_mfma_f32_16x16x32_bf16 v[36:39], v[224:227], v[180:183], v[36:39]
	v_mfma_f32_16x16x32_bf16 v[32:35], v[232:235], v[180:183], v[32:35]
	v_mfma_f32_16x16x32_bf16 v[16:19], v[224:227], v[208:211], v[16:19]
	v_mfma_f32_16x16x32_bf16 v[8:11], v[232:235], v[208:211], v[8:11]
	v_mfma_f32_16x16x32_bf16 v[4:7], v[224:227], v[216:219], v[4:7]
	v_mfma_f32_16x16x32_bf16 v[0:3], v[232:235], v[216:219], v[0:3]
	v_mfma_f32_16x16x32_bf16 v[48:51], v[228:231], v[176:179], v[48:51]
	v_mfma_f32_16x16x32_bf16 v[40:43], v[236:239], v[176:179], v[40:43]
	v_mfma_f32_16x16x32_bf16 v[36:39], v[228:231], v[204:207], v[36:39]
	v_mfma_f32_16x16x32_bf16 v[32:35], v[236:239], v[204:207], v[32:35]
	v_mfma_f32_16x16x32_bf16 v[16:19], v[228:231], v[212:215], v[16:19]
	v_mfma_f32_16x16x32_bf16 v[8:11], v[236:239], v[212:215], v[8:11]
	v_mfma_f32_16x16x32_bf16 v[4:7], v[228:231], v[220:223], v[4:7]
	v_mfma_f32_16x16x32_bf16 v[0:3], v[236:239], v[220:223], v[0:3]
	s_add_i32 s93, 0, 0x18000
	s_barrier
	s_add_u32 s10, s20, 0x100000
	s_addc_u32 s11, s21, 0
	s_mov_b32 m0, s6
	v_lshl_add_u64 v[190:191], s[10:11], 0, v[146:147]
	ds_read_b128 v[172:175], v158 offset:32768
	ds_read_b128 v[176:179], v158 offset:33792
	ds_read_b128 v[180:183], v158 offset:34816
	ds_read_b128 v[204:207], v158 offset:35840
	ds_read_b128 v[208:211], v158 offset:36864
	ds_read_b128 v[212:215], v158 offset:37888
	ds_read_b128 v[216:219], v158 offset:38912
	ds_read_b128 v[220:223], v158 offset:39936
	global_load_lds_dwordx4 v[190:191], off
	v_lshl_add_u64 v[190:191], s[10:11], 0, v[144:145]
	s_mov_b32 m0, s7
	s_nop 0
	global_load_lds_dwordx4 v[190:191], off
	s_waitcnt lgkmcnt(8)
	s_waitcnt vmcnt(10)
	s_barrier
; #define PG8_STAGE(bufoff, gbase, voff) do { _Pragma("unroll") for (int _i = 0; _i < 2; ++_i) \
;         __builtin_amdgcn_global_load_lds((const unsigned*)((const char*)(gbase) + (voff)[_i]), (LAS unsigned*)(lds + (bufoff) + ldsw + _i * 8192), 16, 0, 0); } while (0)
; #define PG8_STAGE_A(bufoff, ptr, half, rev) do { if (REVA && (rev)) { const char* _p = (ptr) - ((half) ? hstepA : 0); PG8_STAGE(bufoff, _p, voffAr); } else { const char* _p = (ptr) + ((half) ? hstepA : 0); PG8_STAGE(bufoff, _p, voffA); } } while (0)
; #define PG8_LDA(dst, b, h) do { _Pragma("unroll") for (int m = 0; m < 4; ++m) _Pragma("unroll") for (int k = 0; k < 2; ++k) dst[m][k] = *(const LAS bf16x8*)(lds + PG8_SA(b, h) + aoff + m * 2048 + k * 1024); } while (0)
; #define PG8_LDB(dst, b, h) do { _Pragma("unroll") for (int n = 0; n < 2; ++n) _Pragma("unroll") for (int k = 0; k < 2; ++k) dst[n][k] = *(const LAS bf16x8*)(lds + PG8_SB(b, h) + boff + n * 2048 + k * 1024); } while (0)
; #define PG8_MMA(ai, bj, At, Bt) do { __builtin_amdgcn_s_setprio(1); _Pragma("unroll") for (int m = 0; m < 4; ++m) _Pragma("unroll") for (int n = 0; n < 2; ++n) _Pragma("unroll") for (int k = 0; k < 2; ++k) \
;         acc[ai][bj][m][n] = __builtin_amdgcn_mfma_f32_16x16x32_bf16(Bt[n][k], At[m][k], acc[ai][bj][m][n], 0, 0, 0); __builtin_amdgcn_s_setprio(0); } while (0)
; #define PG8_WAIT_V(n) asm volatile("s_waitcnt vmcnt(" #n ")" ::: "memory")
; #define PG8_WAIT_L(n) asm volatile("s_waitcnt lgkmcnt(" #n ")" ::: "memory")
; #define PG8_BAR __builtin_amdgcn_s_barrier()
; #define PG8_SCHED __builtin_amdgcn_sched_barrier(0)
;     ...
;             PG8_WAIT_L(8); PG8_BAR; PG8_WAIT_L(0); PG8_MMA(0, 0, At, B0); PG8_BAR; PG8_SCHED;
;             PG8_LDB(B1, 1, 1); PG8_STAGE(PG8_SB(1, 0), b3, voffB);
;             PG8_BAR; PG8_WAIT_L(0); PG8_MMA(0, 1, At, B1); PG8_BAR;
;             PG8_LDA(At, 1, 1); PG8_STAGE_A(PG8_SA(1, 0), a3, 0, r3);
;             PG8_BAR; PG8_WAIT_L(0); PG8_MMA(1, 0, At, B0); PG8_BAR; PG8_SCHED;
;             PG8_STAGE(PG8_SB(1, 1), b3 + hb2, voffB);
;             PG8_WAIT_V(6); PG8_BAR; PG8_MMA(1, 1, At, B1); PG8_BAR;
	s_waitcnt lgkmcnt(0)
	v_mfma_f32_16x16x32_bf16 v[124:127], v[132:135], v[172:175], v[124:127]
	v_mfma_f32_16x16x32_bf16 v[120:123], v[140:143], v[172:175], v[120:123]
	v_mfma_f32_16x16x32_bf16 v[116:119], v[132:135], v[180:183], v[116:119]
	v_mfma_f32_16x16x32_bf16 v[108:111], v[140:143], v[180:183], v[108:111]
	v_mfma_f32_16x16x32_bf16 v[92:95], v[132:135], v[208:211], v[92:95]
	v_mfma_f32_16x16x32_bf16 v[88:91], v[140:143], v[208:211], v[88:91]
	v_mfma_f32_16x16x32_bf16 v[84:87], v[132:135], v[216:219], v[84:87]
	v_mfma_f32_16x16x32_bf16 v[76:79], v[140:143], v[216:219], v[76:79]
	v_mfma_f32_16x16x32_bf16 v[124:127], v[136:139], v[176:179], v[124:127]
	v_mfma_f32_16x16x32_bf16 v[120:123], v[168:171], v[176:179], v[120:123]
	v_mfma_f32_16x16x32_bf16 v[116:119], v[136:139], v[204:207], v[116:119]
	v_mfma_f32_16x16x32_bf16 v[108:111], v[168:171], v[204:207], v[108:111]
	v_mfma_f32_16x16x32_bf16 v[92:95], v[136:139], v[212:215], v[92:95]
	v_mfma_f32_16x16x32_bf16 v[88:91], v[168:171], v[212:215], v[88:91]
	v_mfma_f32_16x16x32_bf16 v[84:87], v[136:139], v[220:223], v[84:87]
	v_mfma_f32_16x16x32_bf16 v[76:79], v[168:171], v[220:223], v[76:79]
	s_barrier
	s_add_i32 s20, 0, 0x1c000
	s_add_i32 s10, s93, s52
	v_add_u32_e32 v159, s20, v157
	v_lshl_add_u64 v[154:155], v[154:155], 0, s[28:29]
	s_mov_b32 m0, s10
	ds_read_b128 v[224:227], v159
	ds_read_b128 v[228:231], v159 offset:1024
	ds_read_b128 v[232:235], v159 offset:2048
	ds_read_b128 v[236:239], v159 offset:3072
	global_load_lds_dwordx4 v[154:155], off
	v_lshl_add_u64 v[154:155], v[184:185], 0, s[28:29]
	s_add_i32 m0, s10, 0x2000
	s_nop 0
	global_load_lds_dwordx4 v[154:155], off
	s_waitcnt vmcnt(10)
	s_barrier
	s_waitcnt lgkmcnt(0)
	v_mfma_f32_16x16x32_bf16 v[112:115], v[224:227], v[172:175], v[112:115]
	v_mfma_f32_16x16x32_bf16 v[104:107], v[232:235], v[172:175], v[104:107]
	v_mfma_f32_16x16x32_bf16 v[100:103], v[224:227], v[180:183], v[100:103]
	v_mfma_f32_16x16x32_bf16 v[96:99], v[232:235], v[180:183], v[96:99]
	v_mfma_f32_16x16x32_bf16 v[80:83], v[224:227], v[208:211], v[80:83]
	v_mfma_f32_16x16x32_bf16 v[72:75], v[232:235], v[208:211], v[72:75]
	v_mfma_f32_16x16x32_bf16 v[68:71], v[224:227], v[216:219], v[68:71]
	v_mfma_f32_16x16x32_bf16 v[64:67], v[232:235], v[216:219], v[64:67]
	v_mfma_f32_16x16x32_bf16 v[112:115], v[228:231], v[176:179], v[112:115]
	v_mfma_f32_16x16x32_bf16 v[104:107], v[236:239], v[176:179], v[104:107]
	v_mfma_f32_16x16x32_bf16 v[100:103], v[228:231], v[204:207], v[100:103]
	v_mfma_f32_16x16x32_bf16 v[96:99], v[236:239], v[204:207], v[96:99]
	v_mfma_f32_16x16x32_bf16 v[80:83], v[228:231], v[212:215], v[80:83]
	v_mfma_f32_16x16x32_bf16 v[72:75], v[236:239], v[212:215], v[72:75]
	v_mfma_f32_16x16x32_bf16 v[68:71], v[228:231], v[220:223], v[68:71]
	v_mfma_f32_16x16x32_bf16 v[64:67], v[236:239], v[220:223], v[64:67]
	s_mov_b32 m0, s70
	v_lshl_add_u64 v[154:155], s[16:17], 0, v[146:147]
	s_barrier
	ds_read_b128 v[172:175], v158 offset:49152
	ds_read_b128 v[176:179], v158 offset:50176
	ds_read_b128 v[180:183], v158 offset:51200
	ds_read_b128 v[204:207], v158 offset:52224
	ds_read_b128 v[208:211], v158 offset:53248
	ds_read_b128 v[212:215], v158 offset:54272
	ds_read_b128 v[216:219], v158 offset:55296
	ds_read_b128 v[220:223], v158 offset:56320
	global_load_lds_dwordx4 v[154:155], off
	v_lshl_add_u64 v[154:155], s[16:17], 0, v[144:145]
	s_mov_b32 m0, s71
	s_nop 0
	global_load_lds_dwordx4 v[154:155], off
	s_waitcnt vmcnt(10)
	s_barrier
	s_waitcnt lgkmcnt(0)
	v_mfma_f32_16x16x32_bf16 v[60:63], v[132:135], v[172:175], v[60:63]
	v_mfma_f32_16x16x32_bf16 v[56:59], v[140:143], v[172:175], v[56:59]
	v_mfma_f32_16x16x32_bf16 v[52:55], v[132:135], v[180:183], v[52:55]
	v_mfma_f32_16x16x32_bf16 v[44:47], v[140:143], v[180:183], v[44:47]
	v_mfma_f32_16x16x32_bf16 v[28:31], v[132:135], v[208:211], v[28:31]
	v_mfma_f32_16x16x32_bf16 v[24:27], v[140:143], v[208:211], v[24:27]
	v_mfma_f32_16x16x32_bf16 v[20:23], v[132:135], v[216:219], v[20:23]
	v_mfma_f32_16x16x32_bf16 v[12:15], v[140:143], v[216:219], v[12:15]
	v_mfma_f32_16x16x32_bf16 v[60:63], v[136:139], v[176:179], v[60:63]
	v_mfma_f32_16x16x32_bf16 v[56:59], v[168:171], v[176:179], v[56:59]
	v_mfma_f32_16x16x32_bf16 v[52:55], v[136:139], v[204:207], v[52:55]
	v_mfma_f32_16x16x32_bf16 v[44:47], v[168:171], v[204:207], v[44:47]
	v_mfma_f32_16x16x32_bf16 v[28:31], v[136:139], v[212:215], v[28:31]
	v_mfma_f32_16x16x32_bf16 v[24:27], v[168:171], v[212:215], v[24:27]
	v_mfma_f32_16x16x32_bf16 v[20:23], v[136:139], v[220:223], v[20:23]
	v_mfma_f32_16x16x32_bf16 v[12:15], v[168:171], v[220:223], v[12:15]
	s_barrier
	s_add_u32 s10, s14, 0x100080
	s_addc_u32 s11, s15, 0
	s_add_i32 s14, s20, s52
	v_lshl_add_u64 v[132:133], s[10:11], 0, v[146:147]
	s_mov_b32 m0, s14
	s_nop 0
	global_load_lds_dwordx4 v[132:133], off
	v_lshl_add_u64 v[132:133], s[10:11], 0, v[144:145]
	s_add_i32 m0, s14, 0x2000
	s_nop 0
	global_load_lds_dwordx4 v[132:133], off
	v_add_u32_e32 v154, 0x10000, v157
	ds_read_b128 v[132:135], v154
	ds_read_b128 v[136:139], v154 offset:1024
	ds_read_b128 v[140:143], v154 offset:2048
	ds_read_b128 v[168:171], v154 offset:3072
	s_waitcnt vmcnt(10)
	s_barrier
; #define PG8_MMA(ai, bj, At, Bt) do { __builtin_amdgcn_s_setprio(1); _Pragma("unroll") for (int m = 0; m < 4; ++m) _Pragma("unroll") for (int n = 0; n < 2; ++n) _Pragma("unroll") for (int k = 0; k < 2; ++k) \
;         acc[ai][bj][m][n] = __builtin_amdgcn_mfma_f32_16x16x32_bf16(Bt[n][k], At[m][k], acc[ai][bj][m][n], 0, 0, 0); __builtin_amdgcn_s_setprio(0); } while (0)
; #define PG8_WAIT_V(n) asm volatile("s_waitcnt vmcnt(" #n ")" ::: "memory")
; #define PG8_BAR __builtin_amdgcn_s_barrier()
;     ...
;             PG8_WAIT_V(6); PG8_BAR; PG8_MMA(1, 1, At, B1); PG8_BAR;
;         }
;         E(acc, cur, wr, wc, fr, fq, lane);
;     __device__ __forceinline__ void operator()(const f32x4 (&acc)[2][2][4][2], const Unit& u, int wr, int wc, int fr, int fq, int lane) const {
;         const bool lat = u.pm < 128;
;         const int s = lat ? (u.pm >> 4) : 8;
;         const float* gate = modi + s * 6144 + 4096 + u.pn * BM + wc * 32 + 4 * fq;
;         const size_t r0 = lat ? (size_t)u.pm * BM : (size_t)(u.pm - 128) * BM;
;         const float* base = (lat ? baseL : baseC) + u.pn * BM + wc * 32 + 4 * fq;
;         float* out = (lat ? outL : outC) + u.pn * BM + wc * 32 + 4 * fq;
;         f32x4 gv[2][2];
; #pragma unroll
;         for (int bj = 0; bj < 2; ++bj)
; #pragma unroll
;             for (int n = 0; n < 2; ++n) gv[bj][n] = *(const f32x4*)(gate + bj * HALF + n * 16);
; #pragma unroll
;         for (int ai = 0; ai < 2; ++ai)
; #pragma unroll
;           for (int mh = 0; mh < 2; ++mh) {
;             f32x4 bs[2][2][2];
; #pragma unroll
;             for (int m2 = 0; m2 < 2; ++m2) {
;                 const size_t ro = (r0 + ai * HALF + wr * 64 + (mh * 2 + m2) * 16 + fr) * (size_t)D;
; #pragma unroll
;                 for (int bj = 0; bj < 2; ++bj)
; #pragma unroll
;                     for (int n = 0; n < 2; ++n) bs[m2][bj][n] = *(const f32x4*)(base + ro + bj * HALF + n * 16);
;             }
;             __builtin_amdgcn_sched_barrier(0);
; #pragma unroll
;             for (int m2 = 0; m2 < 2; ++m2) {
;                 const size_t ro = (r0 + ai * HALF + wr * 64 + (mh * 2 + m2) * 16 + fr) * (size_t)D;
; #pragma unroll
;                 for (int bj = 0; bj < 2; ++bj)
; #pragma unroll
;                     for (int n = 0; n < 2; ++n) *(f32x4*)(out + ro + bj * HALF + n * 16) = bs[m2][bj][n] + gv[bj][n] * acc[ai][bj][mh * 2 + m2][n];
	v_mfma_f32_16x16x32_bf16 v[48:51], v[224:227], v[172:175], v[48:51]
	v_mfma_f32_16x16x32_bf16 v[40:43], v[232:235], v[172:175], v[40:43]
	v_mfma_f32_16x16x32_bf16 v[36:39], v[224:227], v[180:183], v[36:39]
	v_mfma_f32_16x16x32_bf16 v[32:35], v[232:235], v[180:183], v[32:35]
	v_mfma_f32_16x16x32_bf16 v[16:19], v[224:227], v[208:211], v[16:19]
	v_mfma_f32_16x16x32_bf16 v[8:11], v[232:235], v[208:211], v[8:11]
	v_mfma_f32_16x16x32_bf16 v[4:7], v[224:227], v[216:219], v[4:7]
	v_mfma_f32_16x16x32_bf16 v[0:3], v[232:235], v[216:219], v[0:3]
	v_mfma_f32_16x16x32_bf16 v[48:51], v[228:231], v[176:179], v[48:51]
	v_mfma_f32_16x16x32_bf16 v[40:43], v[236:239], v[176:179], v[40:43]
	v_mfma_f32_16x16x32_bf16 v[36:39], v[228:231], v[204:207], v[36:39]
	v_mfma_f32_16x16x32_bf16 v[32:35], v[236:239], v[204:207], v[32:35]
	v_mfma_f32_16x16x32_bf16 v[16:19], v[228:231], v[212:215], v[16:19]
	v_mfma_f32_16x16x32_bf16 v[8:11], v[236:239], v[212:215], v[8:11]
	v_mfma_f32_16x16x32_bf16 v[4:7], v[228:231], v[220:223], v[4:7]
	v_mfma_f32_16x16x32_bf16 v[0:3], v[236:239], v[220:223], v[0:3]
	s_add_i32 s92, s92, 2
	s_add_u32 s46, s46, 0x100
	s_addc_u32 s47, s47, 0
	s_cmp_gt_u32 s92, 61
	s_barrier
	s_cbranch_scc0 .LBB0_335
	s_waitcnt lgkmcnt(0)
	s_cmpk_lt_i32 s0, 0x80
	s_cselect_b32 s3, s61, s67
	s_cselect_b32 s16, s60, s66
	s_add_i32 s9, s0, 0xffffff80
	s_cmpk_lt_i32 s0, 0x80
	s_cselect_b32 s10, s0, s9
	s_lshr_b32 s9, s0, 4
	s_cmpk_lt_i32 s0, 0x80
	s_mulk_i32 s9, 0x1800
	s_cselect_b32 s14, s9, 0xc000
	s_ashr_i32 s15, s14, 31
	s_lshl_b64 s[14:15], s[14:15], 2
	s_add_u32 s0, s68, s14
	s_addc_u32 s11, s69, s15
	s_lshl_b32 s8, s8, 8
	s_ashr_i32 s9, s8, 31
	s_lshl_b64 s[8:9], s[8:9], 2
	s_add_u32 s0, s0, s8
	s_addc_u32 s11, s11, s9
	s_add_u32 s14, s0, s90
	s_addc_u32 s15, s11, 0
	s_ashr_i32 s11, s10, 31
	s_add_u32 s0, s16, s8
	s_addc_u32 s3, s3, s9
	s_add_u32 s8, s0, s90
	s_addc_u32 s9, s3, 0
	v_lshl_add_u64 v[128:129], s[14:15], 0, v[160:161]
	s_mov_b64 s[14:15], 0x704000
	s_mov_b32 s0, 0x704000
	v_lshl_add_u64 v[154:155], s[8:9], 0, v[160:161]
	s_lshl_b64 s[8:9], s[10:11], 21
	v_lshl_add_u64 v[130:131], v[128:129], 0, s[14:15]
	v_add_co_u32_e32 v128, vcc, s0, v128
	v_lshl_add_u64 v[154:155], v[154:155], 0, s[8:9]
	s_nop 0
	v_addc_co_u32_e32 v129, vcc, 0, v129, vcc
	v_lshl_add_u64 v[154:155], v[154:155], 0, v[148:149]
	s_mov_b32 s0, 0x20000
	v_add_co_u32_e32 v184, vcc, s0, v154
	global_load_dwordx4 v[136:139], v[130:131], off offset:64
	global_load_dwordx4 v[132:135], v[130:131], off offset:512
	global_load_dwordx4 v[140:143], v[128:129], off
	s_nop 0
	global_load_dwordx4 v[128:131], v[130:131], off offset:576
	v_addc_co_u32_e32 v185, vcc, 0, v155, vcc
	global_load_dwordx4 v[168:171], v[154:155], off
	global_load_dwordx4 v[172:175], v[154:155], off offset:64
	global_load_dwordx4 v[176:179], v[154:155], off offset:512
	global_load_dwordx4 v[180:183], v[154:155], off offset:576
	global_load_dwordx4 v[204:207], v[184:185], off
	global_load_dwordx4 v[208:211], v[184:185], off offset:64
	global_load_dwordx4 v[212:215], v[184:185], off offset:512
	global_load_dwordx4 v[216:219], v[184:185], off offset:576
	s_waitcnt vmcnt(0)
	v_pk_fma_f32 v[106:107], v[106:107], v[130:131], v[182:183]
	v_pk_fma_f32 v[104:105], v[104:105], v[128:129], v[180:181]
	global_store_dwordx4 v[154:155], v[104:107], off offset:576
	v_pk_fma_f32 v[126:127], v[126:127], v[142:143], v[170:171]
	v_pk_fma_f32 v[124:125], v[124:125], v[140:141], v[168:169]
	v_pk_fma_f32 v[106:107], v[118:119], v[142:143], v[206:207]
	v_pk_fma_f32 v[104:105], v[116:117], v[140:141], v[204:205]
	v_pk_fma_f32 v[122:123], v[122:123], v[138:139], v[174:175]
	v_pk_fma_f32 v[120:121], v[120:121], v[136:137], v[172:173]
	v_pk_fma_f32 v[114:115], v[114:115], v[134:135], v[178:179]
	v_pk_fma_f32 v[112:113], v[112:113], v[132:133], v[176:177]
	global_store_dwordx4 v[184:185], v[104:107], off
	v_pk_fma_f32 v[102:103], v[102:103], v[134:135], v[214:215]
	v_pk_fma_f32 v[100:101], v[100:101], v[132:133], v[212:213]
	v_pk_fma_f32 v[106:107], v[110:111], v[138:139], v[210:211]
	v_pk_fma_f32 v[104:105], v[108:109], v[136:137], v[208:209]
	v_pk_fma_f32 v[98:99], v[98:99], v[130:131], v[218:219]
	v_pk_fma_f32 v[96:97], v[96:97], v[128:129], v[216:217]
	global_store_dwordx4 v[154:155], v[124:127], off
	global_store_dwordx4 v[154:155], v[120:123], off offset:64
	global_store_dwordx4 v[154:155], v[112:115], off offset:512
	global_store_dwordx4 v[184:185], v[104:107], off offset:64
	global_store_dwordx4 v[184:185], v[100:103], off offset:512
	global_store_dwordx4 v[184:185], v[96:99], off offset:576
	s_mov_b32 s0, 0x40000
	v_add_co_u32_e32 v168, vcc, s0, v154
	s_mov_b32 s0, 0x60000
	s_nop 0
	v_addc_co_u32_e32 v169, vcc, 0, v155, vcc
	v_add_co_u32_e32 v170, vcc, s0, v154
	global_load_dwordx4 v[96:99], v[168:169], off
	global_load_dwordx4 v[100:103], v[168:169], off offset:64
	global_load_dwordx4 v[104:107], v[168:169], off offset:512
	global_load_dwordx4 v[108:111], v[168:169], off offset:576
	v_addc_co_u32_e32 v171, vcc, 0, v155, vcc
	global_load_dwordx4 v[112:115], v[170:171], off
	global_load_dwordx4 v[116:119], v[170:171], off offset:64
	global_load_dwordx4 v[120:123], v[170:171], off offset:512
	global_load_dwordx4 v[124:127], v[170:171], off offset:576
	s_waitcnt vmcnt(0)
; #define PG8_WAIT_V(n) asm volatile("s_waitcnt vmcnt(" #n ")" ::: "memory")
; #define PG8_BAR __builtin_amdgcn_s_barrier()
;     ...
;         if (!has_next) break;
; #pragma unroll
;         for (int a = 0; a < 2; ++a)
; #pragma unroll
;             for (int b = 0; b < 2; ++b)
; #pragma unroll
;                 for (int m = 0; m < 4; ++m)
; #pragma unroll
;                     for (int n = 0; n < 2; ++n) acc[a][b][m][n] = (f32x4){0.f, 0.f, 0.f, 0.f};
;         cur = nxt; cA = nA; cB = nB; cAr = nAr; cHb = nHb; ++ui;
;     }
;     PG8_WAIT_V(0);
;     if (wr == 0) PG8_BAR;
;     PG8_BAR;
;     __device__ __forceinline__ void operator()(const f32x4 (&acc)[2][2][4][2], const Unit& u, int wr, int wc, int fr, int fq, int lane) const {
;     ...
;         for (int ai = 0; ai < 2; ++ai)
; #pragma unroll
;           for (int mh = 0; mh < 2; ++mh) {
;             f32x4 bs[2][2][2];
; #pragma unroll
;             for (int m2 = 0; m2 < 2; ++m2) {
;                 const size_t ro = (r0 + ai * HALF + wr * 64 + (mh * 2 + m2) * 16 + fr) * (size_t)D;
; #pragma unroll
;                 for (int bj = 0; bj < 2; ++bj)
; #pragma unroll
;                     for (int n = 0; n < 2; ++n) bs[m2][bj][n] = *(const f32x4*)(base + ro + bj * HALF + n * 16);
;             }
;             __builtin_amdgcn_sched_barrier(0);
; #pragma unroll
;             for (int m2 = 0; m2 < 2; ++m2) {
;                 const size_t ro = (r0 + ai * HALF + wr * 64 + (mh * 2 + m2) * 16 + fr) * (size_t)D;
; #pragma unroll
;                 for (int bj = 0; bj < 2; ++bj)
; #pragma unroll
;                     for (int n = 0; n < 2; ++n) *(f32x4*)(out + ro + bj * HALF + n * 16) = bs[m2][bj][n] + gv[bj][n] * acc[ai][bj][mh * 2 + m2][n];
;             }
;             __builtin_amdgcn_sched_barrier(0);
	v_pk_fma_f32 v[74:75], v[74:75], v[130:131], v[110:111]
	v_pk_fma_f32 v[72:73], v[72:73], v[128:129], v[108:109]
	global_store_dwordx4 v[168:169], v[72:75], off offset:576
	v_pk_fma_f32 v[94:95], v[94:95], v[142:143], v[98:99]
	v_pk_fma_f32 v[92:93], v[92:93], v[140:141], v[96:97]
	v_pk_fma_f32 v[74:75], v[86:87], v[142:143], v[114:115]
	v_pk_fma_f32 v[72:73], v[84:85], v[140:141], v[112:113]
	v_pk_fma_f32 v[90:91], v[90:91], v[138:139], v[102:103]
	v_pk_fma_f32 v[88:89], v[88:89], v[136:137], v[100:101]
	v_pk_fma_f32 v[82:83], v[82:83], v[134:135], v[106:107]
	v_pk_fma_f32 v[80:81], v[80:81], v[132:133], v[104:105]
	global_store_dwordx4 v[170:171], v[72:75], off
	v_pk_fma_f32 v[70:71], v[70:71], v[134:135], v[122:123]
	v_pk_fma_f32 v[68:69], v[68:69], v[132:133], v[120:121]
	v_pk_fma_f32 v[74:75], v[78:79], v[138:139], v[118:119]
	v_pk_fma_f32 v[72:73], v[76:77], v[136:137], v[116:117]
	v_pk_fma_f32 v[66:67], v[66:67], v[130:131], v[126:127]
	v_pk_fma_f32 v[64:65], v[64:65], v[128:129], v[124:125]
	global_store_dwordx4 v[168:169], v[92:95], off
	global_store_dwordx4 v[168:169], v[88:91], off offset:64
	global_store_dwordx4 v[168:169], v[80:83], off offset:512
	global_store_dwordx4 v[170:171], v[72:75], off offset:64
	global_store_dwordx4 v[170:171], v[68:71], off offset:512
	global_store_dwordx4 v[170:171], v[64:67], off offset:576
	v_add_co_u32_e32 v96, vcc, s76, v154
	s_nop 1
	v_addc_co_u32_e32 v97, vcc, 0, v155, vcc
	v_add_co_u32_e32 v98, vcc, s77, v154
	global_load_dwordx4 v[64:67], v[96:97], off
	global_load_dwordx4 v[68:71], v[96:97], off offset:64
	global_load_dwordx4 v[72:75], v[96:97], off offset:512
	global_load_dwordx4 v[76:79], v[96:97], off offset:576
	v_addc_co_u32_e32 v99, vcc, 0, v155, vcc
	global_load_dwordx4 v[80:83], v[98:99], off
	global_load_dwordx4 v[84:87], v[98:99], off offset:64
	global_load_dwordx4 v[88:91], v[98:99], off offset:512
	global_load_dwordx4 v[92:95], v[98:99], off offset:576
	s_waitcnt vmcnt(0)
	v_pk_fma_f32 v[42:43], v[42:43], v[130:131], v[78:79]
	v_pk_fma_f32 v[40:41], v[40:41], v[128:129], v[76:77]
	global_store_dwordx4 v[96:97], v[40:43], off offset:576
	v_pk_fma_f32 v[62:63], v[62:63], v[142:143], v[66:67]
	v_pk_fma_f32 v[60:61], v[60:61], v[140:141], v[64:65]
	v_pk_fma_f32 v[42:43], v[54:55], v[142:143], v[82:83]
	v_pk_fma_f32 v[40:41], v[52:53], v[140:141], v[80:81]
	v_pk_fma_f32 v[58:59], v[58:59], v[138:139], v[70:71]
	v_pk_fma_f32 v[56:57], v[56:57], v[136:137], v[68:69]
	v_pk_fma_f32 v[50:51], v[50:51], v[134:135], v[74:75]
	v_pk_fma_f32 v[48:49], v[48:49], v[132:133], v[72:73]
	global_store_dwordx4 v[98:99], v[40:43], off
	v_pk_fma_f32 v[38:39], v[38:39], v[134:135], v[90:91]
	v_pk_fma_f32 v[36:37], v[36:37], v[132:133], v[88:89]
	v_pk_fma_f32 v[42:43], v[46:47], v[138:139], v[86:87]
	v_pk_fma_f32 v[40:41], v[44:45], v[136:137], v[84:85]
	v_pk_fma_f32 v[34:35], v[34:35], v[130:131], v[94:95]
	v_pk_fma_f32 v[32:33], v[32:33], v[128:129], v[92:93]
	global_store_dwordx4 v[96:97], v[60:63], off
	global_store_dwordx4 v[96:97], v[56:59], off offset:64
	global_store_dwordx4 v[96:97], v[48:51], off offset:512
	global_store_dwordx4 v[98:99], v[40:43], off offset:64
	global_store_dwordx4 v[98:99], v[36:39], off offset:512
	global_store_dwordx4 v[98:99], v[32:35], off offset:576
	v_add_co_u32_e32 v64, vcc, s18, v154
	s_nop 1
	v_addc_co_u32_e32 v65, vcc, 0, v155, vcc
	v_add_co_u32_e32 v66, vcc, s54, v154
	global_load_dwordx4 v[32:35], v[64:65], off
	global_load_dwordx4 v[36:39], v[64:65], off offset:64
	global_load_dwordx4 v[40:43], v[64:65], off offset:512
	global_load_dwordx4 v[44:47], v[64:65], off offset:576
	v_addc_co_u32_e32 v67, vcc, 0, v155, vcc
	global_load_dwordx4 v[48:51], v[66:67], off
	global_load_dwordx4 v[52:55], v[66:67], off offset:64
	global_load_dwordx4 v[56:59], v[66:67], off offset:512
	global_load_dwordx4 v[60:63], v[66:67], off offset:576
	s_waitcnt vmcnt(0)
	v_pk_fma_f32 v[10:11], v[10:11], v[130:131], v[46:47]
	v_pk_fma_f32 v[8:9], v[8:9], v[128:129], v[44:45]
	global_store_dwordx4 v[64:65], v[8:11], off offset:576
	v_pk_fma_f32 v[30:31], v[30:31], v[142:143], v[34:35]
	v_pk_fma_f32 v[28:29], v[28:29], v[140:141], v[32:33]
	v_pk_fma_f32 v[10:11], v[22:23], v[142:143], v[50:51]
	v_pk_fma_f32 v[8:9], v[20:21], v[140:141], v[48:49]
	v_pk_fma_f32 v[26:27], v[26:27], v[138:139], v[38:39]
	v_pk_fma_f32 v[24:25], v[24:25], v[136:137], v[36:37]
	v_pk_fma_f32 v[18:19], v[18:19], v[134:135], v[42:43]
	v_pk_fma_f32 v[16:17], v[16:17], v[132:133], v[40:41]
	global_store_dwordx4 v[66:67], v[8:11], off
	v_pk_fma_f32 v[6:7], v[6:7], v[134:135], v[58:59]
	v_pk_fma_f32 v[4:5], v[4:5], v[132:133], v[56:57]
	v_pk_fma_f32 v[10:11], v[14:15], v[138:139], v[54:55]
	v_pk_fma_f32 v[8:9], v[12:13], v[136:137], v[52:53]
	v_pk_fma_f32 v[2:3], v[2:3], v[130:131], v[62:63]
	v_pk_fma_f32 v[0:1], v[0:1], v[128:129], v[60:61]
	global_store_dwordx4 v[64:65], v[28:31], off
	global_store_dwordx4 v[64:65], v[24:27], off offset:64
	global_store_dwordx4 v[64:65], v[16:19], off offset:512
	global_store_dwordx4 v[66:67], v[8:11], off offset:64
	global_store_dwordx4 v[66:67], v[4:7], off offset:512
	global_store_dwordx4 v[66:67], v[0:3], off offset:576
	s_and_b64 vcc, exec, s[42:43]
	s_mov_b32 s8, s2
	s_mov_b32 s0, s26
	s_mov_b64 s[20:21], s[38:39]
	s_mov_b64 s[44:45], s[36:37]
	s_cbranch_vccz .LBB0_332
	s_waitcnt vmcnt(0)
	s_cmpk_gt_u32 s5, 0xff
	s_cbranch_scc1 .LBB0_339
	s_barrier

; #define PG8_STAGE(bufoff, gbase, voff) do { _Pragma("unroll") for (int _i = 0; _i < 2; ++_i) \
;         __builtin_amdgcn_global_load_lds((const unsigned*)((const char*)(gbase) + (voff)[_i]), (LAS unsigned*)(lds + (bufoff) + ldsw + _i * 8192), 16, 0, 0); } while (0)
; #define PG8_STAGE_A(bufoff, ptr, half, rev) do { if (REVA && (rev)) { const char* _p = (ptr) - ((half) ? hstepA : 0); PG8_STAGE(bufoff, _p, voffAr); } else { const char* _p = (ptr) + ((half) ? hstepA : 0); PG8_STAGE(bufoff, _p, voffA); } } while (0)
; #define PG8_LDA(dst, b, h) do { _Pragma("unroll") for (int m = 0; m < 4; ++m) _Pragma("unroll") for (int k = 0; k < 2; ++k) dst[m][k] = *(const LAS bf16x8*)(lds + PG8_SA(b, h) + aoff + m * 2048 + k * 1024); } while (0)
; #define PG8_LDB(dst, b, h) do { _Pragma("unroll") for (int n = 0; n < 2; ++n) _Pragma("unroll") for (int k = 0; k < 2; ++k) dst[n][k] = *(const LAS bf16x8*)(lds + PG8_SB(b, h) + boff + n * 2048 + k * 1024); } while (0)
; #define PG8_WAIT_L(n) asm volatile("s_waitcnt lgkmcnt(" #n ")" ::: "memory")
; #define PG8_BAR __builtin_amdgcn_s_barrier()
; #define PG8_SCHED __builtin_amdgcn_sched_barrier(0)
;     ...
;         for (int t = 0; t < nt; t += 2) {
;             const bool last = (t == nt - 2);
;             const char* a1 = PG8_APTR(cA, cAr, t + 1); const bool r1 = REVA && ((t + 1) & 4);
;             const char* a2 = last ? nA : PG8_APTR(cA, cAr, t + 2); const bool r2 = REVA && !last && ((t + 2) & 4);
;             const char* a3 = last ? nA + kstep : PG8_APTR(cA, cAr, t + 3); const bool r3 = REVA && !last && ((t + 3) & 4);
;             const char* b2 = last ? nB : cB + (size_t)(t + 2) * kstep; const char* b3 = b2 + kstep; const size_t hb2 = last ? nHb : cHb;
;             PG8_LDB(B0, 0, 0); PG8_SCHED; PG8_LDA(At, 0, 0); PG8_STAGE_A(PG8_SA(1, 1), a1, 1, r1);
;             PG8_WAIT_L(8); PG8_BAR; PG8_WAIT_L(0); PG8_MMA(0, 0, At, B0); PG8_BAR; PG8_SCHED;
;             PG8_LDB(B1, 0, 1); PG8_STAGE(PG8_SB(0, 0), b2, voffB);
;             PG8_BAR; PG8_WAIT_L(0); PG8_MMA(0, 1, At, B1); PG8_BAR;
;     ...
; #pragma unroll
;         for (int a = 0; a < 2; ++a)
; #pragma unroll
;             for (int b = 0; b < 2; ++b)
; #pragma unroll
;                 for (int m = 0; m < 4; ++m)
; #pragma unroll
;                     for (int n = 0; n < 2; ++n) acc[a][b][m][n] = (f32x4){0.f, 0.f, 0.f, 0.f};
.LBB0_521:
	s_add_u32 s6, s38, 0x80
	s_addc_u32 s7, s39, 0
	s_add_u32 s8, s44, 0x80080
	s_addc_u32 s9, s45, 0
	v_lshl_add_u64 v[144:145], s[8:9], 0, v[140:141]
	v_lshl_add_u64 v[146:147], s[8:9], 0, v[142:143]
	s_add_u32 s8, s0, 0x100
	v_mov_b32_e32 v0, 0
	s_addc_u32 s9, s1, 0
	s_mov_b32 s22, -2
	s_mov_b64 s[0:1], 0
	v_mov_b32_e32 v1, v0
	v_pk_mov_b32 v[2:3], v[0:1], v[0:1]
	v_pk_mov_b32 v[4:5], v[0:1], v[0:1]
	v_pk_mov_b32 v[6:7], v[0:1], v[0:1]
	v_pk_mov_b32 v[8:9], v[0:1], v[0:1]
	v_pk_mov_b32 v[10:11], v[0:1], v[0:1]
	v_pk_mov_b32 v[12:13], v[0:1], v[0:1]
	v_pk_mov_b32 v[14:15], v[0:1], v[0:1]
	v_pk_mov_b32 v[16:17], v[0:1], v[0:1]
	v_pk_mov_b32 v[18:19], v[0:1], v[0:1]
	v_pk_mov_b32 v[20:21], v[0:1], v[0:1]
	v_pk_mov_b32 v[22:23], v[0:1], v[0:1]
	v_pk_mov_b32 v[24:25], v[0:1], v[0:1]
	v_pk_mov_b32 v[26:27], v[0:1], v[0:1]
	v_pk_mov_b32 v[28:29], v[0:1], v[0:1]
	v_pk_mov_b32 v[30:31], v[0:1], v[0:1]
	v_pk_mov_b32 v[32:33], v[0:1], v[0:1]
	v_pk_mov_b32 v[34:35], v[0:1], v[0:1]
	v_pk_mov_b32 v[36:37], v[0:1], v[0:1]
	v_pk_mov_b32 v[38:39], v[0:1], v[0:1]
	v_pk_mov_b32 v[40:41], v[0:1], v[0:1]
	v_pk_mov_b32 v[42:43], v[0:1], v[0:1]
	v_pk_mov_b32 v[44:45], v[0:1], v[0:1]
	v_pk_mov_b32 v[46:47], v[0:1], v[0:1]
	v_pk_mov_b32 v[48:49], v[0:1], v[0:1]
	v_pk_mov_b32 v[50:51], v[0:1], v[0:1]
	v_pk_mov_b32 v[52:53], v[0:1], v[0:1]
	v_pk_mov_b32 v[54:55], v[0:1], v[0:1]
	v_pk_mov_b32 v[56:57], v[0:1], v[0:1]
	v_pk_mov_b32 v[58:59], v[0:1], v[0:1]
	v_pk_mov_b32 v[60:61], v[0:1], v[0:1]
	v_pk_mov_b32 v[62:63], v[0:1], v[0:1]
	v_pk_mov_b32 v[64:65], v[0:1], v[0:1]
	v_pk_mov_b32 v[66:67], v[0:1], v[0:1]
	v_pk_mov_b32 v[68:69], v[0:1], v[0:1]
	v_pk_mov_b32 v[70:71], v[0:1], v[0:1]
	v_pk_mov_b32 v[72:73], v[0:1], v[0:1]
	v_pk_mov_b32 v[74:75], v[0:1], v[0:1]
	v_pk_mov_b32 v[76:77], v[0:1], v[0:1]
	v_pk_mov_b32 v[78:79], v[0:1], v[0:1]
	v_pk_mov_b32 v[80:81], v[0:1], v[0:1]
	v_pk_mov_b32 v[82:83], v[0:1], v[0:1]
	v_pk_mov_b32 v[84:85], v[0:1], v[0:1]
	v_pk_mov_b32 v[86:87], v[0:1], v[0:1]
	v_pk_mov_b32 v[88:89], v[0:1], v[0:1]
	v_pk_mov_b32 v[90:91], v[0:1], v[0:1]
	v_pk_mov_b32 v[92:93], v[0:1], v[0:1]
	v_pk_mov_b32 v[94:95], v[0:1], v[0:1]
	v_pk_mov_b32 v[96:97], v[0:1], v[0:1]
	v_pk_mov_b32 v[98:99], v[0:1], v[0:1]
	v_pk_mov_b32 v[100:101], v[0:1], v[0:1]
	v_pk_mov_b32 v[102:103], v[0:1], v[0:1]
	v_pk_mov_b32 v[104:105], v[0:1], v[0:1]
	v_pk_mov_b32 v[106:107], v[0:1], v[0:1]
	v_pk_mov_b32 v[108:109], v[0:1], v[0:1]
	v_pk_mov_b32 v[110:111], v[0:1], v[0:1]
	v_pk_mov_b32 v[112:113], v[0:1], v[0:1]
	v_pk_mov_b32 v[114:115], v[0:1], v[0:1]
	v_pk_mov_b32 v[116:117], v[0:1], v[0:1]
	v_pk_mov_b32 v[118:119], v[0:1], v[0:1]
	v_pk_mov_b32 v[120:121], v[0:1], v[0:1]
	v_pk_mov_b32 v[122:123], v[0:1], v[0:1]
	v_pk_mov_b32 v[124:125], v[0:1], v[0:1]
	v_pk_mov_b32 v[126:127], v[0:1], v[0:1]
	v_add_u32_e32 v160, 0x10000, v139
	ds_read_b128 v[156:159], v160
	ds_read_b128 v[168:171], v160 offset:1024
	ds_read_b128 v[172:175], v160 offset:2048
	ds_read_b128 v[176:179], v160 offset:3072
.LBB0_522:
	s_add_u32 s10, s44, s0
	s_addc_u32 s11, s45, s1
	s_add_u32 s14, s10, 0x100
	s_addc_u32 s15, s11, 0
	s_add_u32 s10, s10, 0x180
	s_addc_u32 s11, s11, 0
	s_add_u32 s16, s8, s0
	s_addc_u32 s17, s9, s1
	s_add_i32 s27, 0, 0x10000
	s_cmpk_eq_i32 s0, 0xf00
	s_cselect_b32 s21, s47, s17
	s_cselect_b32 s20, s46, s16
	s_cselect_b32 s17, s39, s15
	s_cselect_b32 s16, s38, s14
	s_cselect_b32 s90, s37, s3
	s_cselect_b32 s91, s36, s2
	s_cselect_b32 s15, s7, s11
	s_cselect_b32 s14, s6, s10
	v_lshl_add_u64 v[184:185], v[144:145], 0, s[0:1]
	s_add_i32 m0, s66, 0xc000
	ds_read_b128 v[180:183], v155
	ds_read_b128 v[204:207], v155 offset:1024
	ds_read_b128 v[208:211], v155 offset:2048
	ds_read_b128 v[212:215], v155 offset:3072
	ds_read_b128 v[216:219], v155 offset:4096
	ds_read_b128 v[220:223], v155 offset:5120
	ds_read_b128 v[224:227], v155 offset:6144
	ds_read_b128 v[228:231], v155 offset:7168
	global_load_lds_dwordx4 v[184:185], off
	v_lshl_add_u64 v[184:185], v[146:147], 0, s[0:1]
	s_add_i32 m0, s66, 0xe000
	s_nop 0
	global_load_lds_dwordx4 v[184:185], off
	s_waitcnt lgkmcnt(8)
	s_waitcnt vmcnt(10)
	s_barrier
	s_waitcnt lgkmcnt(0)
	v_mfma_f32_16x16x32_bf16 v[124:127], v[156:159], v[180:183], v[124:127]
	v_mfma_f32_16x16x32_bf16 v[120:123], v[172:175], v[180:183], v[120:123]
	v_mfma_f32_16x16x32_bf16 v[108:111], v[156:159], v[208:211], v[108:111]
	v_mfma_f32_16x16x32_bf16 v[104:107], v[172:175], v[208:211], v[104:107]
	v_mfma_f32_16x16x32_bf16 v[92:95], v[156:159], v[216:219], v[92:95]
	v_mfma_f32_16x16x32_bf16 v[88:91], v[172:175], v[216:219], v[88:91]
	v_mfma_f32_16x16x32_bf16 v[76:79], v[156:159], v[224:227], v[76:79]
	v_mfma_f32_16x16x32_bf16 v[72:75], v[172:175], v[224:227], v[72:75]
	v_mfma_f32_16x16x32_bf16 v[124:127], v[168:171], v[204:207], v[124:127]
	v_mfma_f32_16x16x32_bf16 v[120:123], v[176:179], v[204:207], v[120:123]
	v_mfma_f32_16x16x32_bf16 v[108:111], v[168:171], v[212:215], v[108:111]
	v_mfma_f32_16x16x32_bf16 v[104:107], v[176:179], v[212:215], v[104:107]
	v_mfma_f32_16x16x32_bf16 v[92:95], v[168:171], v[220:223], v[92:95]
	v_mfma_f32_16x16x32_bf16 v[88:91], v[176:179], v[220:223], v[88:91]
	v_mfma_f32_16x16x32_bf16 v[76:79], v[168:171], v[228:231], v[76:79]
	v_mfma_f32_16x16x32_bf16 v[72:75], v[176:179], v[228:231], v[72:75]
	s_barrier
	s_add_i32 s10, 0, 0x14000
	s_add_i32 s11, s27, s53
	v_add_u32_e32 v160, s10, v139
	v_lshl_add_u64 v[184:185], s[20:21], 0, v[130:131]
	s_mov_b32 m0, s11
	ds_read_b128 v[232:235], v160
	ds_read_b128 v[236:239], v160 offset:1024
	ds_read_b128 v[240:243], v160 offset:2048
	ds_read_b128 v[244:247], v160 offset:3072
	global_load_lds_dwordx4 v[184:185], off
	v_lshl_add_u64 v[248:249], s[20:21], 0, v[134:135]
	s_add_i32 m0, s11, 0x2000
	s_nop 0
	global_load_lds_dwordx4 v[248:249], off
	s_waitcnt vmcnt(10)
	s_barrier
; #define PG8_STAGE(bufoff, gbase, voff) do { _Pragma("unroll") for (int _i = 0; _i < 2; ++_i) \
;         __builtin_amdgcn_global_load_lds((const unsigned*)((const char*)(gbase) + (voff)[_i]), (LAS unsigned*)(lds + (bufoff) + ldsw + _i * 8192), 16, 0, 0); } while (0)
; #define PG8_STAGE_A(bufoff, ptr, half, rev) do { if (REVA && (rev)) { const char* _p = (ptr) - ((half) ? hstepA : 0); PG8_STAGE(bufoff, _p, voffAr); } else { const char* _p = (ptr) + ((half) ? hstepA : 0); PG8_STAGE(bufoff, _p, voffA); } } while (0)
; #define PG8_LDA(dst, b, h) do { _Pragma("unroll") for (int m = 0; m < 4; ++m) _Pragma("unroll") for (int k = 0; k < 2; ++k) dst[m][k] = *(const LAS bf16x8*)(lds + PG8_SA(b, h) + aoff + m * 2048 + k * 1024); } while (0)
; #define PG8_LDB(dst, b, h) do { _Pragma("unroll") for (int n = 0; n < 2; ++n) _Pragma("unroll") for (int k = 0; k < 2; ++k) dst[n][k] = *(const LAS bf16x8*)(lds + PG8_SB(b, h) + boff + n * 2048 + k * 1024); } while (0)
; #define PG8_MMA(ai, bj, At, Bt) do { __builtin_amdgcn_s_setprio(1); _Pragma("unroll") for (int m = 0; m < 4; ++m) _Pragma("unroll") for (int n = 0; n < 2; ++n) _Pragma("unroll") for (int k = 0; k < 2; ++k) \
;         acc[ai][bj][m][n] = __builtin_amdgcn_mfma_f32_16x16x32_bf16(Bt[n][k], At[m][k], acc[ai][bj][m][n], 0, 0, 0); __builtin_amdgcn_s_setprio(0); } while (0)
; #define PG8_WAIT_V(n) asm volatile("s_waitcnt vmcnt(" #n ")" ::: "memory")
; #define PG8_WAIT_L(n) asm volatile("s_waitcnt lgkmcnt(" #n ")" ::: "memory")
; #define PG8_BAR __builtin_amdgcn_s_barrier()
; #define PG8_SCHED __builtin_amdgcn_sched_barrier(0)
;     ...
;             PG8_BAR; PG8_WAIT_L(0); PG8_MMA(0, 1, At, B1); PG8_BAR;
;             PG8_LDA(At, 0, 1); PG8_STAGE_A(PG8_SA(0, 0), a2, 0, r2);
;             PG8_BAR; PG8_WAIT_L(0); PG8_MMA(1, 0, At, B0); PG8_BAR; PG8_SCHED;
;             PG8_STAGE(PG8_SB(0, 1), b2 + hb2, voffB);
;             PG8_WAIT_V(6); PG8_BAR; PG8_MMA(1, 1, At, B1); PG8_BAR;
;             PG8_LDB(B0, 1, 0); PG8_SCHED; PG8_LDA(At, 1, 0); PG8_STAGE_A(PG8_SA(0, 1), a2, 1, r2);
;             PG8_WAIT_L(8); PG8_BAR; PG8_WAIT_L(0); PG8_MMA(0, 0, At, B0); PG8_BAR; PG8_SCHED;
	s_waitcnt lgkmcnt(0)
	v_mfma_f32_16x16x32_bf16 v[116:119], v[232:235], v[180:183], v[116:119]
	v_mfma_f32_16x16x32_bf16 v[112:115], v[240:243], v[180:183], v[112:115]
	v_mfma_f32_16x16x32_bf16 v[100:103], v[232:235], v[208:211], v[100:103]
	v_mfma_f32_16x16x32_bf16 v[96:99], v[240:243], v[208:211], v[96:99]
	v_mfma_f32_16x16x32_bf16 v[84:87], v[232:235], v[216:219], v[84:87]
	v_mfma_f32_16x16x32_bf16 v[80:83], v[240:243], v[216:219], v[80:83]
	v_mfma_f32_16x16x32_bf16 v[68:71], v[232:235], v[224:227], v[68:71]
	v_mfma_f32_16x16x32_bf16 v[64:67], v[240:243], v[224:227], v[64:67]
	v_mfma_f32_16x16x32_bf16 v[116:119], v[236:239], v[204:207], v[116:119]
	v_mfma_f32_16x16x32_bf16 v[112:115], v[244:247], v[204:207], v[112:115]
	v_mfma_f32_16x16x32_bf16 v[100:103], v[236:239], v[212:215], v[100:103]
	v_mfma_f32_16x16x32_bf16 v[96:99], v[244:247], v[212:215], v[96:99]
	v_mfma_f32_16x16x32_bf16 v[84:87], v[236:239], v[220:223], v[84:87]
	v_mfma_f32_16x16x32_bf16 v[80:83], v[244:247], v[220:223], v[80:83]
	v_mfma_f32_16x16x32_bf16 v[68:71], v[236:239], v[228:231], v[68:71]
	v_mfma_f32_16x16x32_bf16 v[64:67], v[244:247], v[228:231], v[64:67]
	s_mov_b32 m0, s66
	v_lshl_add_u64 v[250:251], s[16:17], 0, v[128:129]
	s_barrier
	ds_read_b128 v[180:183], v155 offset:16384
	ds_read_b128 v[204:207], v155 offset:17408
	ds_read_b128 v[208:211], v155 offset:18432
	ds_read_b128 v[212:215], v155 offset:19456
	ds_read_b128 v[216:219], v155 offset:20480
	ds_read_b128 v[220:223], v155 offset:21504
	ds_read_b128 v[224:227], v155 offset:22528
	ds_read_b128 v[228:231], v155 offset:23552
	global_load_lds_dwordx4 v[250:251], off
	v_lshl_add_u64 v[250:251], s[16:17], 0, v[132:133]
	s_mov_b32 m0, s67
	s_nop 0
	global_load_lds_dwordx4 v[250:251], off
	s_waitcnt vmcnt(10)
	s_barrier
	s_waitcnt lgkmcnt(0)
	v_mfma_f32_16x16x32_bf16 v[60:63], v[156:159], v[180:183], v[60:63]
	v_mfma_f32_16x16x32_bf16 v[56:59], v[172:175], v[180:183], v[56:59]
	v_mfma_f32_16x16x32_bf16 v[44:47], v[156:159], v[208:211], v[44:47]
	v_mfma_f32_16x16x32_bf16 v[40:43], v[172:175], v[208:211], v[40:43]
	v_mfma_f32_16x16x32_bf16 v[28:31], v[156:159], v[216:219], v[28:31]
	v_mfma_f32_16x16x32_bf16 v[24:27], v[172:175], v[216:219], v[24:27]
	v_mfma_f32_16x16x32_bf16 v[12:15], v[156:159], v[224:227], v[12:15]
	v_mfma_f32_16x16x32_bf16 v[8:11], v[172:175], v[224:227], v[8:11]
	v_mfma_f32_16x16x32_bf16 v[60:63], v[168:171], v[204:207], v[60:63]
	v_mfma_f32_16x16x32_bf16 v[56:59], v[176:179], v[204:207], v[56:59]
	v_mfma_f32_16x16x32_bf16 v[44:47], v[168:171], v[212:215], v[44:47]
	v_mfma_f32_16x16x32_bf16 v[40:43], v[176:179], v[212:215], v[40:43]
	v_mfma_f32_16x16x32_bf16 v[28:31], v[168:171], v[220:223], v[28:31]
	v_mfma_f32_16x16x32_bf16 v[24:27], v[176:179], v[220:223], v[24:27]
	v_mfma_f32_16x16x32_bf16 v[12:15], v[168:171], v[228:231], v[12:15]
	v_mfma_f32_16x16x32_bf16 v[8:11], v[176:179], v[228:231], v[8:11]
	s_barrier
	s_add_u32 s20, s20, s91
	s_addc_u32 s21, s21, s90
	s_add_i32 s10, s10, s53
	v_lshl_add_u64 v[250:251], s[20:21], 0, v[130:131]
	s_mov_b32 m0, s10
	v_lshl_add_u64 v[190:191], s[20:21], 0, v[134:135]
	global_load_lds_dwordx4 v[250:251], off
	s_add_i32 m0, s10, 0x2000
	s_nop 0
	global_load_lds_dwordx4 v[190:191], off
	v_add_u32_e32 v160, 0x18000, v139
	ds_read_b128 v[156:159], v160
	ds_read_b128 v[168:171], v160 offset:1024
	ds_read_b128 v[172:175], v160 offset:2048
	ds_read_b128 v[176:179], v160 offset:3072
	s_waitcnt vmcnt(10)
	s_barrier
	v_mfma_f32_16x16x32_bf16 v[52:55], v[232:235], v[180:183], v[52:55]
	v_mfma_f32_16x16x32_bf16 v[48:51], v[240:243], v[180:183], v[48:51]
	v_mfma_f32_16x16x32_bf16 v[36:39], v[232:235], v[208:211], v[36:39]
	v_mfma_f32_16x16x32_bf16 v[32:35], v[240:243], v[208:211], v[32:35]
	v_mfma_f32_16x16x32_bf16 v[20:23], v[232:235], v[216:219], v[20:23]
	v_mfma_f32_16x16x32_bf16 v[16:19], v[240:243], v[216:219], v[16:19]
	v_mfma_f32_16x16x32_bf16 v[4:7], v[232:235], v[224:227], v[4:7]
	v_mfma_f32_16x16x32_bf16 v[0:3], v[240:243], v[224:227], v[0:3]
	v_mfma_f32_16x16x32_bf16 v[52:55], v[236:239], v[204:207], v[52:55]
	v_mfma_f32_16x16x32_bf16 v[48:51], v[244:247], v[204:207], v[48:51]
	v_mfma_f32_16x16x32_bf16 v[36:39], v[236:239], v[212:215], v[36:39]
	v_mfma_f32_16x16x32_bf16 v[32:35], v[244:247], v[212:215], v[32:35]
	v_mfma_f32_16x16x32_bf16 v[20:23], v[236:239], v[220:223], v[20:23]
	v_mfma_f32_16x16x32_bf16 v[16:19], v[244:247], v[220:223], v[16:19]
	v_mfma_f32_16x16x32_bf16 v[4:7], v[236:239], v[228:231], v[4:7]
	v_mfma_f32_16x16x32_bf16 v[0:3], v[244:247], v[228:231], v[0:3]
	s_add_i32 s10, 0, 0x18000
	s_barrier
	s_add_u32 s16, s16, 0x80000
	s_addc_u32 s17, s17, 0
	s_mov_b32 m0, s68
	v_lshl_add_u64 v[232:233], s[16:17], 0, v[128:129]
	ds_read_b128 v[180:183], v155 offset:32768
	ds_read_b128 v[204:207], v155 offset:33792
	ds_read_b128 v[208:211], v155 offset:34816
	ds_read_b128 v[212:215], v155 offset:35840
	ds_read_b128 v[216:219], v155 offset:36864
	ds_read_b128 v[220:223], v155 offset:37888
	ds_read_b128 v[224:227], v155 offset:38912
	ds_read_b128 v[228:231], v155 offset:39936
	global_load_lds_dwordx4 v[232:233], off
	v_lshl_add_u64 v[232:233], s[16:17], 0, v[132:133]
	s_mov_b32 m0, s69
	s_nop 0
	global_load_lds_dwordx4 v[232:233], off
	s_waitcnt lgkmcnt(8)
	s_waitcnt vmcnt(10)
	s_barrier
; #define PG8_STAGE(bufoff, gbase, voff) do { _Pragma("unroll") for (int _i = 0; _i < 2; ++_i) \
;         __builtin_amdgcn_global_load_lds((const unsigned*)((const char*)(gbase) + (voff)[_i]), (LAS unsigned*)(lds + (bufoff) + ldsw + _i * 8192), 16, 0, 0); } while (0)
; #define PG8_STAGE_A(bufoff, ptr, half, rev) do { if (REVA && (rev)) { const char* _p = (ptr) - ((half) ? hstepA : 0); PG8_STAGE(bufoff, _p, voffAr); } else { const char* _p = (ptr) + ((half) ? hstepA : 0); PG8_STAGE(bufoff, _p, voffA); } } while (0)
; #define PG8_LDA(dst, b, h) do { _Pragma("unroll") for (int m = 0; m < 4; ++m) _Pragma("unroll") for (int k = 0; k < 2; ++k) dst[m][k] = *(const LAS bf16x8*)(lds + PG8_SA(b, h) + aoff + m * 2048 + k * 1024); } while (0)
; #define PG8_LDB(dst, b, h) do { _Pragma("unroll") for (int n = 0; n < 2; ++n) _Pragma("unroll") for (int k = 0; k < 2; ++k) dst[n][k] = *(const LAS bf16x8*)(lds + PG8_SB(b, h) + boff + n * 2048 + k * 1024); } while (0)
; #define PG8_MMA(ai, bj, At, Bt) do { __builtin_amdgcn_s_setprio(1); _Pragma("unroll") for (int m = 0; m < 4; ++m) _Pragma("unroll") for (int n = 0; n < 2; ++n) _Pragma("unroll") for (int k = 0; k < 2; ++k) \
;         acc[ai][bj][m][n] = __builtin_amdgcn_mfma_f32_16x16x32_bf16(Bt[n][k], At[m][k], acc[ai][bj][m][n], 0, 0, 0); __builtin_amdgcn_s_setprio(0); } while (0)
; #define PG8_WAIT_L(n) asm volatile("s_waitcnt lgkmcnt(" #n ")" ::: "memory")
; #define PG8_BAR __builtin_amdgcn_s_barrier()
; #define PG8_SCHED __builtin_amdgcn_sched_barrier(0)
;     ...
;             PG8_WAIT_L(8); PG8_BAR; PG8_WAIT_L(0); PG8_MMA(0, 0, At, B0); PG8_BAR; PG8_SCHED;
;             PG8_LDB(B1, 1, 1); PG8_STAGE(PG8_SB(1, 0), b3, voffB);
;             PG8_BAR; PG8_WAIT_L(0); PG8_MMA(0, 1, At, B1); PG8_BAR;
;             PG8_LDA(At, 1, 1); PG8_STAGE_A(PG8_SA(1, 0), a3, 0, r3);
	s_waitcnt lgkmcnt(0)
	v_mfma_f32_16x16x32_bf16 v[124:127], v[156:159], v[180:183], v[124:127]
	v_mfma_f32_16x16x32_bf16 v[120:123], v[172:175], v[180:183], v[120:123]
	v_mfma_f32_16x16x32_bf16 v[108:111], v[156:159], v[208:211], v[108:111]
	v_mfma_f32_16x16x32_bf16 v[104:107], v[172:175], v[208:211], v[104:107]
	v_mfma_f32_16x16x32_bf16 v[92:95], v[156:159], v[216:219], v[92:95]
	v_mfma_f32_16x16x32_bf16 v[88:91], v[172:175], v[216:219], v[88:91]
	v_mfma_f32_16x16x32_bf16 v[76:79], v[156:159], v[224:227], v[76:79]
	v_mfma_f32_16x16x32_bf16 v[72:75], v[172:175], v[224:227], v[72:75]
	v_mfma_f32_16x16x32_bf16 v[124:127], v[168:171], v[204:207], v[124:127]
	v_mfma_f32_16x16x32_bf16 v[120:123], v[176:179], v[204:207], v[120:123]
	v_mfma_f32_16x16x32_bf16 v[108:111], v[168:171], v[212:215], v[108:111]
	v_mfma_f32_16x16x32_bf16 v[104:107], v[176:179], v[212:215], v[104:107]
	v_mfma_f32_16x16x32_bf16 v[92:95], v[168:171], v[220:223], v[92:95]
	v_mfma_f32_16x16x32_bf16 v[88:91], v[176:179], v[220:223], v[88:91]
	v_mfma_f32_16x16x32_bf16 v[76:79], v[168:171], v[228:231], v[76:79]
	v_mfma_f32_16x16x32_bf16 v[72:75], v[176:179], v[228:231], v[72:75]
	s_barrier
	s_add_i32 s11, 0, 0x1c000
	s_add_i32 s10, s10, s53
	v_add_u32_e32 v160, s11, v139
	v_lshl_add_u64 v[184:185], v[184:185], 0, s[28:29]
	s_mov_b32 m0, s10
	ds_read_b128 v[232:235], v160
	ds_read_b128 v[236:239], v160 offset:1024
	ds_read_b128 v[240:243], v160 offset:2048
	ds_read_b128 v[244:247], v160 offset:3072
	global_load_lds_dwordx4 v[184:185], off
	v_lshl_add_u64 v[184:185], v[248:249], 0, s[28:29]
	s_add_i32 m0, s10, 0x2000
	s_nop 0
	global_load_lds_dwordx4 v[184:185], off
	s_waitcnt vmcnt(10)
	s_barrier
	s_waitcnt lgkmcnt(0)
	v_mfma_f32_16x16x32_bf16 v[116:119], v[232:235], v[180:183], v[116:119]
	v_mfma_f32_16x16x32_bf16 v[112:115], v[240:243], v[180:183], v[112:115]
	v_mfma_f32_16x16x32_bf16 v[100:103], v[232:235], v[208:211], v[100:103]
	v_mfma_f32_16x16x32_bf16 v[96:99], v[240:243], v[208:211], v[96:99]
	v_mfma_f32_16x16x32_bf16 v[84:87], v[232:235], v[216:219], v[84:87]
	v_mfma_f32_16x16x32_bf16 v[80:83], v[240:243], v[216:219], v[80:83]
	v_mfma_f32_16x16x32_bf16 v[68:71], v[232:235], v[224:227], v[68:71]
	v_mfma_f32_16x16x32_bf16 v[64:67], v[240:243], v[224:227], v[64:67]
	v_mfma_f32_16x16x32_bf16 v[116:119], v[236:239], v[204:207], v[116:119]
	v_mfma_f32_16x16x32_bf16 v[112:115], v[244:247], v[204:207], v[112:115]
	v_mfma_f32_16x16x32_bf16 v[100:103], v[236:239], v[212:215], v[100:103]
	v_mfma_f32_16x16x32_bf16 v[96:99], v[244:247], v[212:215], v[96:99]
	v_mfma_f32_16x16x32_bf16 v[84:87], v[236:239], v[220:223], v[84:87]
	v_mfma_f32_16x16x32_bf16 v[80:83], v[244:247], v[220:223], v[80:83]
	v_mfma_f32_16x16x32_bf16 v[68:71], v[236:239], v[228:231], v[68:71]
	v_mfma_f32_16x16x32_bf16 v[64:67], v[244:247], v[228:231], v[64:67]
	s_mov_b32 m0, s70
	v_lshl_add_u64 v[184:185], s[14:15], 0, v[128:129]
	s_barrier
	ds_read_b128 v[180:183], v155 offset:49152
	ds_read_b128 v[204:207], v155 offset:50176
	ds_read_b128 v[208:211], v155 offset:51200
	ds_read_b128 v[212:215], v155 offset:52224
	ds_read_b128 v[216:219], v155 offset:53248
	ds_read_b128 v[220:223], v155 offset:54272
	ds_read_b128 v[224:227], v155 offset:55296
	ds_read_b128 v[228:231], v155 offset:56320
	global_load_lds_dwordx4 v[184:185], off
	v_lshl_add_u64 v[184:185], s[14:15], 0, v[132:133]
	s_mov_b32 m0, s71
	s_nop 0
	global_load_lds_dwordx4 v[184:185], off
	s_waitcnt vmcnt(10)
	s_barrier
; __device__ __forceinline__ unsigned cvt_pk_bf16(float lo, float hi) { unsigned r; asm volatile("v_cvt_pk_bf16_f32 %0, %1, %2" : "=v"(r) : "v"(lo), "v"(hi)); return r; }
; #define PG8_STAGE(bufoff, gbase, voff) do { _Pragma("unroll") for (int _i = 0; _i < 2; ++_i) \
;         __builtin_amdgcn_global_load_lds((const unsigned*)((const char*)(gbase) + (voff)[_i]), (LAS unsigned*)(lds + (bufoff) + ldsw + _i * 8192), 16, 0, 0); } while (0)
; #define PG8_WAIT_V(n) asm volatile("s_waitcnt vmcnt(" #n ")" ::: "memory")
; #define PG8_WAIT_L(n) asm volatile("s_waitcnt lgkmcnt(" #n ")" ::: "memory")
; #define PG8_BAR __builtin_amdgcn_s_barrier()
; #define PG8_SCHED __builtin_amdgcn_sched_barrier(0)
;     ...
;             PG8_BAR; PG8_WAIT_L(0); PG8_MMA(1, 0, At, B0); PG8_BAR; PG8_SCHED;
;             PG8_STAGE(PG8_SB(1, 1), b3 + hb2, voffB);
;             PG8_WAIT_V(6); PG8_BAR; PG8_MMA(1, 1, At, B1); PG8_BAR;
;         }
;         E(acc, cur, wr, wc, fr, fq, lane);
;     __device__ __forceinline__ void generic(const f32x4 (&acc)[2][2][4][2], const Unit& u, int wr, int wc, int fr, int fq) const {
;     ...
;                         if (u.pm < 8 && u.pn < 128) {
;                             if (bj == 0) {
;                                 const f32x4 a0 = acc[ai][0][m][0], a1 = acc[ai][0][m][1], b0 = acc[ai][1][m][0], b1 = acc[ai][1][m][1];
;                                 const f32x4 e0 = a0 + b0, e1 = a1 + b1, o0 = a0 - b0, o1 = a1 - b1;
;                                 bf16_t* p = O + (size_t)(u.pm * BM + rt) * T + (u.pn >> 4) * 4096 + (u.pn & 15) * 128 + wc * 32 + 8 * fq;
;                                 u32x4 w; w.x = cvt_pk_bf16(e0[0], e0[1]); w.y = cvt_pk_bf16(e0[2], e0[3]); w.z = cvt_pk_bf16(e1[0], e1[1]); w.w = cvt_pk_bf16(e1[2], e1[3]);
;                                 *(u32x4*)p = w;
;                                 w.x = cvt_pk_bf16(o0[0], o0[1]); w.y = cvt_pk_bf16(o0[2], o0[3]); w.z = cvt_pk_bf16(o1[0], o1[1]); w.w = cvt_pk_bf16(o1[2], o1[3]);
;                                 *(u32x4*)(p + 2048) = w;
;                             }
;                         } else {
;                             u32x4 w; w.x = cvt_pk_bf16(v0[0], v0[1]); w.y = cvt_pk_bf16(v0[2], v0[3]); w.z = cvt_pk_bf16(v1[0], v1[1]); w.w = cvt_pk_bf16(v1[2], v1[3]);
;                             *(u32x4*)(O + (size_t)(u.pm * BM + rt) * T + u.pn * BM + ct) = w;
	s_waitcnt lgkmcnt(0)
	v_mfma_f32_16x16x32_bf16 v[60:63], v[156:159], v[180:183], v[60:63]
	v_mfma_f32_16x16x32_bf16 v[56:59], v[172:175], v[180:183], v[56:59]
	v_mfma_f32_16x16x32_bf16 v[44:47], v[156:159], v[208:211], v[44:47]
	v_mfma_f32_16x16x32_bf16 v[40:43], v[172:175], v[208:211], v[40:43]
	v_mfma_f32_16x16x32_bf16 v[28:31], v[156:159], v[216:219], v[28:31]
	v_mfma_f32_16x16x32_bf16 v[24:27], v[172:175], v[216:219], v[24:27]
	v_mfma_f32_16x16x32_bf16 v[12:15], v[156:159], v[224:227], v[12:15]
	v_mfma_f32_16x16x32_bf16 v[8:11], v[172:175], v[224:227], v[8:11]
	v_mfma_f32_16x16x32_bf16 v[60:63], v[168:171], v[204:207], v[60:63]
	v_mfma_f32_16x16x32_bf16 v[56:59], v[176:179], v[204:207], v[56:59]
	v_mfma_f32_16x16x32_bf16 v[44:47], v[168:171], v[212:215], v[44:47]
	v_mfma_f32_16x16x32_bf16 v[40:43], v[176:179], v[212:215], v[40:43]
	v_mfma_f32_16x16x32_bf16 v[28:31], v[168:171], v[220:223], v[28:31]
	v_mfma_f32_16x16x32_bf16 v[24:27], v[176:179], v[220:223], v[24:27]
	v_mfma_f32_16x16x32_bf16 v[12:15], v[168:171], v[228:231], v[12:15]
	v_mfma_f32_16x16x32_bf16 v[8:11], v[176:179], v[228:231], v[8:11]
	s_barrier
	s_add_i32 s10, s11, s53
	v_lshl_add_u64 v[156:157], v[250:251], 0, s[28:29]
	s_mov_b32 m0, s10
	s_nop 0
	global_load_lds_dwordx4 v[156:157], off
	v_lshl_add_u64 v[156:157], v[190:191], 0, s[28:29]
	s_add_i32 m0, s10, 0x2000
	s_nop 0
	global_load_lds_dwordx4 v[156:157], off
	v_add_u32_e32 v160, 0x10000, v139
	ds_read_b128 v[156:159], v160
	ds_read_b128 v[168:171], v160 offset:1024
	ds_read_b128 v[172:175], v160 offset:2048
	ds_read_b128 v[176:179], v160 offset:3072
	s_waitcnt vmcnt(10)
	s_barrier
	v_mfma_f32_16x16x32_bf16 v[52:55], v[232:235], v[180:183], v[52:55]
	v_mfma_f32_16x16x32_bf16 v[48:51], v[240:243], v[180:183], v[48:51]
	v_mfma_f32_16x16x32_bf16 v[36:39], v[232:235], v[208:211], v[36:39]
	v_mfma_f32_16x16x32_bf16 v[32:35], v[240:243], v[208:211], v[32:35]
	v_mfma_f32_16x16x32_bf16 v[20:23], v[232:235], v[216:219], v[20:23]
	v_mfma_f32_16x16x32_bf16 v[16:19], v[240:243], v[216:219], v[16:19]
	v_mfma_f32_16x16x32_bf16 v[4:7], v[232:235], v[224:227], v[4:7]
	v_mfma_f32_16x16x32_bf16 v[0:3], v[240:243], v[224:227], v[0:3]
	v_mfma_f32_16x16x32_bf16 v[52:55], v[236:239], v[204:207], v[52:55]
	v_mfma_f32_16x16x32_bf16 v[48:51], v[244:247], v[204:207], v[48:51]
	v_mfma_f32_16x16x32_bf16 v[36:39], v[236:239], v[212:215], v[36:39]
	v_mfma_f32_16x16x32_bf16 v[32:35], v[244:247], v[212:215], v[32:35]
	v_mfma_f32_16x16x32_bf16 v[20:23], v[236:239], v[220:223], v[20:23]
	v_mfma_f32_16x16x32_bf16 v[16:19], v[244:247], v[220:223], v[16:19]
	v_mfma_f32_16x16x32_bf16 v[4:7], v[236:239], v[228:231], v[4:7]
	v_mfma_f32_16x16x32_bf16 v[0:3], v[244:247], v[228:231], v[0:3]
	s_add_i32 s22, s22, 2
	s_add_u32 s0, s0, 0x100
	s_addc_u32 s1, s1, 0
	s_cmp_gt_u32 s22, 29
	s_barrier
	s_cbranch_scc0 .LBB0_522
	s_waitcnt lgkmcnt(0)
	s_cmp_gt_i32 s89, 7
	s_cselect_b64 s[0:1], -1, 0
	s_cmpk_gt_i32 s5, 0x7f
	s_cselect_b64 s[2:3], -1, 0
	s_or_b64 s[0:1], s[0:1], s[2:3]
	s_mov_b64 s[2:3], -1
	s_and_b64 vcc, exec, s[0:1]
	v_lshl_add_u32 v146, s89, 8, v137
	v_lshlrev_b32_e32 v144, 1, v138
	s_cbranch_vccz .LBB0_525
	v_mov_b64_e32 v[168:169], s[24:25]
	v_mad_i64_i32 v[168:169], s[2:3], v146, s80, v[168:169]
	s_lshl_b32 s2, s5, 8
	s_ashr_i32 s3, s2, 31
	v_lshl_add_u64 v[168:169], s[2:3], 1, v[168:169]
	v_mov_b32_e32 v145, v161
	v_lshl_add_u64 v[168:169], v[168:169], 0, v[144:145]
	v_cvt_pk_bf16_f32 v156, v124, v125
	v_cvt_pk_bf16_f32 v157, v126, v127
	v_cvt_pk_bf16_f32 v158, v120, v121
	v_cvt_pk_bf16_f32 v159, v122, v123
	global_store_dwordx4 v[168:169], v[156:159], off
	s_mov_b64 s[2:3], 0

; #define PG8_STAGE(bufoff, gbase, voff) do { _Pragma("unroll") for (int _i = 0; _i < 2; ++_i) \
;         __builtin_amdgcn_global_load_lds((const unsigned*)((const char*)(gbase) + (voff)[_i]), (LAS unsigned*)(lds + (bufoff) + ldsw + _i * 8192), 16, 0, 0); } while (0)
; #define PG8_STAGE_A(bufoff, ptr, half, rev) do { if (REVA && (rev)) { const char* _p = (ptr) - ((half) ? hstepA : 0); PG8_STAGE(bufoff, _p, voffAr); } else { const char* _p = (ptr) + ((half) ? hstepA : 0); PG8_STAGE(bufoff, _p, voffA); } } while (0)
; #define PG8_LDA(dst, b, h) do { _Pragma("unroll") for (int m = 0; m < 4; ++m) _Pragma("unroll") for (int k = 0; k < 2; ++k) dst[m][k] = *(const LAS bf16x8*)(lds + PG8_SA(b, h) + aoff + m * 2048 + k * 1024); } while (0)
; #define PG8_LDB(dst, b, h) do { _Pragma("unroll") for (int n = 0; n < 2; ++n) _Pragma("unroll") for (int k = 0; k < 2; ++k) dst[n][k] = *(const LAS bf16x8*)(lds + PG8_SB(b, h) + boff + n * 2048 + k * 1024); } while (0)
; #define PG8_WAIT_L(n) asm volatile("s_waitcnt lgkmcnt(" #n ")" ::: "memory")
; #define PG8_BAR __builtin_amdgcn_s_barrier()
; #define PG8_SCHED __builtin_amdgcn_sched_barrier(0)
;     ...
;         for (int t = 0; t < nt; t += 2) {
;             const bool last = (t == nt - 2);
;             const char* a1 = PG8_APTR(cA, cAr, t + 1); const bool r1 = REVA && ((t + 1) & 4);
;             const char* a2 = last ? nA : PG8_APTR(cA, cAr, t + 2); const bool r2 = REVA && !last && ((t + 2) & 4);
;             const char* a3 = last ? nA + kstep : PG8_APTR(cA, cAr, t + 3); const bool r3 = REVA && !last && ((t + 3) & 4);
;             const char* b2 = last ? nB : cB + (size_t)(t + 2) * kstep; const char* b3 = b2 + kstep; const size_t hb2 = last ? nHb : cHb;
;             PG8_LDB(B0, 0, 0); PG8_SCHED; PG8_LDA(At, 0, 0); PG8_STAGE_A(PG8_SA(1, 1), a1, 1, r1);
;             PG8_WAIT_L(8); PG8_BAR; PG8_WAIT_L(0); PG8_MMA(0, 0, At, B0); PG8_BAR; PG8_SCHED;
;             PG8_LDB(B1, 0, 1); PG8_STAGE(PG8_SB(0, 0), b2, voffB);
;             PG8_BAR; PG8_WAIT_L(0); PG8_MMA(0, 1, At, B1); PG8_BAR;
;     ...
; #pragma unroll
;         for (int a = 0; a < 2; ++a)
; #pragma unroll
;             for (int b = 0; b < 2; ++b)
; #pragma unroll
;                 for (int m = 0; m < 4; ++m)
; #pragma unroll
;                     for (int n = 0; n < 2; ++n) acc[a][b][m][n] = (f32x4){0.f, 0.f, 0.f, 0.f};
.LBB0_566:
	s_add_u32 s25, s36, 0x80
	s_addc_u32 s27, s37, 0
	s_add_u32 s14, s38, 0x80080
	s_addc_u32 s15, s39, 0
	s_add_u32 s52, s0, 0x100
	v_mov_b32_e32 v0, 0
	v_lshl_add_u64 v[140:141], s[14:15], 0, v[136:137]
	v_lshl_add_u64 v[142:143], s[14:15], 0, v[138:139]
	s_addc_u32 s53, s1, 0
	s_mov_b32 s66, -2
	s_mov_b64 s[0:1], 0
	v_mov_b32_e32 v1, v0
	v_pk_mov_b32 v[2:3], v[0:1], v[0:1]
	v_pk_mov_b32 v[4:5], v[0:1], v[0:1]
	v_pk_mov_b32 v[6:7], v[0:1], v[0:1]
	v_pk_mov_b32 v[8:9], v[0:1], v[0:1]
	v_pk_mov_b32 v[10:11], v[0:1], v[0:1]
	v_pk_mov_b32 v[12:13], v[0:1], v[0:1]
	v_pk_mov_b32 v[14:15], v[0:1], v[0:1]
	v_pk_mov_b32 v[16:17], v[0:1], v[0:1]
	v_pk_mov_b32 v[18:19], v[0:1], v[0:1]
	v_pk_mov_b32 v[20:21], v[0:1], v[0:1]
	v_pk_mov_b32 v[22:23], v[0:1], v[0:1]
	v_pk_mov_b32 v[24:25], v[0:1], v[0:1]
	v_pk_mov_b32 v[26:27], v[0:1], v[0:1]
	v_pk_mov_b32 v[28:29], v[0:1], v[0:1]
	v_pk_mov_b32 v[30:31], v[0:1], v[0:1]
	v_pk_mov_b32 v[32:33], v[0:1], v[0:1]
	v_pk_mov_b32 v[34:35], v[0:1], v[0:1]
	v_pk_mov_b32 v[36:37], v[0:1], v[0:1]
	v_pk_mov_b32 v[38:39], v[0:1], v[0:1]
	v_pk_mov_b32 v[40:41], v[0:1], v[0:1]
	v_pk_mov_b32 v[42:43], v[0:1], v[0:1]
	v_pk_mov_b32 v[44:45], v[0:1], v[0:1]
	v_pk_mov_b32 v[46:47], v[0:1], v[0:1]
	v_pk_mov_b32 v[48:49], v[0:1], v[0:1]
	v_pk_mov_b32 v[50:51], v[0:1], v[0:1]
	v_pk_mov_b32 v[52:53], v[0:1], v[0:1]
	v_pk_mov_b32 v[54:55], v[0:1], v[0:1]
	v_pk_mov_b32 v[56:57], v[0:1], v[0:1]
	v_pk_mov_b32 v[58:59], v[0:1], v[0:1]
	v_pk_mov_b32 v[60:61], v[0:1], v[0:1]
	v_pk_mov_b32 v[62:63], v[0:1], v[0:1]
	v_pk_mov_b32 v[64:65], v[0:1], v[0:1]
	v_pk_mov_b32 v[66:67], v[0:1], v[0:1]
	v_pk_mov_b32 v[68:69], v[0:1], v[0:1]
	v_pk_mov_b32 v[70:71], v[0:1], v[0:1]
	v_pk_mov_b32 v[72:73], v[0:1], v[0:1]
	v_pk_mov_b32 v[74:75], v[0:1], v[0:1]
	v_pk_mov_b32 v[76:77], v[0:1], v[0:1]
	v_pk_mov_b32 v[78:79], v[0:1], v[0:1]
	v_pk_mov_b32 v[80:81], v[0:1], v[0:1]
	v_pk_mov_b32 v[82:83], v[0:1], v[0:1]
	v_pk_mov_b32 v[84:85], v[0:1], v[0:1]
	v_pk_mov_b32 v[86:87], v[0:1], v[0:1]
	v_pk_mov_b32 v[88:89], v[0:1], v[0:1]
	v_pk_mov_b32 v[90:91], v[0:1], v[0:1]
	v_pk_mov_b32 v[92:93], v[0:1], v[0:1]
	v_pk_mov_b32 v[94:95], v[0:1], v[0:1]
	v_pk_mov_b32 v[96:97], v[0:1], v[0:1]
	v_pk_mov_b32 v[98:99], v[0:1], v[0:1]
	v_pk_mov_b32 v[100:101], v[0:1], v[0:1]
	v_pk_mov_b32 v[102:103], v[0:1], v[0:1]
	v_pk_mov_b32 v[104:105], v[0:1], v[0:1]
	v_pk_mov_b32 v[106:107], v[0:1], v[0:1]
	v_pk_mov_b32 v[108:109], v[0:1], v[0:1]
	v_pk_mov_b32 v[110:111], v[0:1], v[0:1]
	v_pk_mov_b32 v[112:113], v[0:1], v[0:1]
	v_pk_mov_b32 v[114:115], v[0:1], v[0:1]
	v_pk_mov_b32 v[116:117], v[0:1], v[0:1]
	v_pk_mov_b32 v[118:119], v[0:1], v[0:1]
	v_pk_mov_b32 v[120:121], v[0:1], v[0:1]
	v_pk_mov_b32 v[122:123], v[0:1], v[0:1]
	v_pk_mov_b32 v[124:125], v[0:1], v[0:1]
	v_pk_mov_b32 v[126:127], v[0:1], v[0:1]
	v_add_u32_e32 v158, 0x10000, v145
	ds_read_b128 v[150:153], v158
	ds_read_b128 v[154:157], v158 offset:1024
	ds_read_b128 v[168:171], v158 offset:2048
	ds_read_b128 v[172:175], v158 offset:3072
.LBB0_567:
	s_add_u32 s10, s38, s0
	s_addc_u32 s11, s39, s1
	s_add_u32 s16, s10, 0x100
	s_addc_u32 s17, s11, 0
	s_add_u32 s10, s10, 0x180
	s_addc_u32 s11, s11, 0
	s_add_u32 s14, s52, s0
	s_addc_u32 s15, s53, s1
	s_add_i32 s67, 0, 0x10000
	s_cmpk_eq_i32 s0, 0xf00
	s_cselect_b32 s15, s45, s15
	s_cselect_b32 s14, s44, s14
	s_cselect_b32 s21, s37, s17
	s_cselect_b32 s20, s36, s16
	s_cselect_b32 s17, s27, s11
	s_cselect_b32 s16, s25, s10
	v_lshl_add_u64 v[158:159], v[140:141], 0, s[0:1]
	s_add_i32 m0, s22, 0xc000
	ds_read_b128 v[176:179], v149
	ds_read_b128 v[180:183], v149 offset:1024
	ds_read_b128 v[204:207], v149 offset:2048
	ds_read_b128 v[208:211], v149 offset:3072
	ds_read_b128 v[212:215], v149 offset:4096
	ds_read_b128 v[216:219], v149 offset:5120
	ds_read_b128 v[220:223], v149 offset:6144
	ds_read_b128 v[224:227], v149 offset:7168
	global_load_lds_dwordx4 v[158:159], off
	v_lshl_add_u64 v[158:159], v[142:143], 0, s[0:1]
	s_add_i32 m0, s22, 0xe000
	s_nop 0
	global_load_lds_dwordx4 v[158:159], off
	s_waitcnt lgkmcnt(8)
	s_waitcnt vmcnt(10)
	s_barrier
	s_waitcnt lgkmcnt(0)
	v_mfma_f32_16x16x32_bf16 v[124:127], v[150:153], v[176:179], v[124:127]
	v_mfma_f32_16x16x32_bf16 v[120:123], v[168:171], v[176:179], v[120:123]
	v_mfma_f32_16x16x32_bf16 v[116:119], v[150:153], v[204:207], v[116:119]
	v_mfma_f32_16x16x32_bf16 v[108:111], v[168:171], v[204:207], v[108:111]
	v_mfma_f32_16x16x32_bf16 v[100:103], v[150:153], v[212:215], v[100:103]
	v_mfma_f32_16x16x32_bf16 v[92:95], v[168:171], v[212:215], v[92:95]
	v_mfma_f32_16x16x32_bf16 v[84:87], v[150:153], v[220:223], v[84:87]
	v_mfma_f32_16x16x32_bf16 v[76:79], v[168:171], v[220:223], v[76:79]
	v_mfma_f32_16x16x32_bf16 v[124:127], v[154:157], v[180:183], v[124:127]
	v_mfma_f32_16x16x32_bf16 v[120:123], v[172:175], v[180:183], v[120:123]
	v_mfma_f32_16x16x32_bf16 v[116:119], v[154:157], v[208:211], v[116:119]
	v_mfma_f32_16x16x32_bf16 v[108:111], v[172:175], v[208:211], v[108:111]
	v_mfma_f32_16x16x32_bf16 v[100:103], v[154:157], v[216:219], v[100:103]
	v_mfma_f32_16x16x32_bf16 v[92:95], v[172:175], v[216:219], v[92:95]
	v_mfma_f32_16x16x32_bf16 v[84:87], v[154:157], v[224:227], v[84:87]
	v_mfma_f32_16x16x32_bf16 v[76:79], v[172:175], v[224:227], v[76:79]
	s_barrier
	s_add_i32 s10, 0, 0x14000
	v_add_u32_e32 v158, s10, v145
	s_add_i32 s11, s67, s5
	ds_read_b128 v[228:231], v158
	ds_read_b128 v[232:235], v158 offset:1024
	ds_read_b128 v[236:239], v158 offset:2048
	ds_read_b128 v[240:243], v158 offset:3072
	v_lshl_add_u64 v[158:159], s[14:15], 0, v[132:133]
	s_mov_b32 m0, s11
	v_lshl_add_u64 v[184:185], s[14:15], 0, v[128:129]
	global_load_lds_dwordx4 v[158:159], off
	s_add_i32 m0, s11, 0x2000
	s_nop 0
	global_load_lds_dwordx4 v[184:185], off
	s_waitcnt vmcnt(10)
	s_barrier
; #define PG8_STAGE(bufoff, gbase, voff) do { _Pragma("unroll") for (int _i = 0; _i < 2; ++_i) \
;         __builtin_amdgcn_global_load_lds((const unsigned*)((const char*)(gbase) + (voff)[_i]), (LAS unsigned*)(lds + (bufoff) + ldsw + _i * 8192), 16, 0, 0); } while (0)
; #define PG8_STAGE_A(bufoff, ptr, half, rev) do { if (REVA && (rev)) { const char* _p = (ptr) - ((half) ? hstepA : 0); PG8_STAGE(bufoff, _p, voffAr); } else { const char* _p = (ptr) + ((half) ? hstepA : 0); PG8_STAGE(bufoff, _p, voffA); } } while (0)
; #define PG8_LDA(dst, b, h) do { _Pragma("unroll") for (int m = 0; m < 4; ++m) _Pragma("unroll") for (int k = 0; k < 2; ++k) dst[m][k] = *(const LAS bf16x8*)(lds + PG8_SA(b, h) + aoff + m * 2048 + k * 1024); } while (0)
; #define PG8_LDB(dst, b, h) do { _Pragma("unroll") for (int n = 0; n < 2; ++n) _Pragma("unroll") for (int k = 0; k < 2; ++k) dst[n][k] = *(const LAS bf16x8*)(lds + PG8_SB(b, h) + boff + n * 2048 + k * 1024); } while (0)
; #define PG8_MMA(ai, bj, At, Bt) do { __builtin_amdgcn_s_setprio(1); _Pragma("unroll") for (int m = 0; m < 4; ++m) _Pragma("unroll") for (int n = 0; n < 2; ++n) _Pragma("unroll") for (int k = 0; k < 2; ++k) \
;         acc[ai][bj][m][n] = __builtin_amdgcn_mfma_f32_16x16x32_bf16(Bt[n][k], At[m][k], acc[ai][bj][m][n], 0, 0, 0); __builtin_amdgcn_s_setprio(0); } while (0)
; #define PG8_WAIT_V(n) asm volatile("s_waitcnt vmcnt(" #n ")" ::: "memory")
; #define PG8_WAIT_L(n) asm volatile("s_waitcnt lgkmcnt(" #n ")" ::: "memory")
; #define PG8_BAR __builtin_amdgcn_s_barrier()
; #define PG8_SCHED __builtin_amdgcn_sched_barrier(0)
;     ...
;             PG8_BAR; PG8_WAIT_L(0); PG8_MMA(0, 1, At, B1); PG8_BAR;
;             PG8_LDA(At, 0, 1); PG8_STAGE_A(PG8_SA(0, 0), a2, 0, r2);
;             PG8_BAR; PG8_WAIT_L(0); PG8_MMA(1, 0, At, B0); PG8_BAR; PG8_SCHED;
;             PG8_STAGE(PG8_SB(0, 1), b2 + hb2, voffB);
;             PG8_WAIT_V(6); PG8_BAR; PG8_MMA(1, 1, At, B1); PG8_BAR;
;             PG8_LDB(B0, 1, 0); PG8_SCHED; PG8_LDA(At, 1, 0); PG8_STAGE_A(PG8_SA(0, 1), a2, 1, r2);
;             PG8_WAIT_L(8); PG8_BAR; PG8_WAIT_L(0); PG8_MMA(0, 0, At, B0); PG8_BAR; PG8_SCHED;
	s_waitcnt lgkmcnt(0)
	v_mfma_f32_16x16x32_bf16 v[112:115], v[228:231], v[176:179], v[112:115]
	v_mfma_f32_16x16x32_bf16 v[104:107], v[236:239], v[176:179], v[104:107]
	v_mfma_f32_16x16x32_bf16 v[96:99], v[228:231], v[204:207], v[96:99]
	v_mfma_f32_16x16x32_bf16 v[88:91], v[236:239], v[204:207], v[88:91]
	v_mfma_f32_16x16x32_bf16 v[80:83], v[228:231], v[212:215], v[80:83]
	v_mfma_f32_16x16x32_bf16 v[72:75], v[236:239], v[212:215], v[72:75]
	v_mfma_f32_16x16x32_bf16 v[68:71], v[228:231], v[220:223], v[68:71]
	v_mfma_f32_16x16x32_bf16 v[64:67], v[236:239], v[220:223], v[64:67]
	v_mfma_f32_16x16x32_bf16 v[112:115], v[232:235], v[180:183], v[112:115]
	v_mfma_f32_16x16x32_bf16 v[104:107], v[240:243], v[180:183], v[104:107]
	v_mfma_f32_16x16x32_bf16 v[96:99], v[232:235], v[208:211], v[96:99]
	v_mfma_f32_16x16x32_bf16 v[88:91], v[240:243], v[208:211], v[88:91]
	v_mfma_f32_16x16x32_bf16 v[80:83], v[232:235], v[216:219], v[80:83]
	v_mfma_f32_16x16x32_bf16 v[72:75], v[240:243], v[216:219], v[72:75]
	v_mfma_f32_16x16x32_bf16 v[68:71], v[232:235], v[224:227], v[68:71]
	v_mfma_f32_16x16x32_bf16 v[64:67], v[240:243], v[224:227], v[64:67]
	s_mov_b32 m0, s22
	v_lshl_add_u64 v[190:191], s[20:21], 0, v[134:135]
	s_barrier
	ds_read_b128 v[176:179], v149 offset:16384
	ds_read_b128 v[180:183], v149 offset:17408
	ds_read_b128 v[204:207], v149 offset:18432
	ds_read_b128 v[208:211], v149 offset:19456
	ds_read_b128 v[212:215], v149 offset:20480
	ds_read_b128 v[216:219], v149 offset:21504
	ds_read_b128 v[220:223], v149 offset:22528
	ds_read_b128 v[224:227], v149 offset:23552
	global_load_lds_dwordx4 v[190:191], off
	v_lshl_add_u64 v[190:191], s[20:21], 0, v[130:131]
	s_mov_b32 m0, s46
	s_nop 0
	global_load_lds_dwordx4 v[190:191], off
	s_waitcnt vmcnt(10)
	s_barrier
	s_waitcnt lgkmcnt(0)
	v_mfma_f32_16x16x32_bf16 v[60:63], v[150:153], v[176:179], v[60:63]
	v_mfma_f32_16x16x32_bf16 v[56:59], v[168:171], v[176:179], v[56:59]
	v_mfma_f32_16x16x32_bf16 v[52:55], v[150:153], v[204:207], v[52:55]
	v_mfma_f32_16x16x32_bf16 v[44:47], v[168:171], v[204:207], v[44:47]
	v_mfma_f32_16x16x32_bf16 v[36:39], v[150:153], v[212:215], v[36:39]
	v_mfma_f32_16x16x32_bf16 v[28:31], v[168:171], v[212:215], v[28:31]
	v_mfma_f32_16x16x32_bf16 v[20:23], v[150:153], v[220:223], v[20:23]
	v_mfma_f32_16x16x32_bf16 v[12:15], v[168:171], v[220:223], v[12:15]
	v_mfma_f32_16x16x32_bf16 v[60:63], v[154:157], v[180:183], v[60:63]
	v_mfma_f32_16x16x32_bf16 v[56:59], v[172:175], v[180:183], v[56:59]
	v_mfma_f32_16x16x32_bf16 v[52:55], v[154:157], v[208:211], v[52:55]
	v_mfma_f32_16x16x32_bf16 v[44:47], v[172:175], v[208:211], v[44:47]
	v_mfma_f32_16x16x32_bf16 v[36:39], v[154:157], v[216:219], v[36:39]
	v_mfma_f32_16x16x32_bf16 v[28:31], v[172:175], v[216:219], v[28:31]
	v_mfma_f32_16x16x32_bf16 v[20:23], v[154:157], v[224:227], v[20:23]
	v_mfma_f32_16x16x32_bf16 v[12:15], v[172:175], v[224:227], v[12:15]
	s_barrier
	s_add_u32 s68, s14, 0x80000
	s_addc_u32 s69, s15, 0
	s_add_i32 s10, s10, s5
	v_lshl_add_u64 v[150:151], s[68:69], 0, v[132:133]
	s_mov_b32 m0, s10
	s_nop 0
	global_load_lds_dwordx4 v[150:151], off
	v_lshl_add_u64 v[150:151], s[68:69], 0, v[128:129]
	s_add_i32 m0, s10, 0x2000
	s_nop 0
	global_load_lds_dwordx4 v[150:151], off
	v_add_u32_e32 v172, 0x18000, v145
	ds_read_b128 v[150:153], v172
	ds_read_b128 v[154:157], v172 offset:1024
	ds_read_b128 v[168:171], v172 offset:2048
	ds_read_b128 v[172:175], v172 offset:3072
	s_waitcnt vmcnt(10)
	s_barrier
	v_mfma_f32_16x16x32_bf16 v[48:51], v[228:231], v[176:179], v[48:51]
	v_mfma_f32_16x16x32_bf16 v[40:43], v[236:239], v[176:179], v[40:43]
	v_mfma_f32_16x16x32_bf16 v[32:35], v[228:231], v[204:207], v[32:35]
	v_mfma_f32_16x16x32_bf16 v[24:27], v[236:239], v[204:207], v[24:27]
	v_mfma_f32_16x16x32_bf16 v[16:19], v[228:231], v[212:215], v[16:19]
	v_mfma_f32_16x16x32_bf16 v[8:11], v[236:239], v[212:215], v[8:11]
	v_mfma_f32_16x16x32_bf16 v[4:7], v[228:231], v[220:223], v[4:7]
	v_mfma_f32_16x16x32_bf16 v[0:3], v[236:239], v[220:223], v[0:3]
	v_mfma_f32_16x16x32_bf16 v[48:51], v[232:235], v[180:183], v[48:51]
	v_mfma_f32_16x16x32_bf16 v[40:43], v[240:243], v[180:183], v[40:43]
	v_mfma_f32_16x16x32_bf16 v[32:35], v[232:235], v[208:211], v[32:35]
	v_mfma_f32_16x16x32_bf16 v[24:27], v[240:243], v[208:211], v[24:27]
	v_mfma_f32_16x16x32_bf16 v[16:19], v[232:235], v[216:219], v[16:19]
	v_mfma_f32_16x16x32_bf16 v[8:11], v[240:243], v[216:219], v[8:11]
	v_mfma_f32_16x16x32_bf16 v[4:7], v[232:235], v[224:227], v[4:7]
	v_mfma_f32_16x16x32_bf16 v[0:3], v[240:243], v[224:227], v[0:3]
	s_add_i32 s10, 0, 0x18000
	s_barrier
	s_add_u32 s20, s20, 0x80000
	s_addc_u32 s21, s21, 0
	s_mov_b32 m0, s47
	v_lshl_add_u64 v[190:191], s[20:21], 0, v[134:135]
	ds_read_b128 v[176:179], v149 offset:32768
	ds_read_b128 v[180:183], v149 offset:33792
	ds_read_b128 v[204:207], v149 offset:34816
	ds_read_b128 v[208:211], v149 offset:35840
	ds_read_b128 v[212:215], v149 offset:36864
	ds_read_b128 v[216:219], v149 offset:37888
	ds_read_b128 v[220:223], v149 offset:38912
	ds_read_b128 v[224:227], v149 offset:39936
	global_load_lds_dwordx4 v[190:191], off
	v_lshl_add_u64 v[190:191], s[20:21], 0, v[130:131]
	s_mov_b32 m0, s50
	s_nop 0
	global_load_lds_dwordx4 v[190:191], off
	s_waitcnt lgkmcnt(8)
	s_waitcnt vmcnt(10)
	s_barrier
; #define PG8_STAGE(bufoff, gbase, voff) do { _Pragma("unroll") for (int _i = 0; _i < 2; ++_i) \
;         __builtin_amdgcn_global_load_lds((const unsigned*)((const char*)(gbase) + (voff)[_i]), (LAS unsigned*)(lds + (bufoff) + ldsw + _i * 8192), 16, 0, 0); } while (0)
; #define PG8_STAGE_A(bufoff, ptr, half, rev) do { if (REVA && (rev)) { const char* _p = (ptr) - ((half) ? hstepA : 0); PG8_STAGE(bufoff, _p, voffAr); } else { const char* _p = (ptr) + ((half) ? hstepA : 0); PG8_STAGE(bufoff, _p, voffA); } } while (0)
; #define PG8_LDA(dst, b, h) do { _Pragma("unroll") for (int m = 0; m < 4; ++m) _Pragma("unroll") for (int k = 0; k < 2; ++k) dst[m][k] = *(const LAS bf16x8*)(lds + PG8_SA(b, h) + aoff + m * 2048 + k * 1024); } while (0)
; #define PG8_LDB(dst, b, h) do { _Pragma("unroll") for (int n = 0; n < 2; ++n) _Pragma("unroll") for (int k = 0; k < 2; ++k) dst[n][k] = *(const LAS bf16x8*)(lds + PG8_SB(b, h) + boff + n * 2048 + k * 1024); } while (0)
; #define PG8_MMA(ai, bj, At, Bt) do { __builtin_amdgcn_s_setprio(1); _Pragma("unroll") for (int m = 0; m < 4; ++m) _Pragma("unroll") for (int n = 0; n < 2; ++n) _Pragma("unroll") for (int k = 0; k < 2; ++k) \
;         acc[ai][bj][m][n] = __builtin_amdgcn_mfma_f32_16x16x32_bf16(Bt[n][k], At[m][k], acc[ai][bj][m][n], 0, 0, 0); __builtin_amdgcn_s_setprio(0); } while (0)
; #define PG8_WAIT_V(n) asm volatile("s_waitcnt vmcnt(" #n ")" ::: "memory")
; #define PG8_WAIT_L(n) asm volatile("s_waitcnt lgkmcnt(" #n ")" ::: "memory")
; #define PG8_BAR __builtin_amdgcn_s_barrier()
; #define PG8_SCHED __builtin_amdgcn_sched_barrier(0)
;     ...
;             PG8_WAIT_L(8); PG8_BAR; PG8_WAIT_L(0); PG8_MMA(0, 0, At, B0); PG8_BAR; PG8_SCHED;
;             PG8_LDB(B1, 1, 1); PG8_STAGE(PG8_SB(1, 0), b3, voffB);
;             PG8_BAR; PG8_WAIT_L(0); PG8_MMA(0, 1, At, B1); PG8_BAR;
;             PG8_LDA(At, 1, 1); PG8_STAGE_A(PG8_SA(1, 0), a3, 0, r3);
;             PG8_BAR; PG8_WAIT_L(0); PG8_MMA(1, 0, At, B0); PG8_BAR; PG8_SCHED;
;             PG8_STAGE(PG8_SB(1, 1), b3 + hb2, voffB);
;             PG8_WAIT_V(6); PG8_BAR; PG8_MMA(1, 1, At, B1); PG8_BAR;
	s_waitcnt lgkmcnt(0)
	v_mfma_f32_16x16x32_bf16 v[124:127], v[150:153], v[176:179], v[124:127]
	v_mfma_f32_16x16x32_bf16 v[120:123], v[168:171], v[176:179], v[120:123]
	v_mfma_f32_16x16x32_bf16 v[116:119], v[150:153], v[204:207], v[116:119]
	v_mfma_f32_16x16x32_bf16 v[108:111], v[168:171], v[204:207], v[108:111]
	v_mfma_f32_16x16x32_bf16 v[100:103], v[150:153], v[212:215], v[100:103]
	v_mfma_f32_16x16x32_bf16 v[92:95], v[168:171], v[212:215], v[92:95]
	v_mfma_f32_16x16x32_bf16 v[84:87], v[150:153], v[220:223], v[84:87]
	v_mfma_f32_16x16x32_bf16 v[76:79], v[168:171], v[220:223], v[76:79]
	v_mfma_f32_16x16x32_bf16 v[124:127], v[154:157], v[180:183], v[124:127]
	v_mfma_f32_16x16x32_bf16 v[120:123], v[172:175], v[180:183], v[120:123]
	v_mfma_f32_16x16x32_bf16 v[116:119], v[154:157], v[208:211], v[116:119]
	v_mfma_f32_16x16x32_bf16 v[108:111], v[172:175], v[208:211], v[108:111]
	v_mfma_f32_16x16x32_bf16 v[100:103], v[154:157], v[216:219], v[100:103]
	v_mfma_f32_16x16x32_bf16 v[92:95], v[172:175], v[216:219], v[92:95]
	v_mfma_f32_16x16x32_bf16 v[84:87], v[154:157], v[224:227], v[84:87]
	v_mfma_f32_16x16x32_bf16 v[76:79], v[172:175], v[224:227], v[76:79]
	s_barrier
	s_add_i32 s11, 0, 0x1c000
	s_add_i32 s10, s10, s5
	v_add_u32_e32 v190, s11, v145
	v_lshl_add_u64 v[158:159], v[158:159], 0, s[28:29]
	s_mov_b32 m0, s10
	ds_read_b128 v[228:231], v190
	ds_read_b128 v[232:235], v190 offset:1024
	ds_read_b128 v[236:239], v190 offset:2048
	ds_read_b128 v[240:243], v190 offset:3072
	global_load_lds_dwordx4 v[158:159], off
	v_lshl_add_u64 v[158:159], v[184:185], 0, s[28:29]
	s_add_i32 m0, s10, 0x2000
	s_nop 0
	global_load_lds_dwordx4 v[158:159], off
	s_waitcnt vmcnt(10)
	s_barrier
	s_waitcnt lgkmcnt(0)
	v_mfma_f32_16x16x32_bf16 v[112:115], v[228:231], v[176:179], v[112:115]
	v_mfma_f32_16x16x32_bf16 v[104:107], v[236:239], v[176:179], v[104:107]
	v_mfma_f32_16x16x32_bf16 v[96:99], v[228:231], v[204:207], v[96:99]
	v_mfma_f32_16x16x32_bf16 v[88:91], v[236:239], v[204:207], v[88:91]
	v_mfma_f32_16x16x32_bf16 v[80:83], v[228:231], v[212:215], v[80:83]
	v_mfma_f32_16x16x32_bf16 v[72:75], v[236:239], v[212:215], v[72:75]
	v_mfma_f32_16x16x32_bf16 v[68:71], v[228:231], v[220:223], v[68:71]
	v_mfma_f32_16x16x32_bf16 v[64:67], v[236:239], v[220:223], v[64:67]
	v_mfma_f32_16x16x32_bf16 v[112:115], v[232:235], v[180:183], v[112:115]
	v_mfma_f32_16x16x32_bf16 v[104:107], v[240:243], v[180:183], v[104:107]
	v_mfma_f32_16x16x32_bf16 v[96:99], v[232:235], v[208:211], v[96:99]
	v_mfma_f32_16x16x32_bf16 v[88:91], v[240:243], v[208:211], v[88:91]
	v_mfma_f32_16x16x32_bf16 v[80:83], v[232:235], v[216:219], v[80:83]
	v_mfma_f32_16x16x32_bf16 v[72:75], v[240:243], v[216:219], v[72:75]
	v_mfma_f32_16x16x32_bf16 v[68:71], v[232:235], v[224:227], v[68:71]
	v_mfma_f32_16x16x32_bf16 v[64:67], v[240:243], v[224:227], v[64:67]
	s_mov_b32 m0, s48
	v_lshl_add_u64 v[158:159], s[16:17], 0, v[134:135]
	s_barrier
	ds_read_b128 v[176:179], v149 offset:49152
	ds_read_b128 v[180:183], v149 offset:50176
	ds_read_b128 v[204:207], v149 offset:51200
	ds_read_b128 v[208:211], v149 offset:52224
	ds_read_b128 v[212:215], v149 offset:53248
	ds_read_b128 v[216:219], v149 offset:54272
	ds_read_b128 v[220:223], v149 offset:55296
	ds_read_b128 v[224:227], v149 offset:56320
	global_load_lds_dwordx4 v[158:159], off
	v_lshl_add_u64 v[158:159], s[16:17], 0, v[130:131]
	s_mov_b32 m0, s49
	s_nop 0
	global_load_lds_dwordx4 v[158:159], off
	s_waitcnt vmcnt(10)
	s_barrier
	s_waitcnt lgkmcnt(0)
	v_mfma_f32_16x16x32_bf16 v[60:63], v[150:153], v[176:179], v[60:63]
	v_mfma_f32_16x16x32_bf16 v[56:59], v[168:171], v[176:179], v[56:59]
	v_mfma_f32_16x16x32_bf16 v[52:55], v[150:153], v[204:207], v[52:55]
	v_mfma_f32_16x16x32_bf16 v[44:47], v[168:171], v[204:207], v[44:47]
	v_mfma_f32_16x16x32_bf16 v[36:39], v[150:153], v[212:215], v[36:39]
	v_mfma_f32_16x16x32_bf16 v[28:31], v[168:171], v[212:215], v[28:31]
	v_mfma_f32_16x16x32_bf16 v[20:23], v[150:153], v[220:223], v[20:23]
	v_mfma_f32_16x16x32_bf16 v[12:15], v[168:171], v[220:223], v[12:15]
	v_mfma_f32_16x16x32_bf16 v[60:63], v[154:157], v[180:183], v[60:63]
	v_mfma_f32_16x16x32_bf16 v[56:59], v[172:175], v[180:183], v[56:59]
	v_mfma_f32_16x16x32_bf16 v[52:55], v[154:157], v[208:211], v[52:55]
	v_mfma_f32_16x16x32_bf16 v[44:47], v[172:175], v[208:211], v[44:47]
	v_mfma_f32_16x16x32_bf16 v[36:39], v[154:157], v[216:219], v[36:39]
	v_mfma_f32_16x16x32_bf16 v[28:31], v[172:175], v[216:219], v[28:31]
	v_mfma_f32_16x16x32_bf16 v[20:23], v[154:157], v[224:227], v[20:23]
	v_mfma_f32_16x16x32_bf16 v[12:15], v[172:175], v[224:227], v[12:15]
	s_barrier
	s_add_u32 s14, s14, 0x80080
	s_addc_u32 s15, s15, 0
	s_add_i32 s10, s11, s5
	v_lshl_add_u64 v[150:151], s[14:15], 0, v[132:133]
	s_mov_b32 m0, s10
	s_nop 0
	global_load_lds_dwordx4 v[150:151], off
	v_lshl_add_u64 v[150:151], s[14:15], 0, v[128:129]
	s_add_i32 m0, s10, 0x2000
	s_nop 0
	global_load_lds_dwordx4 v[150:151], off
	v_add_u32_e32 v158, 0x10000, v145
	ds_read_b128 v[150:153], v158
	ds_read_b128 v[154:157], v158 offset:1024
	ds_read_b128 v[168:171], v158 offset:2048
	ds_read_b128 v[172:175], v158 offset:3072
	s_waitcnt vmcnt(10)
	s_barrier
; __device__ __forceinline__ unsigned cvt_pk_bf16(float lo, float hi) { unsigned r; asm volatile("v_cvt_pk_bf16_f32 %0, %1, %2" : "=v"(r) : "v"(lo), "v"(hi)); return r; }
; #define PG8_MMA(ai, bj, At, Bt) do { __builtin_amdgcn_s_setprio(1); _Pragma("unroll") for (int m = 0; m < 4; ++m) _Pragma("unroll") for (int n = 0; n < 2; ++n) _Pragma("unroll") for (int k = 0; k < 2; ++k) \
;         acc[ai][bj][m][n] = __builtin_amdgcn_mfma_f32_16x16x32_bf16(Bt[n][k], At[m][k], acc[ai][bj][m][n], 0, 0, 0); __builtin_amdgcn_s_setprio(0); } while (0)
; #define PG8_WAIT_V(n) asm volatile("s_waitcnt vmcnt(" #n ")" ::: "memory")
; #define PG8_BAR __builtin_amdgcn_s_barrier()
;     ...
;             PG8_WAIT_V(6); PG8_BAR; PG8_MMA(1, 1, At, B1); PG8_BAR;
;         }
;         E(acc, cur, wr, wc, fr, fq, lane);
;         if (!has_next) break;
; #pragma unroll
;         for (int a = 0; a < 2; ++a)
; #pragma unroll
;             for (int b = 0; b < 2; ++b)
; #pragma unroll
;                 for (int m = 0; m < 4; ++m)
; #pragma unroll
;                     for (int n = 0; n < 2; ++n) acc[a][b][m][n] = (f32x4){0.f, 0.f, 0.f, 0.f};
;         cur = nxt; cA = nA; cB = nB; cAr = nAr; cHb = nHb; ++ui;
;     }
;     PG8_WAIT_V(0);
;     if (wr == 0) PG8_BAR;
;     PG8_BAR;
;     __device__ __forceinline__ void generic(const f32x4 (&acc)[2][2][4][2], const Unit& u, int wr, int wc, int fr, int fq) const {
;     ...
;                     } else if (MODE == 0) {
;                         u32x4 w; w.x = cvt_pk_bf16(v0[0], v0[1]); w.y = cvt_pk_bf16(v0[2], v0[3]); w.z = cvt_pk_bf16(v1[0], v1[1]); w.w = cvt_pk_bf16(v1[2], v1[3]);
;                         *(u32x4*)(O + (size_t)(u.pm * BM + rt) * ldc + u.pn * BM + ct) = w;
	v_mfma_f32_16x16x32_bf16 v[48:51], v[228:231], v[176:179], v[48:51]
	v_mfma_f32_16x16x32_bf16 v[40:43], v[236:239], v[176:179], v[40:43]
	v_mfma_f32_16x16x32_bf16 v[32:35], v[228:231], v[204:207], v[32:35]
	v_mfma_f32_16x16x32_bf16 v[24:27], v[236:239], v[204:207], v[24:27]
	v_mfma_f32_16x16x32_bf16 v[16:19], v[228:231], v[212:215], v[16:19]
	v_mfma_f32_16x16x32_bf16 v[8:11], v[236:239], v[212:215], v[8:11]
	v_mfma_f32_16x16x32_bf16 v[4:7], v[228:231], v[220:223], v[4:7]
	v_mfma_f32_16x16x32_bf16 v[0:3], v[236:239], v[220:223], v[0:3]
	v_mfma_f32_16x16x32_bf16 v[48:51], v[232:235], v[180:183], v[48:51]
	v_mfma_f32_16x16x32_bf16 v[40:43], v[240:243], v[180:183], v[40:43]
	v_mfma_f32_16x16x32_bf16 v[32:35], v[232:235], v[208:211], v[32:35]
	v_mfma_f32_16x16x32_bf16 v[24:27], v[240:243], v[208:211], v[24:27]
	v_mfma_f32_16x16x32_bf16 v[16:19], v[232:235], v[216:219], v[16:19]
	v_mfma_f32_16x16x32_bf16 v[8:11], v[240:243], v[216:219], v[8:11]
	v_mfma_f32_16x16x32_bf16 v[4:7], v[232:235], v[224:227], v[4:7]
	v_mfma_f32_16x16x32_bf16 v[0:3], v[240:243], v[224:227], v[0:3]
	s_add_i32 s66, s66, 2
	s_add_u32 s0, s0, 0x100
	s_addc_u32 s1, s1, 0
	s_cmp_gt_u32 s66, 29
	s_barrier
	s_cbranch_scc0 .LBB0_567
	s_waitcnt lgkmcnt(0)
	s_lshl_b32 s9, s9, 8
	v_cvt_pk_bf16_f32 v124, v124, v125
	v_cvt_pk_bf16_f32 v125, v126, v127
	v_cvt_pk_bf16_f32 v126, v120, v121
	v_add_u32_e32 v120, s9, v144
	v_ashrrev_i32_e32 v121, 31, v120
	s_lshl_b32 s0, s8, 8
	v_cvt_pk_bf16_f32 v127, v122, v123
	v_lshlrev_b64 v[122:123], 12, v[120:121]
	s_ashr_i32 s1, s0, 31
	v_lshl_add_u64 v[122:123], s[2:3], 0, v[122:123]
	s_lshl_b64 s[0:1], s[0:1], 1
	v_lshl_add_u64 v[122:123], v[122:123], 0, s[0:1]
	v_lshl_add_u64 v[122:123], v[122:123], 0, v[160:161]
	global_store_dwordx4 v[122:123], v[124:127], off
	v_cvt_pk_bf16_f32 v112, v112, v113
	v_cvt_pk_bf16_f32 v113, v114, v115
	v_cvt_pk_bf16_f32 v114, v104, v105
	v_cvt_pk_bf16_f32 v115, v106, v107
	global_store_dwordx4 v[122:123], v[112:115], off offset:256
	v_cvt_pk_bf16_f32 v104, v116, v117
	v_cvt_pk_bf16_f32 v105, v118, v119
	v_cvt_pk_bf16_f32 v106, v108, v109
	v_add_u32_e32 v108, s9, v146
	v_ashrrev_i32_e32 v109, 31, v108
	v_lshlrev_b64 v[108:109], 12, v[108:109]
	v_lshl_add_u64 v[108:109], s[2:3], 0, v[108:109]
	v_lshl_add_u64 v[108:109], v[108:109], 0, s[0:1]
	v_lshl_add_u64 v[108:109], v[108:109], 0, v[160:161]
	v_cvt_pk_bf16_f32 v107, v110, v111
	global_store_dwordx4 v[108:109], v[104:107], off
	v_cvt_pk_bf16_f32 v96, v96, v97
	v_cvt_pk_bf16_f32 v97, v98, v99
	v_cvt_pk_bf16_f32 v98, v88, v89
	v_cvt_pk_bf16_f32 v99, v90, v91
	global_store_dwordx4 v[108:109], v[96:99], off offset:256
	v_cvt_pk_bf16_f32 v88, v100, v101
	v_cvt_pk_bf16_f32 v89, v102, v103
	v_cvt_pk_bf16_f32 v90, v92, v93
	v_add_u32_e32 v92, s9, v147
	v_ashrrev_i32_e32 v93, 31, v92
	v_lshlrev_b64 v[92:93], 12, v[92:93]
	v_lshl_add_u64 v[92:93], s[2:3], 0, v[92:93]
	v_lshl_add_u64 v[92:93], v[92:93], 0, s[0:1]
	v_lshl_add_u64 v[92:93], v[92:93], 0, v[160:161]
	v_cvt_pk_bf16_f32 v91, v94, v95
	global_store_dwordx4 v[92:93], v[88:91], off
	v_cvt_pk_bf16_f32 v80, v80, v81
	v_cvt_pk_bf16_f32 v81, v82, v83
	v_cvt_pk_bf16_f32 v82, v72, v73
	v_cvt_pk_bf16_f32 v83, v74, v75
	global_store_dwordx4 v[92:93], v[80:83], off offset:256
	v_cvt_pk_bf16_f32 v72, v84, v85
	v_cvt_pk_bf16_f32 v73, v86, v87
	v_cvt_pk_bf16_f32 v74, v76, v77
	v_add_u32_e32 v76, s9, v148
	v_ashrrev_i32_e32 v77, 31, v76
	v_lshlrev_b64 v[76:77], 12, v[76:77]
	v_lshl_add_u64 v[76:77], s[2:3], 0, v[76:77]
	v_lshl_add_u64 v[76:77], v[76:77], 0, s[0:1]
	v_lshl_add_u64 v[76:77], v[76:77], 0, v[160:161]
	v_cvt_pk_bf16_f32 v75, v78, v79
	global_store_dwordx4 v[76:77], v[72:75], off
	v_cvt_pk_bf16_f32 v68, v68, v69
	v_cvt_pk_bf16_f32 v69, v70, v71
	v_cvt_pk_bf16_f32 v70, v64, v65
	v_cvt_pk_bf16_f32 v71, v66, v67
	global_store_dwordx4 v[76:77], v[68:71], off offset:256
	v_cvt_pk_bf16_f32 v60, v60, v61
	v_cvt_pk_bf16_f32 v61, v62, v63
	v_cvt_pk_bf16_f32 v62, v56, v57
	v_add_u32_e32 v56, 0x80, v120
	v_ashrrev_i32_e32 v57, 31, v56
	v_lshlrev_b64 v[56:57], 12, v[56:57]
	v_lshl_add_u64 v[56:57], s[2:3], 0, v[56:57]
	v_lshl_add_u64 v[56:57], v[56:57], 0, s[0:1]
	v_lshl_add_u64 v[56:57], v[56:57], 0, v[160:161]
	v_cvt_pk_bf16_f32 v63, v58, v59
	global_store_dwordx4 v[56:57], v[60:63], off
	v_cvt_pk_bf16_f32 v48, v48, v49
	v_cvt_pk_bf16_f32 v49, v50, v51
	v_cvt_pk_bf16_f32 v50, v40, v41
	v_cvt_pk_bf16_f32 v51, v42, v43
	global_store_dwordx4 v[56:57], v[48:51], off offset:256
	v_cvt_pk_bf16_f32 v40, v52, v53
	v_cvt_pk_bf16_f32 v41, v54, v55
	v_cvt_pk_bf16_f32 v42, v44, v45
	v_add_u32_e32 v44, 0x90, v120
	v_ashrrev_i32_e32 v45, 31, v44
	v_lshlrev_b64 v[44:45], 12, v[44:45]
	v_lshl_add_u64 v[44:45], s[2:3], 0, v[44:45]
	v_lshl_add_u64 v[44:45], v[44:45], 0, s[0:1]
	v_lshl_add_u64 v[44:45], v[44:45], 0, v[160:161]
	v_cvt_pk_bf16_f32 v43, v46, v47
	global_store_dwordx4 v[44:45], v[40:43], off
	v_cvt_pk_bf16_f32 v32, v32, v33
	v_cvt_pk_bf16_f32 v33, v34, v35
	v_cvt_pk_bf16_f32 v34, v24, v25
	v_cvt_pk_bf16_f32 v35, v26, v27
	global_store_dwordx4 v[44:45], v[32:35], off offset:256
	v_cvt_pk_bf16_f32 v24, v36, v37
	v_cvt_pk_bf16_f32 v25, v38, v39
	v_cvt_pk_bf16_f32 v26, v28, v29
	v_add_u32_e32 v28, 0xa0, v120
	v_ashrrev_i32_e32 v29, 31, v28
	v_lshlrev_b64 v[28:29], 12, v[28:29]
	v_lshl_add_u64 v[28:29], s[2:3], 0, v[28:29]
	v_lshl_add_u64 v[28:29], v[28:29], 0, s[0:1]
	v_lshl_add_u64 v[28:29], v[28:29], 0, v[160:161]
	v_cvt_pk_bf16_f32 v27, v30, v31
	global_store_dwordx4 v[28:29], v[24:27], off
	v_cvt_pk_bf16_f32 v16, v16, v17
	v_cvt_pk_bf16_f32 v17, v18, v19
	v_cvt_pk_bf16_f32 v18, v8, v9
	v_cvt_pk_bf16_f32 v19, v10, v11
	global_store_dwordx4 v[28:29], v[16:19], off offset:256
	v_cvt_pk_bf16_f32 v8, v20, v21
	v_cvt_pk_bf16_f32 v9, v22, v23
	v_cvt_pk_bf16_f32 v10, v12, v13
	v_add_u32_e32 v12, 0xb0, v120
	v_ashrrev_i32_e32 v13, 31, v12
	v_lshlrev_b64 v[12:13], 12, v[12:13]
	v_lshl_add_u64 v[12:13], s[2:3], 0, v[12:13]
	v_lshl_add_u64 v[12:13], v[12:13], 0, s[0:1]
	v_lshl_add_u64 v[12:13], v[12:13], 0, v[160:161]
	s_and_b64 vcc, exec, s[42:43]
	s_mov_b32 s8, s24
	s_mov_b32 s9, s26
	s_mov_b64 s[0:1], s[44:45]
	s_mov_b64 s[38:39], s[36:37]
	v_cvt_pk_bf16_f32 v11, v14, v15
	global_store_dwordx4 v[12:13], v[8:11], off
	v_cvt_pk_bf16_f32 v4, v4, v5
	v_cvt_pk_bf16_f32 v5, v6, v7
	v_cvt_pk_bf16_f32 v6, v0, v1
	v_cvt_pk_bf16_f32 v7, v2, v3
	global_store_dwordx4 v[12:13], v[4:7], off offset:256
	s_cbranch_vccz .LBB0_564
	s_waitcnt vmcnt(0)
	s_cmpk_gt_u32 s4, 0xff
	s_cbranch_scc1 .LBB0_571
	s_barrier

; #define PG8_STAGE(bufoff, gbase, voff) do { _Pragma("unroll") for (int _i = 0; _i < 2; ++_i) \
;         __builtin_amdgcn_global_load_lds((const unsigned*)((const char*)(gbase) + (voff)[_i]), (LAS unsigned*)(lds + (bufoff) + ldsw + _i * 8192), 16, 0, 0); } while (0)
; #define PG8_STAGE_A(bufoff, ptr, half, rev) do { if (REVA && (rev)) { const char* _p = (ptr) - ((half) ? hstepA : 0); PG8_STAGE(bufoff, _p, voffAr); } else { const char* _p = (ptr) + ((half) ? hstepA : 0); PG8_STAGE(bufoff, _p, voffA); } } while (0)
; #define PG8_LDA(dst, b, h) do { _Pragma("unroll") for (int m = 0; m < 4; ++m) _Pragma("unroll") for (int k = 0; k < 2; ++k) dst[m][k] = *(const LAS bf16x8*)(lds + PG8_SA(b, h) + aoff + m * 2048 + k * 1024); } while (0)
; #define PG8_LDB(dst, b, h) do { _Pragma("unroll") for (int n = 0; n < 2; ++n) _Pragma("unroll") for (int k = 0; k < 2; ++k) dst[n][k] = *(const LAS bf16x8*)(lds + PG8_SB(b, h) + boff + n * 2048 + k * 1024); } while (0)
; #define PG8_WAIT_L(n) asm volatile("s_waitcnt lgkmcnt(" #n ")" ::: "memory")
; #define PG8_BAR __builtin_amdgcn_s_barrier()
; #define PG8_SCHED __builtin_amdgcn_sched_barrier(0)
;     ...
;         for (int t = 0; t < nt; t += 2) {
;             const bool last = (t == nt - 2);
;             const char* a1 = PG8_APTR(cA, cAr, t + 1); const bool r1 = REVA && ((t + 1) & 4);
;             const char* a2 = last ? nA : PG8_APTR(cA, cAr, t + 2); const bool r2 = REVA && !last && ((t + 2) & 4);
;             const char* a3 = last ? nA + kstep : PG8_APTR(cA, cAr, t + 3); const bool r3 = REVA && !last && ((t + 3) & 4);
;             const char* b2 = last ? nB : cB + (size_t)(t + 2) * kstep; const char* b3 = b2 + kstep; const size_t hb2 = last ? nHb : cHb;
;             PG8_LDB(B0, 0, 0); PG8_SCHED; PG8_LDA(At, 0, 0); PG8_STAGE_A(PG8_SA(1, 1), a1, 1, r1);
;             PG8_WAIT_L(8); PG8_BAR; PG8_WAIT_L(0); PG8_MMA(0, 0, At, B0); PG8_BAR; PG8_SCHED;
;             PG8_LDB(B1, 0, 1); PG8_STAGE(PG8_SB(0, 0), b2, voffB);
;             PG8_BAR; PG8_WAIT_L(0); PG8_MMA(0, 1, At, B1); PG8_BAR;
;     ...
; #pragma unroll
;         for (int a = 0; a < 2; ++a)
; #pragma unroll
;             for (int b = 0; b < 2; ++b)
; #pragma unroll
;                 for (int m = 0; m < 4; ++m)
; #pragma unroll
;                     for (int n = 0; n < 2; ++n) acc[a][b][m][n] = (f32x4){0.f, 0.f, 0.f, 0.f};
.LBB0_902:
	s_add_u32 s8, s2, 0x80
	s_addc_u32 s9, s3, 0
	s_add_u32 s22, s0, 0x100
	s_addc_u32 s27, s1, 0
	s_add_u32 s0, s38, 0x80080
	s_addc_u32 s1, s39, 0
	v_mov_b32_e32 v0, 0
	v_lshl_add_u64 v[140:141], s[0:1], 0, v[136:137]
	v_lshl_add_u64 v[142:143], s[0:1], 0, v[138:139]
	s_mov_b32 s44, -2
	s_mov_b64 s[0:1], 0
	v_mov_b32_e32 v1, v0
	v_pk_mov_b32 v[2:3], v[0:1], v[0:1]
	v_pk_mov_b32 v[4:5], v[0:1], v[0:1]
	v_pk_mov_b32 v[6:7], v[0:1], v[0:1]
	v_pk_mov_b32 v[8:9], v[0:1], v[0:1]
	v_pk_mov_b32 v[10:11], v[0:1], v[0:1]
	v_pk_mov_b32 v[12:13], v[0:1], v[0:1]
	v_pk_mov_b32 v[14:15], v[0:1], v[0:1]
	v_pk_mov_b32 v[16:17], v[0:1], v[0:1]
	v_pk_mov_b32 v[18:19], v[0:1], v[0:1]
	v_pk_mov_b32 v[20:21], v[0:1], v[0:1]
	v_pk_mov_b32 v[22:23], v[0:1], v[0:1]
	v_pk_mov_b32 v[24:25], v[0:1], v[0:1]
	v_pk_mov_b32 v[26:27], v[0:1], v[0:1]
	v_pk_mov_b32 v[28:29], v[0:1], v[0:1]
	v_pk_mov_b32 v[30:31], v[0:1], v[0:1]
	v_pk_mov_b32 v[32:33], v[0:1], v[0:1]
	v_pk_mov_b32 v[34:35], v[0:1], v[0:1]
	v_pk_mov_b32 v[36:37], v[0:1], v[0:1]
	v_pk_mov_b32 v[38:39], v[0:1], v[0:1]
	v_pk_mov_b32 v[40:41], v[0:1], v[0:1]
	v_pk_mov_b32 v[42:43], v[0:1], v[0:1]
	v_pk_mov_b32 v[44:45], v[0:1], v[0:1]
	v_pk_mov_b32 v[46:47], v[0:1], v[0:1]
	v_pk_mov_b32 v[48:49], v[0:1], v[0:1]
	v_pk_mov_b32 v[50:51], v[0:1], v[0:1]
	v_pk_mov_b32 v[52:53], v[0:1], v[0:1]
	v_pk_mov_b32 v[54:55], v[0:1], v[0:1]
	v_pk_mov_b32 v[56:57], v[0:1], v[0:1]
	v_pk_mov_b32 v[58:59], v[0:1], v[0:1]
	v_pk_mov_b32 v[60:61], v[0:1], v[0:1]
	v_pk_mov_b32 v[62:63], v[0:1], v[0:1]
	v_pk_mov_b32 v[64:65], v[0:1], v[0:1]
	v_pk_mov_b32 v[66:67], v[0:1], v[0:1]
	v_pk_mov_b32 v[68:69], v[0:1], v[0:1]
	v_pk_mov_b32 v[70:71], v[0:1], v[0:1]
	v_pk_mov_b32 v[72:73], v[0:1], v[0:1]
	v_pk_mov_b32 v[74:75], v[0:1], v[0:1]
	v_pk_mov_b32 v[76:77], v[0:1], v[0:1]
	v_pk_mov_b32 v[78:79], v[0:1], v[0:1]
	v_pk_mov_b32 v[80:81], v[0:1], v[0:1]
	v_pk_mov_b32 v[82:83], v[0:1], v[0:1]
	v_pk_mov_b32 v[84:85], v[0:1], v[0:1]
	v_pk_mov_b32 v[86:87], v[0:1], v[0:1]
	v_pk_mov_b32 v[88:89], v[0:1], v[0:1]
	v_pk_mov_b32 v[90:91], v[0:1], v[0:1]
	v_pk_mov_b32 v[92:93], v[0:1], v[0:1]
	v_pk_mov_b32 v[94:95], v[0:1], v[0:1]
	v_pk_mov_b32 v[96:97], v[0:1], v[0:1]
	v_pk_mov_b32 v[98:99], v[0:1], v[0:1]
	v_pk_mov_b32 v[100:101], v[0:1], v[0:1]
	v_pk_mov_b32 v[102:103], v[0:1], v[0:1]
	v_pk_mov_b32 v[104:105], v[0:1], v[0:1]
	v_pk_mov_b32 v[106:107], v[0:1], v[0:1]
	v_pk_mov_b32 v[108:109], v[0:1], v[0:1]
	v_pk_mov_b32 v[110:111], v[0:1], v[0:1]
	v_pk_mov_b32 v[112:113], v[0:1], v[0:1]
	v_pk_mov_b32 v[114:115], v[0:1], v[0:1]
	v_pk_mov_b32 v[116:117], v[0:1], v[0:1]
	v_pk_mov_b32 v[118:119], v[0:1], v[0:1]
	v_pk_mov_b32 v[120:121], v[0:1], v[0:1]
	v_pk_mov_b32 v[122:123], v[0:1], v[0:1]
	v_pk_mov_b32 v[124:125], v[0:1], v[0:1]
	v_pk_mov_b32 v[126:127], v[0:1], v[0:1]
	v_add_u32_e32 v158, 0x10000, v145
	ds_read_b128 v[154:157], v158
	ds_read_b128 v[168:171], v158 offset:1024
	ds_read_b128 v[172:175], v158 offset:2048
	ds_read_b128 v[176:179], v158 offset:3072
.LBB0_903:
	s_add_u32 s10, s38, s0
	s_addc_u32 s11, s39, s1
	s_add_u32 s20, s10, 0x100
	s_addc_u32 s21, s11, 0
	s_add_u32 s10, s10, 0x180
	s_addc_u32 s11, s11, 0
	s_add_u32 s14, s22, s0
	s_addc_u32 s15, s27, s1
	s_add_i32 s45, 0, 0x10000
	s_cmpk_eq_i32 s0, 0xf00
	s_cselect_b32 s15, s37, s15
	s_cselect_b32 s14, s36, s14
	s_cselect_b32 s17, s9, s11
	s_cselect_b32 s16, s8, s10
	s_cselect_b32 s21, s3, s21
	s_cselect_b32 s20, s2, s20
	v_lshl_add_u64 v[158:159], v[140:141], 0, s[0:1]
	s_add_i32 m0, s48, 0xc000
	ds_read_b128 v[180:183], v153
	ds_read_b128 v[204:207], v153 offset:1024
	ds_read_b128 v[208:211], v153 offset:2048
	ds_read_b128 v[212:215], v153 offset:3072
	ds_read_b128 v[216:219], v153 offset:4096
	ds_read_b128 v[220:223], v153 offset:5120
	ds_read_b128 v[224:227], v153 offset:6144
	ds_read_b128 v[228:231], v153 offset:7168
	global_load_lds_dwordx4 v[158:159], off
	v_lshl_add_u64 v[158:159], v[142:143], 0, s[0:1]
	s_add_i32 m0, s48, 0xe000
	s_nop 0
	global_load_lds_dwordx4 v[158:159], off
	s_waitcnt lgkmcnt(8)
	s_waitcnt vmcnt(10)
	s_barrier
	s_waitcnt lgkmcnt(0)
	v_mfma_f32_16x16x32_bf16 v[124:127], v[154:157], v[180:183], v[124:127]
	v_mfma_f32_16x16x32_bf16 v[120:123], v[172:175], v[180:183], v[120:123]
	v_mfma_f32_16x16x32_bf16 v[108:111], v[154:157], v[208:211], v[108:111]
	v_mfma_f32_16x16x32_bf16 v[104:107], v[172:175], v[208:211], v[104:107]
	v_mfma_f32_16x16x32_bf16 v[92:95], v[154:157], v[216:219], v[92:95]
	v_mfma_f32_16x16x32_bf16 v[88:91], v[172:175], v[216:219], v[88:91]
	v_mfma_f32_16x16x32_bf16 v[76:79], v[154:157], v[224:227], v[76:79]
	v_mfma_f32_16x16x32_bf16 v[72:75], v[172:175], v[224:227], v[72:75]
	v_mfma_f32_16x16x32_bf16 v[124:127], v[168:171], v[204:207], v[124:127]
	v_mfma_f32_16x16x32_bf16 v[120:123], v[176:179], v[204:207], v[120:123]
	v_mfma_f32_16x16x32_bf16 v[108:111], v[168:171], v[212:215], v[108:111]
	v_mfma_f32_16x16x32_bf16 v[104:107], v[176:179], v[212:215], v[104:107]
	v_mfma_f32_16x16x32_bf16 v[92:95], v[168:171], v[220:223], v[92:95]
	v_mfma_f32_16x16x32_bf16 v[88:91], v[176:179], v[220:223], v[88:91]
	v_mfma_f32_16x16x32_bf16 v[76:79], v[168:171], v[228:231], v[76:79]
	v_mfma_f32_16x16x32_bf16 v[72:75], v[176:179], v[228:231], v[72:75]
	s_barrier
	s_add_i32 s10, 0, 0x14000
	v_add_u32_e32 v158, s10, v145
	s_add_i32 s11, s45, s47
	ds_read_b128 v[232:235], v158
	ds_read_b128 v[236:239], v158 offset:1024
	ds_read_b128 v[240:243], v158 offset:2048
	ds_read_b128 v[244:247], v158 offset:3072
	v_lshl_add_u64 v[158:159], s[14:15], 0, v[130:131]
	s_mov_b32 m0, s11
	v_lshl_add_u64 v[184:185], s[14:15], 0, v[134:135]
	global_load_lds_dwordx4 v[158:159], off
	s_add_i32 m0, s11, 0x2000
	s_nop 0
	global_load_lds_dwordx4 v[184:185], off
	s_waitcnt vmcnt(10)
	s_barrier
; #define PG8_STAGE(bufoff, gbase, voff) do { _Pragma("unroll") for (int _i = 0; _i < 2; ++_i) \
;         __builtin_amdgcn_global_load_lds((const unsigned*)((const char*)(gbase) + (voff)[_i]), (LAS unsigned*)(lds + (bufoff) + ldsw + _i * 8192), 16, 0, 0); } while (0)
; #define PG8_STAGE_A(bufoff, ptr, half, rev) do { if (REVA && (rev)) { const char* _p = (ptr) - ((half) ? hstepA : 0); PG8_STAGE(bufoff, _p, voffAr); } else { const char* _p = (ptr) + ((half) ? hstepA : 0); PG8_STAGE(bufoff, _p, voffA); } } while (0)
; #define PG8_LDA(dst, b, h) do { _Pragma("unroll") for (int m = 0; m < 4; ++m) _Pragma("unroll") for (int k = 0; k < 2; ++k) dst[m][k] = *(const LAS bf16x8*)(lds + PG8_SA(b, h) + aoff + m * 2048 + k * 1024); } while (0)
; #define PG8_LDB(dst, b, h) do { _Pragma("unroll") for (int n = 0; n < 2; ++n) _Pragma("unroll") for (int k = 0; k < 2; ++k) dst[n][k] = *(const LAS bf16x8*)(lds + PG8_SB(b, h) + boff + n * 2048 + k * 1024); } while (0)
; #define PG8_MMA(ai, bj, At, Bt) do { __builtin_amdgcn_s_setprio(1); _Pragma("unroll") for (int m = 0; m < 4; ++m) _Pragma("unroll") for (int n = 0; n < 2; ++n) _Pragma("unroll") for (int k = 0; k < 2; ++k) \
;         acc[ai][bj][m][n] = __builtin_amdgcn_mfma_f32_16x16x32_bf16(Bt[n][k], At[m][k], acc[ai][bj][m][n], 0, 0, 0); __builtin_amdgcn_s_setprio(0); } while (0)
; #define PG8_WAIT_V(n) asm volatile("s_waitcnt vmcnt(" #n ")" ::: "memory")
; #define PG8_WAIT_L(n) asm volatile("s_waitcnt lgkmcnt(" #n ")" ::: "memory")
; #define PG8_BAR __builtin_amdgcn_s_barrier()
; #define PG8_SCHED __builtin_amdgcn_sched_barrier(0)
;     ...
;             PG8_BAR; PG8_WAIT_L(0); PG8_MMA(0, 1, At, B1); PG8_BAR;
;             PG8_LDA(At, 0, 1); PG8_STAGE_A(PG8_SA(0, 0), a2, 0, r2);
;             PG8_BAR; PG8_WAIT_L(0); PG8_MMA(1, 0, At, B0); PG8_BAR; PG8_SCHED;
;             PG8_STAGE(PG8_SB(0, 1), b2 + hb2, voffB);
;             PG8_WAIT_V(6); PG8_BAR; PG8_MMA(1, 1, At, B1); PG8_BAR;
;             PG8_LDB(B0, 1, 0); PG8_SCHED; PG8_LDA(At, 1, 0); PG8_STAGE_A(PG8_SA(0, 1), a2, 1, r2);
;             PG8_WAIT_L(8); PG8_BAR; PG8_WAIT_L(0); PG8_MMA(0, 0, At, B0); PG8_BAR; PG8_SCHED;
	s_waitcnt lgkmcnt(0)
	v_mfma_f32_16x16x32_bf16 v[116:119], v[232:235], v[180:183], v[116:119]
	v_mfma_f32_16x16x32_bf16 v[112:115], v[240:243], v[180:183], v[112:115]
	v_mfma_f32_16x16x32_bf16 v[100:103], v[232:235], v[208:211], v[100:103]
	v_mfma_f32_16x16x32_bf16 v[96:99], v[240:243], v[208:211], v[96:99]
	v_mfma_f32_16x16x32_bf16 v[84:87], v[232:235], v[216:219], v[84:87]
	v_mfma_f32_16x16x32_bf16 v[80:83], v[240:243], v[216:219], v[80:83]
	v_mfma_f32_16x16x32_bf16 v[68:71], v[232:235], v[224:227], v[68:71]
	v_mfma_f32_16x16x32_bf16 v[64:67], v[240:243], v[224:227], v[64:67]
	v_mfma_f32_16x16x32_bf16 v[116:119], v[236:239], v[204:207], v[116:119]
	v_mfma_f32_16x16x32_bf16 v[112:115], v[244:247], v[204:207], v[112:115]
	v_mfma_f32_16x16x32_bf16 v[100:103], v[236:239], v[212:215], v[100:103]
	v_mfma_f32_16x16x32_bf16 v[96:99], v[244:247], v[212:215], v[96:99]
	v_mfma_f32_16x16x32_bf16 v[84:87], v[236:239], v[220:223], v[84:87]
	v_mfma_f32_16x16x32_bf16 v[80:83], v[244:247], v[220:223], v[80:83]
	v_mfma_f32_16x16x32_bf16 v[68:71], v[236:239], v[228:231], v[68:71]
	v_mfma_f32_16x16x32_bf16 v[64:67], v[244:247], v[228:231], v[64:67]
	s_mov_b32 m0, s48
	v_lshl_add_u64 v[190:191], s[20:21], 0, v[128:129]
	s_barrier
	ds_read_b128 v[180:183], v153 offset:16384
	ds_read_b128 v[204:207], v153 offset:17408
	ds_read_b128 v[208:211], v153 offset:18432
	ds_read_b128 v[212:215], v153 offset:19456
	ds_read_b128 v[216:219], v153 offset:20480
	ds_read_b128 v[220:223], v153 offset:21504
	ds_read_b128 v[224:227], v153 offset:22528
	ds_read_b128 v[228:231], v153 offset:23552
	global_load_lds_dwordx4 v[190:191], off
	v_lshl_add_u64 v[190:191], s[20:21], 0, v[132:133]
	s_mov_b32 m0, s49
	s_nop 0
	global_load_lds_dwordx4 v[190:191], off
	s_waitcnt vmcnt(10)
	s_barrier
	s_waitcnt lgkmcnt(0)
	v_mfma_f32_16x16x32_bf16 v[60:63], v[154:157], v[180:183], v[60:63]
	v_mfma_f32_16x16x32_bf16 v[56:59], v[172:175], v[180:183], v[56:59]
	v_mfma_f32_16x16x32_bf16 v[44:47], v[154:157], v[208:211], v[44:47]
	v_mfma_f32_16x16x32_bf16 v[40:43], v[172:175], v[208:211], v[40:43]
	v_mfma_f32_16x16x32_bf16 v[28:31], v[154:157], v[216:219], v[28:31]
	v_mfma_f32_16x16x32_bf16 v[24:27], v[172:175], v[216:219], v[24:27]
	v_mfma_f32_16x16x32_bf16 v[12:15], v[154:157], v[224:227], v[12:15]
	v_mfma_f32_16x16x32_bf16 v[8:11], v[172:175], v[224:227], v[8:11]
	v_mfma_f32_16x16x32_bf16 v[60:63], v[168:171], v[204:207], v[60:63]
	v_mfma_f32_16x16x32_bf16 v[56:59], v[176:179], v[204:207], v[56:59]
	v_mfma_f32_16x16x32_bf16 v[44:47], v[168:171], v[212:215], v[44:47]
	v_mfma_f32_16x16x32_bf16 v[40:43], v[176:179], v[212:215], v[40:43]
	v_mfma_f32_16x16x32_bf16 v[28:31], v[168:171], v[220:223], v[28:31]
	v_mfma_f32_16x16x32_bf16 v[24:27], v[176:179], v[220:223], v[24:27]
	v_mfma_f32_16x16x32_bf16 v[12:15], v[168:171], v[228:231], v[12:15]
	v_mfma_f32_16x16x32_bf16 v[8:11], v[176:179], v[228:231], v[8:11]
	s_barrier
	s_add_u32 s70, s14, 0x880000
	s_addc_u32 s71, s15, 0
	s_add_i32 s10, s10, s47
	v_lshl_add_u64 v[154:155], s[70:71], 0, v[130:131]
	s_mov_b32 m0, s10
	s_nop 0
	global_load_lds_dwordx4 v[154:155], off
	v_lshl_add_u64 v[154:155], s[70:71], 0, v[134:135]
	s_add_i32 m0, s10, 0x2000
	s_nop 0
	global_load_lds_dwordx4 v[154:155], off
	v_add_u32_e32 v176, 0x18000, v145
	ds_read_b128 v[154:157], v176
	ds_read_b128 v[168:171], v176 offset:1024
	ds_read_b128 v[172:175], v176 offset:2048
	ds_read_b128 v[176:179], v176 offset:3072
	s_waitcnt vmcnt(10)
	s_barrier
	v_mfma_f32_16x16x32_bf16 v[52:55], v[232:235], v[180:183], v[52:55]
	v_mfma_f32_16x16x32_bf16 v[48:51], v[240:243], v[180:183], v[48:51]
	v_mfma_f32_16x16x32_bf16 v[36:39], v[232:235], v[208:211], v[36:39]
	v_mfma_f32_16x16x32_bf16 v[32:35], v[240:243], v[208:211], v[32:35]
	v_mfma_f32_16x16x32_bf16 v[20:23], v[232:235], v[216:219], v[20:23]
	v_mfma_f32_16x16x32_bf16 v[16:19], v[240:243], v[216:219], v[16:19]
	v_mfma_f32_16x16x32_bf16 v[4:7], v[232:235], v[224:227], v[4:7]
	v_mfma_f32_16x16x32_bf16 v[0:3], v[240:243], v[224:227], v[0:3]
	v_mfma_f32_16x16x32_bf16 v[52:55], v[236:239], v[204:207], v[52:55]
	v_mfma_f32_16x16x32_bf16 v[48:51], v[244:247], v[204:207], v[48:51]
	v_mfma_f32_16x16x32_bf16 v[36:39], v[236:239], v[212:215], v[36:39]
	v_mfma_f32_16x16x32_bf16 v[32:35], v[244:247], v[212:215], v[32:35]
	v_mfma_f32_16x16x32_bf16 v[20:23], v[236:239], v[220:223], v[20:23]
	v_mfma_f32_16x16x32_bf16 v[16:19], v[244:247], v[220:223], v[16:19]
	v_mfma_f32_16x16x32_bf16 v[4:7], v[236:239], v[228:231], v[4:7]
	v_mfma_f32_16x16x32_bf16 v[0:3], v[244:247], v[228:231], v[0:3]
	s_add_i32 s10, 0, 0x18000
	s_barrier
	s_add_u32 s20, s20, 0x80000
	s_addc_u32 s21, s21, 0
	s_mov_b32 m0, s50
	v_lshl_add_u64 v[190:191], s[20:21], 0, v[128:129]
	ds_read_b128 v[180:183], v153 offset:32768
	ds_read_b128 v[204:207], v153 offset:33792
	ds_read_b128 v[208:211], v153 offset:34816
	ds_read_b128 v[212:215], v153 offset:35840
	ds_read_b128 v[216:219], v153 offset:36864
	ds_read_b128 v[220:223], v153 offset:37888
	ds_read_b128 v[224:227], v153 offset:38912
	ds_read_b128 v[228:231], v153 offset:39936
	global_load_lds_dwordx4 v[190:191], off
	v_lshl_add_u64 v[190:191], s[20:21], 0, v[132:133]
	s_mov_b32 m0, s51
	s_nop 0
	global_load_lds_dwordx4 v[190:191], off
	s_waitcnt lgkmcnt(8)
	s_waitcnt vmcnt(10)
	s_barrier
; #define PG8_STAGE(bufoff, gbase, voff) do { _Pragma("unroll") for (int _i = 0; _i < 2; ++_i) \
;         __builtin_amdgcn_global_load_lds((const unsigned*)((const char*)(gbase) + (voff)[_i]), (LAS unsigned*)(lds + (bufoff) + ldsw + _i * 8192), 16, 0, 0); } while (0)
; #define PG8_STAGE_A(bufoff, ptr, half, rev) do { if (REVA && (rev)) { const char* _p = (ptr) - ((half) ? hstepA : 0); PG8_STAGE(bufoff, _p, voffAr); } else { const char* _p = (ptr) + ((half) ? hstepA : 0); PG8_STAGE(bufoff, _p, voffA); } } while (0)
; #define PG8_LDA(dst, b, h) do { _Pragma("unroll") for (int m = 0; m < 4; ++m) _Pragma("unroll") for (int k = 0; k < 2; ++k) dst[m][k] = *(const LAS bf16x8*)(lds + PG8_SA(b, h) + aoff + m * 2048 + k * 1024); } while (0)
; #define PG8_LDB(dst, b, h) do { _Pragma("unroll") for (int n = 0; n < 2; ++n) _Pragma("unroll") for (int k = 0; k < 2; ++k) dst[n][k] = *(const LAS bf16x8*)(lds + PG8_SB(b, h) + boff + n * 2048 + k * 1024); } while (0)
; #define PG8_MMA(ai, bj, At, Bt) do { __builtin_amdgcn_s_setprio(1); _Pragma("unroll") for (int m = 0; m < 4; ++m) _Pragma("unroll") for (int n = 0; n < 2; ++n) _Pragma("unroll") for (int k = 0; k < 2; ++k) \
;         acc[ai][bj][m][n] = __builtin_amdgcn_mfma_f32_16x16x32_bf16(Bt[n][k], At[m][k], acc[ai][bj][m][n], 0, 0, 0); __builtin_amdgcn_s_setprio(0); } while (0)
; #define PG8_WAIT_L(n) asm volatile("s_waitcnt lgkmcnt(" #n ")" ::: "memory")
; #define PG8_BAR __builtin_amdgcn_s_barrier()
; #define PG8_SCHED __builtin_amdgcn_sched_barrier(0)
;     ...
;             PG8_LDB(B0, 1, 0); PG8_SCHED; PG8_LDA(At, 1, 0); PG8_STAGE_A(PG8_SA(0, 1), a2, 1, r2);
;             PG8_WAIT_L(8); PG8_BAR; PG8_WAIT_L(0); PG8_MMA(0, 0, At, B0); PG8_BAR; PG8_SCHED;
;             PG8_LDB(B1, 1, 1); PG8_STAGE(PG8_SB(1, 0), b3, voffB);
;             PG8_BAR; PG8_WAIT_L(0); PG8_MMA(0, 1, At, B1); PG8_BAR;
;             PG8_LDA(At, 1, 1); PG8_STAGE_A(PG8_SA(1, 0), a3, 0, r3);
;             PG8_BAR; PG8_WAIT_L(0); PG8_MMA(1, 0, At, B0); PG8_BAR; PG8_SCHED;
	s_waitcnt lgkmcnt(0)
	v_mfma_f32_16x16x32_bf16 v[124:127], v[154:157], v[180:183], v[124:127]
	v_mfma_f32_16x16x32_bf16 v[120:123], v[172:175], v[180:183], v[120:123]
	v_mfma_f32_16x16x32_bf16 v[108:111], v[154:157], v[208:211], v[108:111]
	v_mfma_f32_16x16x32_bf16 v[104:107], v[172:175], v[208:211], v[104:107]
	v_mfma_f32_16x16x32_bf16 v[92:95], v[154:157], v[216:219], v[92:95]
	v_mfma_f32_16x16x32_bf16 v[88:91], v[172:175], v[216:219], v[88:91]
	v_mfma_f32_16x16x32_bf16 v[76:79], v[154:157], v[224:227], v[76:79]
	v_mfma_f32_16x16x32_bf16 v[72:75], v[172:175], v[224:227], v[72:75]
	v_mfma_f32_16x16x32_bf16 v[124:127], v[168:171], v[204:207], v[124:127]
	v_mfma_f32_16x16x32_bf16 v[120:123], v[176:179], v[204:207], v[120:123]
	v_mfma_f32_16x16x32_bf16 v[108:111], v[168:171], v[212:215], v[108:111]
	v_mfma_f32_16x16x32_bf16 v[104:107], v[176:179], v[212:215], v[104:107]
	v_mfma_f32_16x16x32_bf16 v[92:95], v[168:171], v[220:223], v[92:95]
	v_mfma_f32_16x16x32_bf16 v[88:91], v[176:179], v[220:223], v[88:91]
	v_mfma_f32_16x16x32_bf16 v[76:79], v[168:171], v[228:231], v[76:79]
	v_mfma_f32_16x16x32_bf16 v[72:75], v[176:179], v[228:231], v[72:75]
	s_barrier
	s_add_i32 s11, 0, 0x1c000
	s_add_i32 s10, s10, s47
	v_add_u32_e32 v190, s11, v145
	v_lshl_add_u64 v[158:159], v[158:159], 0, s[28:29]
	s_mov_b32 m0, s10
	ds_read_b128 v[232:235], v190
	ds_read_b128 v[236:239], v190 offset:1024
	ds_read_b128 v[240:243], v190 offset:2048
	ds_read_b128 v[244:247], v190 offset:3072
	global_load_lds_dwordx4 v[158:159], off
	v_lshl_add_u64 v[158:159], v[184:185], 0, s[28:29]
	s_add_i32 m0, s10, 0x2000
	s_nop 0
	global_load_lds_dwordx4 v[158:159], off
	s_waitcnt vmcnt(10)
	s_barrier
	s_waitcnt lgkmcnt(0)
	v_mfma_f32_16x16x32_bf16 v[116:119], v[232:235], v[180:183], v[116:119]
	v_mfma_f32_16x16x32_bf16 v[112:115], v[240:243], v[180:183], v[112:115]
	v_mfma_f32_16x16x32_bf16 v[100:103], v[232:235], v[208:211], v[100:103]
	v_mfma_f32_16x16x32_bf16 v[96:99], v[240:243], v[208:211], v[96:99]
	v_mfma_f32_16x16x32_bf16 v[84:87], v[232:235], v[216:219], v[84:87]
	v_mfma_f32_16x16x32_bf16 v[80:83], v[240:243], v[216:219], v[80:83]
	v_mfma_f32_16x16x32_bf16 v[68:71], v[232:235], v[224:227], v[68:71]
	v_mfma_f32_16x16x32_bf16 v[64:67], v[240:243], v[224:227], v[64:67]
	v_mfma_f32_16x16x32_bf16 v[116:119], v[236:239], v[204:207], v[116:119]
	v_mfma_f32_16x16x32_bf16 v[112:115], v[244:247], v[204:207], v[112:115]
	v_mfma_f32_16x16x32_bf16 v[100:103], v[236:239], v[212:215], v[100:103]
	v_mfma_f32_16x16x32_bf16 v[96:99], v[244:247], v[212:215], v[96:99]
	v_mfma_f32_16x16x32_bf16 v[84:87], v[236:239], v[220:223], v[84:87]
	v_mfma_f32_16x16x32_bf16 v[80:83], v[244:247], v[220:223], v[80:83]
	v_mfma_f32_16x16x32_bf16 v[68:71], v[236:239], v[228:231], v[68:71]
	v_mfma_f32_16x16x32_bf16 v[64:67], v[244:247], v[228:231], v[64:67]
	s_mov_b32 m0, s66
	v_lshl_add_u64 v[158:159], s[16:17], 0, v[128:129]
	s_barrier
	ds_read_b128 v[180:183], v153 offset:49152
	ds_read_b128 v[204:207], v153 offset:50176
	ds_read_b128 v[208:211], v153 offset:51200
	ds_read_b128 v[212:215], v153 offset:52224
	ds_read_b128 v[216:219], v153 offset:53248
	ds_read_b128 v[220:223], v153 offset:54272
	ds_read_b128 v[224:227], v153 offset:55296
	ds_read_b128 v[228:231], v153 offset:56320
	global_load_lds_dwordx4 v[158:159], off
	v_lshl_add_u64 v[158:159], s[16:17], 0, v[132:133]
	s_mov_b32 m0, s67
	s_nop 0
	global_load_lds_dwordx4 v[158:159], off
	s_waitcnt vmcnt(10)
	s_barrier
; __device__ __forceinline__ unsigned cvt_pk_bf16(float lo, float hi) { unsigned r; asm volatile("v_cvt_pk_bf16_f32 %0, %1, %2" : "=v"(r) : "v"(lo), "v"(hi)); return r; }
; #define PG8_STAGE(bufoff, gbase, voff) do { _Pragma("unroll") for (int _i = 0; _i < 2; ++_i) \
;         __builtin_amdgcn_global_load_lds((const unsigned*)((const char*)(gbase) + (voff)[_i]), (LAS unsigned*)(lds + (bufoff) + ldsw + _i * 8192), 16, 0, 0); } while (0)
; #define PG8_MMA(ai, bj, At, Bt) do { __builtin_amdgcn_s_setprio(1); _Pragma("unroll") for (int m = 0; m < 4; ++m) _Pragma("unroll") for (int n = 0; n < 2; ++n) _Pragma("unroll") for (int k = 0; k < 2; ++k) \
;         acc[ai][bj][m][n] = __builtin_amdgcn_mfma_f32_16x16x32_bf16(Bt[n][k], At[m][k], acc[ai][bj][m][n], 0, 0, 0); __builtin_amdgcn_s_setprio(0); } while (0)
; #define PG8_WAIT_V(n) asm volatile("s_waitcnt vmcnt(" #n ")" ::: "memory")
; #define PG8_WAIT_L(n) asm volatile("s_waitcnt lgkmcnt(" #n ")" ::: "memory")
; #define PG8_BAR __builtin_amdgcn_s_barrier()
; #define PG8_SCHED __builtin_amdgcn_sched_barrier(0)
;     ...
;             PG8_BAR; PG8_WAIT_L(0); PG8_MMA(1, 0, At, B0); PG8_BAR; PG8_SCHED;
;             PG8_STAGE(PG8_SB(1, 1), b3 + hb2, voffB);
;             PG8_WAIT_V(6); PG8_BAR; PG8_MMA(1, 1, At, B1); PG8_BAR;
;         }
;         E(acc, cur, wr, wc, fr, fq, lane);
;     __device__ __forceinline__ void generic(const f32x4 (&acc)[2][2][4][2], const Unit& u, int wr, int wc, int fr, int fq) const {
;     ...
;                         const int b = u.pn >> 3, g = u.pn & 7, k = (Lb == 4096) ? (2 * ((u.pm & 7) * BM + rt) + (u.pm >> 3)) : (u.pm * BM + rt), rb = rowbase0 + b * (Lb + 1);
;                         u32x4 w; w.x = cvt_pk_bf16(v0[0], v0[1]); w.y = cvt_pk_bf16(v0[2], v0[3]); w.z = cvt_pk_bf16(v1[0], v1[1]); w.w = cvt_pk_bf16(v1[2], v1[3]);
;                         *(u32x4*)(O + (size_t)(rb + k) * 2048 + g * 256 + ct) = w;
;                         if (k == 0) *(u32x4*)(O + (size_t)(rb + Lb) * 2048 + g * 256 + ct) = w;
	s_waitcnt lgkmcnt(0)
	v_mfma_f32_16x16x32_bf16 v[60:63], v[154:157], v[180:183], v[60:63]
	v_mfma_f32_16x16x32_bf16 v[56:59], v[172:175], v[180:183], v[56:59]
	v_mfma_f32_16x16x32_bf16 v[44:47], v[154:157], v[208:211], v[44:47]
	v_mfma_f32_16x16x32_bf16 v[40:43], v[172:175], v[208:211], v[40:43]
	v_mfma_f32_16x16x32_bf16 v[28:31], v[154:157], v[216:219], v[28:31]
	v_mfma_f32_16x16x32_bf16 v[24:27], v[172:175], v[216:219], v[24:27]
	v_mfma_f32_16x16x32_bf16 v[12:15], v[154:157], v[224:227], v[12:15]
	v_mfma_f32_16x16x32_bf16 v[8:11], v[172:175], v[224:227], v[8:11]
	v_mfma_f32_16x16x32_bf16 v[60:63], v[168:171], v[204:207], v[60:63]
	v_mfma_f32_16x16x32_bf16 v[56:59], v[176:179], v[204:207], v[56:59]
	v_mfma_f32_16x16x32_bf16 v[44:47], v[168:171], v[212:215], v[44:47]
	v_mfma_f32_16x16x32_bf16 v[40:43], v[176:179], v[212:215], v[40:43]
	v_mfma_f32_16x16x32_bf16 v[28:31], v[168:171], v[220:223], v[28:31]
	v_mfma_f32_16x16x32_bf16 v[24:27], v[176:179], v[220:223], v[24:27]
	v_mfma_f32_16x16x32_bf16 v[12:15], v[168:171], v[228:231], v[12:15]
	v_mfma_f32_16x16x32_bf16 v[8:11], v[176:179], v[228:231], v[8:11]
	s_barrier
	s_add_u32 s14, s14, 0x880080
	s_addc_u32 s15, s15, 0
	s_add_i32 s10, s11, s47
	v_lshl_add_u64 v[154:155], s[14:15], 0, v[130:131]
	s_mov_b32 m0, s10
	s_nop 0
	global_load_lds_dwordx4 v[154:155], off
	v_lshl_add_u64 v[154:155], s[14:15], 0, v[134:135]
	s_add_i32 m0, s10, 0x2000
	s_nop 0
	global_load_lds_dwordx4 v[154:155], off
	v_add_u32_e32 v158, 0x10000, v145
	ds_read_b128 v[154:157], v158
	ds_read_b128 v[168:171], v158 offset:1024
	ds_read_b128 v[172:175], v158 offset:2048
	ds_read_b128 v[176:179], v158 offset:3072
	s_waitcnt vmcnt(10)
	s_barrier
	v_mfma_f32_16x16x32_bf16 v[52:55], v[232:235], v[180:183], v[52:55]
	v_mfma_f32_16x16x32_bf16 v[48:51], v[240:243], v[180:183], v[48:51]
	v_mfma_f32_16x16x32_bf16 v[36:39], v[232:235], v[208:211], v[36:39]
	v_mfma_f32_16x16x32_bf16 v[32:35], v[240:243], v[208:211], v[32:35]
	v_mfma_f32_16x16x32_bf16 v[20:23], v[232:235], v[216:219], v[20:23]
	v_mfma_f32_16x16x32_bf16 v[16:19], v[240:243], v[216:219], v[16:19]
	v_mfma_f32_16x16x32_bf16 v[4:7], v[232:235], v[224:227], v[4:7]
	v_mfma_f32_16x16x32_bf16 v[0:3], v[240:243], v[224:227], v[0:3]
	v_mfma_f32_16x16x32_bf16 v[52:55], v[236:239], v[204:207], v[52:55]
	v_mfma_f32_16x16x32_bf16 v[48:51], v[244:247], v[204:207], v[48:51]
	v_mfma_f32_16x16x32_bf16 v[36:39], v[236:239], v[212:215], v[36:39]
	v_mfma_f32_16x16x32_bf16 v[32:35], v[244:247], v[212:215], v[32:35]
	v_mfma_f32_16x16x32_bf16 v[20:23], v[236:239], v[220:223], v[20:23]
	v_mfma_f32_16x16x32_bf16 v[16:19], v[244:247], v[220:223], v[16:19]
	v_mfma_f32_16x16x32_bf16 v[4:7], v[236:239], v[228:231], v[4:7]
	v_mfma_f32_16x16x32_bf16 v[0:3], v[244:247], v[228:231], v[0:3]
	s_add_i32 s44, s44, 2
	s_add_u32 s0, s0, 0x100
	s_addc_u32 s1, s1, 0
	s_cmp_gt_u32 s44, 29
	s_barrier
	s_cbranch_scc0 .LBB0_903
	s_waitcnt lgkmcnt(0)
	s_lshl_b32 s1, s7, 8
	s_and_b32 s8, s1, 0x700
	s_ashr_i32 s0, s6, 3
	v_add_u32_e32 v140, s8, v144
	s_ashr_i32 s7, s7, 3
	v_lshl_add_u32 v140, v140, 1, s7
	s_mulk_i32 s0, 0x1001
	v_cvt_pk_bf16_f32 v124, v124, v125
	v_cvt_pk_bf16_f32 v125, v126, v127
	v_cvt_pk_bf16_f32 v126, v120, v121
	v_add_u32_e32 v120, s0, v140
	v_ashrrev_i32_e32 v121, 31, v120
	s_lshl_b32 s1, s6, 8
	v_lshlrev_b64 v[120:121], 12, v[120:121]
	s_and_b32 s1, s1, 0x700
	v_lshl_add_u64 v[120:121], s[24:25], 0, v[120:121]
	s_lshl_b32 s22, s1, 1
	v_lshl_add_u64 v[120:121], v[120:121], 0, s[22:23]
	v_lshl_add_u64 v[120:121], v[120:121], 0, v[160:161]
	v_cmp_eq_u32_e64 s[44:45], 0, v140
	v_cvt_pk_bf16_f32 v127, v122, v123
	global_store_dwordx4 v[120:121], v[124:127], off
	s_and_saveexec_b64 s[14:15], s[44:45]
	s_cbranch_execz .LBB0_906
	s_ashr_i32 s1, s0, 31
	s_lshl_b64 s[16:17], s[0:1], 12
	s_add_u32 s1, s24, s16
	s_addc_u32 s6, s25, s17
	s_add_u32 s16, s1, s22
	s_addc_u32 s17, s6, 0
	v_lshl_add_u64 v[122:123], s[16:17], 0, v[160:161]
	v_add_co_u32_e32 v122, vcc, 0x1000000, v122
	s_nop 1
	v_addc_co_u32_e32 v123, vcc, 0, v123, vcc
	global_store_dwordx4 v[122:123], v[124:127], off

;     ...
;         for (int a = 0; a < 2; ++a)
; #pragma unroll
;             for (int b = 0; b < 2; ++b)
; #pragma unroll
;                 for (int m = 0; m < 4; ++m)
; #pragma unroll
;                     for (int n = 0; n < 2; ++n) acc[a][b][m][n] = (f32x4){0.f, 0.f, 0.f, 0.f};
;         cur = nxt; cA = nA; cB = nB; cAr = nAr; cHb = nHb; ++ui;
.LBB0_946:
	s_add_u32 s22, s36, 0x80
	v_mov_b32_e32 v0, 0
	s_addc_u32 s27, s37, 0
	s_mov_b32 s14, 0
	s_mov_b64 s[44:45], -1
	s_mov_b64 s[40:41], 0
	v_mov_b32_e32 v1, v0
	v_pk_mov_b32 v[2:3], v[0:1], v[0:1]
	v_pk_mov_b32 v[4:5], v[0:1], v[0:1]
	v_pk_mov_b32 v[6:7], v[0:1], v[0:1]
	v_pk_mov_b32 v[8:9], v[0:1], v[0:1]
	v_pk_mov_b32 v[10:11], v[0:1], v[0:1]
	v_pk_mov_b32 v[12:13], v[0:1], v[0:1]
	v_pk_mov_b32 v[14:15], v[0:1], v[0:1]
	v_pk_mov_b32 v[16:17], v[0:1], v[0:1]
	v_pk_mov_b32 v[18:19], v[0:1], v[0:1]
	v_pk_mov_b32 v[20:21], v[0:1], v[0:1]
	v_pk_mov_b32 v[22:23], v[0:1], v[0:1]
	v_pk_mov_b32 v[24:25], v[0:1], v[0:1]
	v_pk_mov_b32 v[26:27], v[0:1], v[0:1]
	v_pk_mov_b32 v[28:29], v[0:1], v[0:1]
	v_pk_mov_b32 v[30:31], v[0:1], v[0:1]
	v_pk_mov_b32 v[32:33], v[0:1], v[0:1]
	v_pk_mov_b32 v[34:35], v[0:1], v[0:1]
	v_pk_mov_b32 v[36:37], v[0:1], v[0:1]
	v_pk_mov_b32 v[38:39], v[0:1], v[0:1]
	v_pk_mov_b32 v[40:41], v[0:1], v[0:1]
	v_pk_mov_b32 v[42:43], v[0:1], v[0:1]
	v_pk_mov_b32 v[44:45], v[0:1], v[0:1]
	v_pk_mov_b32 v[46:47], v[0:1], v[0:1]
	v_pk_mov_b32 v[48:49], v[0:1], v[0:1]
	v_pk_mov_b32 v[50:51], v[0:1], v[0:1]
	v_pk_mov_b32 v[52:53], v[0:1], v[0:1]
	v_pk_mov_b32 v[54:55], v[0:1], v[0:1]
	v_pk_mov_b32 v[56:57], v[0:1], v[0:1]
	v_pk_mov_b32 v[58:59], v[0:1], v[0:1]
	v_pk_mov_b32 v[60:61], v[0:1], v[0:1]
	v_pk_mov_b32 v[62:63], v[0:1], v[0:1]
	v_pk_mov_b32 v[64:65], v[0:1], v[0:1]
	v_pk_mov_b32 v[66:67], v[0:1], v[0:1]
	v_pk_mov_b32 v[68:69], v[0:1], v[0:1]
	v_pk_mov_b32 v[70:71], v[0:1], v[0:1]
	v_pk_mov_b32 v[72:73], v[0:1], v[0:1]
	v_pk_mov_b32 v[74:75], v[0:1], v[0:1]
	v_pk_mov_b32 v[76:77], v[0:1], v[0:1]
	v_pk_mov_b32 v[78:79], v[0:1], v[0:1]
	v_pk_mov_b32 v[80:81], v[0:1], v[0:1]
	v_pk_mov_b32 v[82:83], v[0:1], v[0:1]
	v_pk_mov_b32 v[84:85], v[0:1], v[0:1]
	v_pk_mov_b32 v[86:87], v[0:1], v[0:1]
	v_pk_mov_b32 v[88:89], v[0:1], v[0:1]
	v_pk_mov_b32 v[90:91], v[0:1], v[0:1]
	v_pk_mov_b32 v[92:93], v[0:1], v[0:1]
	v_pk_mov_b32 v[94:95], v[0:1], v[0:1]
	v_pk_mov_b32 v[96:97], v[0:1], v[0:1]
	v_pk_mov_b32 v[98:99], v[0:1], v[0:1]
	v_pk_mov_b32 v[100:101], v[0:1], v[0:1]
	v_pk_mov_b32 v[102:103], v[0:1], v[0:1]
	v_pk_mov_b32 v[104:105], v[0:1], v[0:1]
	v_pk_mov_b32 v[106:107], v[0:1], v[0:1]
	v_pk_mov_b32 v[108:109], v[0:1], v[0:1]
	v_pk_mov_b32 v[110:111], v[0:1], v[0:1]
	v_pk_mov_b32 v[112:113], v[0:1], v[0:1]
	v_pk_mov_b32 v[114:115], v[0:1], v[0:1]
	v_pk_mov_b32 v[116:117], v[0:1], v[0:1]
	v_pk_mov_b32 v[118:119], v[0:1], v[0:1]
	v_pk_mov_b32 v[120:121], v[0:1], v[0:1]
	v_pk_mov_b32 v[122:123], v[0:1], v[0:1]
	v_pk_mov_b32 v[124:125], v[0:1], v[0:1]
	v_pk_mov_b32 v[126:127], v[0:1], v[0:1]

;     ...
;         for (int a = 0; a < 2; ++a)
; #pragma unroll
;             for (int b = 0; b < 2; ++b)
; #pragma unroll
;                 for (int m = 0; m < 4; ++m)
; #pragma unroll
;                     for (int n = 0; n < 2; ++n) acc[a][b][m][n] = (f32x4){0.f, 0.f, 0.f, 0.f};
;         cur = nxt; cA = nA; cB = nB; cAr = nAr; cHb = nHb; ++ui;
.LBB0_1039:
	s_add_u32 s40, s66, 0x80
	v_mov_b32_e32 v0, 0
	s_addc_u32 s41, s67, 0
	s_mov_b32 s78, 0
	v_mov_b32_e32 v1, v0
	v_pk_mov_b32 v[2:3], v[0:1], v[0:1]
	v_pk_mov_b32 v[4:5], v[0:1], v[0:1]
	v_pk_mov_b32 v[6:7], v[0:1], v[0:1]
	v_pk_mov_b32 v[8:9], v[0:1], v[0:1]
	v_pk_mov_b32 v[10:11], v[0:1], v[0:1]
	v_pk_mov_b32 v[12:13], v[0:1], v[0:1]
	v_pk_mov_b32 v[14:15], v[0:1], v[0:1]
	v_pk_mov_b32 v[16:17], v[0:1], v[0:1]
	v_pk_mov_b32 v[18:19], v[0:1], v[0:1]
	v_pk_mov_b32 v[20:21], v[0:1], v[0:1]
	v_pk_mov_b32 v[22:23], v[0:1], v[0:1]
	v_pk_mov_b32 v[24:25], v[0:1], v[0:1]
	v_pk_mov_b32 v[26:27], v[0:1], v[0:1]
	v_pk_mov_b32 v[28:29], v[0:1], v[0:1]
	v_pk_mov_b32 v[30:31], v[0:1], v[0:1]
	v_pk_mov_b32 v[32:33], v[0:1], v[0:1]
	v_pk_mov_b32 v[34:35], v[0:1], v[0:1]
	v_pk_mov_b32 v[36:37], v[0:1], v[0:1]
	v_pk_mov_b32 v[38:39], v[0:1], v[0:1]
	v_pk_mov_b32 v[40:41], v[0:1], v[0:1]
	v_pk_mov_b32 v[42:43], v[0:1], v[0:1]
	v_pk_mov_b32 v[44:45], v[0:1], v[0:1]
	v_pk_mov_b32 v[46:47], v[0:1], v[0:1]
	v_pk_mov_b32 v[48:49], v[0:1], v[0:1]
	v_pk_mov_b32 v[50:51], v[0:1], v[0:1]
	v_pk_mov_b32 v[52:53], v[0:1], v[0:1]
	v_pk_mov_b32 v[54:55], v[0:1], v[0:1]
	v_pk_mov_b32 v[56:57], v[0:1], v[0:1]
	v_pk_mov_b32 v[58:59], v[0:1], v[0:1]
	v_pk_mov_b32 v[60:61], v[0:1], v[0:1]
	v_pk_mov_b32 v[62:63], v[0:1], v[0:1]
	v_pk_mov_b32 v[64:65], v[0:1], v[0:1]
	v_pk_mov_b32 v[66:67], v[0:1], v[0:1]
	v_pk_mov_b32 v[68:69], v[0:1], v[0:1]
	v_pk_mov_b32 v[70:71], v[0:1], v[0:1]
	v_pk_mov_b32 v[72:73], v[0:1], v[0:1]
	v_pk_mov_b32 v[74:75], v[0:1], v[0:1]
	v_pk_mov_b32 v[76:77], v[0:1], v[0:1]
	v_pk_mov_b32 v[78:79], v[0:1], v[0:1]
	v_pk_mov_b32 v[80:81], v[0:1], v[0:1]
	v_pk_mov_b32 v[82:83], v[0:1], v[0:1]
	v_pk_mov_b32 v[84:85], v[0:1], v[0:1]
	v_pk_mov_b32 v[86:87], v[0:1], v[0:1]
	v_pk_mov_b32 v[88:89], v[0:1], v[0:1]
	v_pk_mov_b32 v[90:91], v[0:1], v[0:1]
	v_pk_mov_b32 v[92:93], v[0:1], v[0:1]
	v_pk_mov_b32 v[94:95], v[0:1], v[0:1]
	v_pk_mov_b32 v[96:97], v[0:1], v[0:1]
	v_pk_mov_b32 v[98:99], v[0:1], v[0:1]
	v_pk_mov_b32 v[100:101], v[0:1], v[0:1]
	v_pk_mov_b32 v[102:103], v[0:1], v[0:1]
	v_pk_mov_b32 v[104:105], v[0:1], v[0:1]
	v_pk_mov_b32 v[106:107], v[0:1], v[0:1]
	v_pk_mov_b32 v[108:109], v[0:1], v[0:1]
	v_pk_mov_b32 v[110:111], v[0:1], v[0:1]
	v_pk_mov_b32 v[112:113], v[0:1], v[0:1]
	v_pk_mov_b32 v[114:115], v[0:1], v[0:1]
	v_pk_mov_b32 v[116:117], v[0:1], v[0:1]
	v_pk_mov_b32 v[118:119], v[0:1], v[0:1]
	v_pk_mov_b32 v[120:121], v[0:1], v[0:1]
	v_pk_mov_b32 v[122:123], v[0:1], v[0:1]
	v_pk_mov_b32 v[124:125], v[0:1], v[0:1]
	v_pk_mov_b32 v[126:127], v[0:1], v[0:1]
	s_branch .LBB0_1041

; #define PG8_STAGE(bufoff, gbase, voff) do { _Pragma("unroll") for (int _i = 0; _i < 2; ++_i) \
;         __builtin_amdgcn_global_load_lds((const unsigned*)((const char*)(gbase) + (voff)[_i]), (LAS unsigned*)(lds + (bufoff) + ldsw + _i * 8192), 16, 0, 0); } while (0)
; #define PG8_STAGE_A(bufoff, ptr, half, rev) do { if (REVA && (rev)) { const char* _p = (ptr) - ((half) ? hstepA : 0); PG8_STAGE(bufoff, _p, voffAr); } else { const char* _p = (ptr) + ((half) ? hstepA : 0); PG8_STAGE(bufoff, _p, voffA); } } while (0)
; #define PG8_LDA(dst, b, h) do { _Pragma("unroll") for (int m = 0; m < 4; ++m) _Pragma("unroll") for (int k = 0; k < 2; ++k) dst[m][k] = *(const LAS bf16x8*)(lds + PG8_SA(b, h) + aoff + m * 2048 + k * 1024); } while (0)
; #define PG8_WAIT_L(n) asm volatile("s_waitcnt lgkmcnt(" #n ")" ::: "memory")
; #define PG8_BAR __builtin_amdgcn_s_barrier()
;     ...
;     for (;;) {
;         const bool has_next = next_unit(ui + 1, nM, nN, MP, nxt, rot);
;         const char* nA = has_next ? nxt.a : cA; const char* nB = has_next ? nxt.b : cB; const char* nAr = has_next ? nxt.ar : cAr; const size_t nHb = has_next ? nxt.hb : cHb;
;         for (int t = 0; t < nt; t += 2) {
;             const bool last = (t == nt - 2);
;             const char* a1 = PG8_APTR(cA, cAr, t + 1); const bool r1 = REVA && ((t + 1) & 4);
;             const char* a2 = last ? nA : PG8_APTR(cA, cAr, t + 2); const bool r2 = REVA && !last && ((t + 2) & 4);
;             const char* a3 = last ? nA + kstep : PG8_APTR(cA, cAr, t + 3); const bool r3 = REVA && !last && ((t + 3) & 4);
;             const char* b2 = last ? nB : cB + (size_t)(t + 2) * kstep; const char* b3 = b2 + kstep; const size_t hb2 = last ? nHb : cHb;
;             PG8_LDB(B0, 0, 0); PG8_SCHED; PG8_LDA(At, 0, 0); PG8_STAGE_A(PG8_SA(1, 1), a1, 1, r1);
;             PG8_WAIT_L(8); PG8_BAR; PG8_WAIT_L(0); PG8_MMA(0, 0, At, B0); PG8_BAR; PG8_SCHED;
;             PG8_LDB(B1, 0, 1); PG8_STAGE(PG8_SB(0, 0), b2, voffB);
;             PG8_BAR; PG8_WAIT_L(0); PG8_MMA(0, 1, At, B1); PG8_BAR;
;     ...
;         for (int a = 0; a < 2; ++a)
; #pragma unroll
;             for (int b = 0; b < 2; ++b)
; #pragma unroll
;                 for (int m = 0; m < 4; ++m)
; #pragma unroll
;                     for (int n = 0; n < 2; ++n) acc[a][b][m][n] = (f32x4){0.f, 0.f, 0.f, 0.f};
;         cur = nxt; cA = nA; cB = nB; cAr = nAr; cHb = nHb; ++ui;
.LBB0_1131:
	s_add_u32 s6, s78, 0x80
	s_addc_u32 s7, s79, 0
	s_add_u32 s8, s0, 0x80080
	s_addc_u32 s9, s1, 0
	v_lshl_add_u64 v[96:97], s[8:9], 0, v[176:177]
	v_lshl_add_u64 v[98:99], s[8:9], 0, v[178:179]
	s_add_u32 s8, s2, 0x100
	v_mov_b32_e32 v0, 0
	s_addc_u32 s9, s3, 0
	s_mov_b32 s26, -2
	s_mov_b64 s[2:3], 0
	v_mov_b32_e32 v1, v0
	v_pk_mov_b32 v[2:3], v[0:1], v[0:1]
	v_pk_mov_b32 v[4:5], v[0:1], v[0:1]
	v_pk_mov_b32 v[6:7], v[0:1], v[0:1]
	v_pk_mov_b32 v[8:9], v[0:1], v[0:1]
	v_pk_mov_b32 v[10:11], v[0:1], v[0:1]
	v_pk_mov_b32 v[12:13], v[0:1], v[0:1]
	v_pk_mov_b32 v[14:15], v[0:1], v[0:1]
	v_pk_mov_b32 v[16:17], v[0:1], v[0:1]
	v_pk_mov_b32 v[18:19], v[0:1], v[0:1]
	v_pk_mov_b32 v[20:21], v[0:1], v[0:1]
	v_pk_mov_b32 v[22:23], v[0:1], v[0:1]
	v_pk_mov_b32 v[24:25], v[0:1], v[0:1]
	v_pk_mov_b32 v[26:27], v[0:1], v[0:1]
	v_pk_mov_b32 v[28:29], v[0:1], v[0:1]
	v_pk_mov_b32 v[30:31], v[0:1], v[0:1]
	v_pk_mov_b32 v[32:33], v[0:1], v[0:1]
	v_pk_mov_b32 v[34:35], v[0:1], v[0:1]
	v_pk_mov_b32 v[36:37], v[0:1], v[0:1]
	v_pk_mov_b32 v[38:39], v[0:1], v[0:1]
	v_pk_mov_b32 v[40:41], v[0:1], v[0:1]
	v_pk_mov_b32 v[42:43], v[0:1], v[0:1]
	v_pk_mov_b32 v[44:45], v[0:1], v[0:1]
	v_pk_mov_b32 v[46:47], v[0:1], v[0:1]
	v_pk_mov_b32 v[48:49], v[0:1], v[0:1]
	v_pk_mov_b32 v[50:51], v[0:1], v[0:1]
	v_pk_mov_b32 v[52:53], v[0:1], v[0:1]
	v_pk_mov_b32 v[54:55], v[0:1], v[0:1]
	v_pk_mov_b32 v[56:57], v[0:1], v[0:1]
	v_pk_mov_b32 v[58:59], v[0:1], v[0:1]
	v_pk_mov_b32 v[60:61], v[0:1], v[0:1]
	v_pk_mov_b32 v[62:63], v[0:1], v[0:1]
	v_pk_mov_b32 v[64:65], v[0:1], v[0:1]
	v_pk_mov_b32 v[66:67], v[0:1], v[0:1]
	v_pk_mov_b32 v[68:69], v[0:1], v[0:1]
	v_pk_mov_b32 v[70:71], v[0:1], v[0:1]
	v_pk_mov_b32 v[72:73], v[0:1], v[0:1]
	v_pk_mov_b32 v[74:75], v[0:1], v[0:1]
	v_pk_mov_b32 v[76:77], v[0:1], v[0:1]
	v_pk_mov_b32 v[78:79], v[0:1], v[0:1]
	v_pk_mov_b32 v[80:81], v[0:1], v[0:1]
	v_pk_mov_b32 v[82:83], v[0:1], v[0:1]
	v_pk_mov_b32 v[84:85], v[0:1], v[0:1]
	v_pk_mov_b32 v[86:87], v[0:1], v[0:1]
	v_pk_mov_b32 v[88:89], v[0:1], v[0:1]
	v_pk_mov_b32 v[90:91], v[0:1], v[0:1]
	v_pk_mov_b32 v[92:93], v[0:1], v[0:1]
	v_pk_mov_b32 v[94:95], v[0:1], v[0:1]
	v_pk_mov_b32 v[100:101], v[0:1], v[0:1]
	v_pk_mov_b32 v[102:103], v[0:1], v[0:1]
	v_pk_mov_b32 v[104:105], v[0:1], v[0:1]
	v_pk_mov_b32 v[106:107], v[0:1], v[0:1]
	v_pk_mov_b32 v[112:113], v[0:1], v[0:1]
	v_pk_mov_b32 v[114:115], v[0:1], v[0:1]
	v_pk_mov_b32 v[116:117], v[0:1], v[0:1]
	v_pk_mov_b32 v[118:119], v[0:1], v[0:1]
	v_pk_mov_b32 v[124:125], v[0:1], v[0:1]
	v_pk_mov_b32 v[126:127], v[0:1], v[0:1]
	v_pk_mov_b32 v[128:129], v[0:1], v[0:1]
	v_pk_mov_b32 v[130:131], v[0:1], v[0:1]
	v_pk_mov_b32 v[136:137], v[0:1], v[0:1]
	v_pk_mov_b32 v[138:139], v[0:1], v[0:1]
	v_pk_mov_b32 v[144:145], v[0:1], v[0:1]
	v_pk_mov_b32 v[146:147], v[0:1], v[0:1]
	v_add_u32_e32 v140, 0x10000, v205
	ds_read_b128 v[108:111], v140
	ds_read_b128 v[120:123], v140 offset:1024
	ds_read_b128 v[132:135], v140 offset:2048
	ds_read_b128 v[140:143], v140 offset:3072
.LBB0_1132:
	s_add_u32 s10, s0, s2
	s_addc_u32 s11, s1, s3
	s_add_u32 s16, s10, 0x100
	s_addc_u32 s17, s11, 0
	s_add_u32 s10, s10, 0x180
	s_addc_u32 s11, s11, 0
	s_add_u32 s14, s8, s2
	s_addc_u32 s15, s9, s3
	s_add_i32 s27, 0, 0x10000
	s_cmpk_eq_i32 s2, 0xf00
	s_cselect_b32 s15, s25, s15
	s_cselect_b32 s14, s24, s14
	s_cselect_b32 s21, s79, s17
	s_cselect_b32 s20, s78, s16
	s_cselect_b32 s17, s7, s11
	s_cselect_b32 s16, s6, s10
	v_lshl_add_u64 v[184:185], v[96:97], 0, s[2:3]
	s_add_i32 m0, s70, 0xc000
	ds_read_b128 v[148:151], v209
	ds_read_b128 v[152:155], v209 offset:1024
	ds_read_b128 v[156:159], v209 offset:2048
	ds_read_b128 v[180:183], v209 offset:3072
	ds_read_b128 v[210:213], v209 offset:4096
	ds_read_b128 v[214:217], v209 offset:5120
	ds_read_b128 v[218:221], v209 offset:6144
	ds_read_b128 v[222:225], v209 offset:7168
	global_load_lds_dwordx4 v[184:185], off
	v_lshl_add_u64 v[184:185], v[98:99], 0, s[2:3]
	s_add_i32 m0, s70, 0xe000
	s_nop 0
	global_load_lds_dwordx4 v[184:185], off
	s_waitcnt lgkmcnt(8)
	s_waitcnt vmcnt(10)
	s_barrier
	s_waitcnt lgkmcnt(0)
	v_mfma_f32_16x16x32_bf16 v[144:147], v[108:111], v[148:151], v[144:147]
	v_mfma_f32_16x16x32_bf16 v[136:139], v[132:135], v[148:151], v[136:139]
	v_mfma_f32_16x16x32_bf16 v[116:119], v[108:111], v[156:159], v[116:119]
	v_mfma_f32_16x16x32_bf16 v[112:115], v[132:135], v[156:159], v[112:115]
	v_mfma_f32_16x16x32_bf16 v[92:95], v[108:111], v[210:213], v[92:95]
	v_mfma_f32_16x16x32_bf16 v[88:91], v[132:135], v[210:213], v[88:91]
	v_mfma_f32_16x16x32_bf16 v[76:79], v[108:111], v[218:221], v[76:79]
	v_mfma_f32_16x16x32_bf16 v[72:75], v[132:135], v[218:221], v[72:75]
	v_mfma_f32_16x16x32_bf16 v[144:147], v[120:123], v[152:155], v[144:147]
	v_mfma_f32_16x16x32_bf16 v[136:139], v[140:143], v[152:155], v[136:139]
	v_mfma_f32_16x16x32_bf16 v[116:119], v[120:123], v[180:183], v[116:119]
	v_mfma_f32_16x16x32_bf16 v[112:115], v[140:143], v[180:183], v[112:115]
	v_mfma_f32_16x16x32_bf16 v[92:95], v[120:123], v[214:217], v[92:95]
	v_mfma_f32_16x16x32_bf16 v[88:91], v[140:143], v[214:217], v[88:91]
	v_mfma_f32_16x16x32_bf16 v[76:79], v[120:123], v[222:225], v[76:79]
	v_mfma_f32_16x16x32_bf16 v[72:75], v[140:143], v[222:225], v[72:75]
	s_barrier
	s_add_i32 s10, 0, 0x14000
	v_add_u32_e32 v184, s10, v205
	s_add_i32 s11, s27, s69
	ds_read_b128 v[226:229], v184
	ds_read_b128 v[230:233], v184 offset:1024
	ds_read_b128 v[234:237], v184 offset:2048
	ds_read_b128 v[238:241], v184 offset:3072
	v_lshl_add_u64 v[184:185], s[14:15], 0, v[172:173]
	s_mov_b32 m0, s11
	v_lshl_add_u64 v[190:191], s[14:15], 0, v[168:169]
	global_load_lds_dwordx4 v[184:185], off
	s_add_i32 m0, s11, 0x2000
	s_nop 0
	global_load_lds_dwordx4 v[190:191], off
	s_waitcnt vmcnt(10)
	s_barrier
; #define PG8_STAGE(bufoff, gbase, voff) do { _Pragma("unroll") for (int _i = 0; _i < 2; ++_i) \
;         __builtin_amdgcn_global_load_lds((const unsigned*)((const char*)(gbase) + (voff)[_i]), (LAS unsigned*)(lds + (bufoff) + ldsw + _i * 8192), 16, 0, 0); } while (0)
; #define PG8_STAGE_A(bufoff, ptr, half, rev) do { if (REVA && (rev)) { const char* _p = (ptr) - ((half) ? hstepA : 0); PG8_STAGE(bufoff, _p, voffAr); } else { const char* _p = (ptr) + ((half) ? hstepA : 0); PG8_STAGE(bufoff, _p, voffA); } } while (0)
; #define PG8_LDA(dst, b, h) do { _Pragma("unroll") for (int m = 0; m < 4; ++m) _Pragma("unroll") for (int k = 0; k < 2; ++k) dst[m][k] = *(const LAS bf16x8*)(lds + PG8_SA(b, h) + aoff + m * 2048 + k * 1024); } while (0)
; #define PG8_LDB(dst, b, h) do { _Pragma("unroll") for (int n = 0; n < 2; ++n) _Pragma("unroll") for (int k = 0; k < 2; ++k) dst[n][k] = *(const LAS bf16x8*)(lds + PG8_SB(b, h) + boff + n * 2048 + k * 1024); } while (0)
; #define PG8_MMA(ai, bj, At, Bt) do { __builtin_amdgcn_s_setprio(1); _Pragma("unroll") for (int m = 0; m < 4; ++m) _Pragma("unroll") for (int n = 0; n < 2; ++n) _Pragma("unroll") for (int k = 0; k < 2; ++k) \
;         acc[ai][bj][m][n] = __builtin_amdgcn_mfma_f32_16x16x32_bf16(Bt[n][k], At[m][k], acc[ai][bj][m][n], 0, 0, 0); __builtin_amdgcn_s_setprio(0); } while (0)
; #define PG8_WAIT_V(n) asm volatile("s_waitcnt vmcnt(" #n ")" ::: "memory")
; #define PG8_WAIT_L(n) asm volatile("s_waitcnt lgkmcnt(" #n ")" ::: "memory")
; #define PG8_BAR __builtin_amdgcn_s_barrier()
; #define PG8_SCHED __builtin_amdgcn_sched_barrier(0)
;     ...
;             PG8_BAR; PG8_WAIT_L(0); PG8_MMA(0, 1, At, B1); PG8_BAR;
;             PG8_LDA(At, 0, 1); PG8_STAGE_A(PG8_SA(0, 0), a2, 0, r2);
;             PG8_BAR; PG8_WAIT_L(0); PG8_MMA(1, 0, At, B0); PG8_BAR; PG8_SCHED;
;             PG8_STAGE(PG8_SB(0, 1), b2 + hb2, voffB);
;             PG8_WAIT_V(6); PG8_BAR; PG8_MMA(1, 1, At, B1); PG8_BAR;
;             PG8_LDB(B0, 1, 0); PG8_SCHED; PG8_LDA(At, 1, 0); PG8_STAGE_A(PG8_SA(0, 1), a2, 1, r2);
;             PG8_WAIT_L(8); PG8_BAR; PG8_WAIT_L(0); PG8_MMA(0, 0, At, B0); PG8_BAR; PG8_SCHED;
;             PG8_LDB(B1, 1, 1); PG8_STAGE(PG8_SB(1, 0), b3, voffB);
;             PG8_BAR; PG8_WAIT_L(0); PG8_MMA(0, 1, At, B1); PG8_BAR;
	s_waitcnt lgkmcnt(0)
	v_mfma_f32_16x16x32_bf16 v[128:131], v[226:229], v[148:151], v[128:131]
	v_mfma_f32_16x16x32_bf16 v[124:127], v[234:237], v[148:151], v[124:127]
	v_mfma_f32_16x16x32_bf16 v[104:107], v[226:229], v[156:159], v[104:107]
	v_mfma_f32_16x16x32_bf16 v[100:103], v[234:237], v[156:159], v[100:103]
	v_mfma_f32_16x16x32_bf16 v[84:87], v[226:229], v[210:213], v[84:87]
	v_mfma_f32_16x16x32_bf16 v[80:83], v[234:237], v[210:213], v[80:83]
	v_mfma_f32_16x16x32_bf16 v[68:71], v[226:229], v[218:221], v[68:71]
	v_mfma_f32_16x16x32_bf16 v[64:67], v[234:237], v[218:221], v[64:67]
	v_mfma_f32_16x16x32_bf16 v[128:131], v[230:233], v[152:155], v[128:131]
	v_mfma_f32_16x16x32_bf16 v[124:127], v[238:241], v[152:155], v[124:127]
	v_mfma_f32_16x16x32_bf16 v[104:107], v[230:233], v[180:183], v[104:107]
	v_mfma_f32_16x16x32_bf16 v[100:103], v[238:241], v[180:183], v[100:103]
	v_mfma_f32_16x16x32_bf16 v[84:87], v[230:233], v[214:217], v[84:87]
	v_mfma_f32_16x16x32_bf16 v[80:83], v[238:241], v[214:217], v[80:83]
	v_mfma_f32_16x16x32_bf16 v[68:71], v[230:233], v[222:225], v[68:71]
	v_mfma_f32_16x16x32_bf16 v[64:67], v[238:241], v[222:225], v[64:67]
	s_mov_b32 m0, s70
	v_lshl_add_u64 v[242:243], s[20:21], 0, v[174:175]
	s_barrier
	ds_read_b128 v[148:151], v209 offset:16384
	ds_read_b128 v[152:155], v209 offset:17408
	ds_read_b128 v[156:159], v209 offset:18432
	ds_read_b128 v[180:183], v209 offset:19456
	ds_read_b128 v[210:213], v209 offset:20480
	ds_read_b128 v[214:217], v209 offset:21504
	ds_read_b128 v[218:221], v209 offset:22528
	ds_read_b128 v[222:225], v209 offset:23552
	global_load_lds_dwordx4 v[242:243], off
	v_lshl_add_u64 v[242:243], s[20:21], 0, v[170:171]
	s_mov_b32 m0, s71
	s_nop 0
	global_load_lds_dwordx4 v[242:243], off
	s_waitcnt vmcnt(10)
	s_barrier
	s_waitcnt lgkmcnt(0)
	v_mfma_f32_16x16x32_bf16 v[60:63], v[108:111], v[148:151], v[60:63]
	v_mfma_f32_16x16x32_bf16 v[56:59], v[132:135], v[148:151], v[56:59]
	v_mfma_f32_16x16x32_bf16 v[44:47], v[108:111], v[156:159], v[44:47]
	v_mfma_f32_16x16x32_bf16 v[40:43], v[132:135], v[156:159], v[40:43]
	v_mfma_f32_16x16x32_bf16 v[28:31], v[108:111], v[210:213], v[28:31]
	v_mfma_f32_16x16x32_bf16 v[24:27], v[132:135], v[210:213], v[24:27]
	v_mfma_f32_16x16x32_bf16 v[12:15], v[108:111], v[218:221], v[12:15]
	v_mfma_f32_16x16x32_bf16 v[8:11], v[132:135], v[218:221], v[8:11]
	v_mfma_f32_16x16x32_bf16 v[60:63], v[120:123], v[152:155], v[60:63]
	v_mfma_f32_16x16x32_bf16 v[56:59], v[140:143], v[152:155], v[56:59]
	v_mfma_f32_16x16x32_bf16 v[44:47], v[120:123], v[180:183], v[44:47]
	v_mfma_f32_16x16x32_bf16 v[40:43], v[140:143], v[180:183], v[40:43]
	v_mfma_f32_16x16x32_bf16 v[28:31], v[120:123], v[214:217], v[28:31]
	v_mfma_f32_16x16x32_bf16 v[24:27], v[140:143], v[214:217], v[24:27]
	v_mfma_f32_16x16x32_bf16 v[12:15], v[120:123], v[222:225], v[12:15]
	v_mfma_f32_16x16x32_bf16 v[8:11], v[140:143], v[222:225], v[8:11]
	s_barrier
	s_add_u32 s36, s14, 0x80000
	s_addc_u32 s37, s15, 0
	s_add_i32 s10, s10, s69
	v_lshl_add_u64 v[108:109], s[36:37], 0, v[172:173]
	s_mov_b32 m0, s10
	s_nop 0
	global_load_lds_dwordx4 v[108:109], off
	v_lshl_add_u64 v[108:109], s[36:37], 0, v[168:169]
	s_add_i32 m0, s10, 0x2000
	s_nop 0
	global_load_lds_dwordx4 v[108:109], off
	v_add_u32_e32 v140, 0x18000, v205
	ds_read_b128 v[108:111], v140
	ds_read_b128 v[120:123], v140 offset:1024
	ds_read_b128 v[132:135], v140 offset:2048
	ds_read_b128 v[140:143], v140 offset:3072
	s_waitcnt vmcnt(10)
	s_barrier
	v_mfma_f32_16x16x32_bf16 v[52:55], v[226:229], v[148:151], v[52:55]
	v_mfma_f32_16x16x32_bf16 v[48:51], v[234:237], v[148:151], v[48:51]
	v_mfma_f32_16x16x32_bf16 v[36:39], v[226:229], v[156:159], v[36:39]
	v_mfma_f32_16x16x32_bf16 v[32:35], v[234:237], v[156:159], v[32:35]
	v_mfma_f32_16x16x32_bf16 v[20:23], v[226:229], v[210:213], v[20:23]
	v_mfma_f32_16x16x32_bf16 v[16:19], v[234:237], v[210:213], v[16:19]
	v_mfma_f32_16x16x32_bf16 v[4:7], v[226:229], v[218:221], v[4:7]
	v_mfma_f32_16x16x32_bf16 v[0:3], v[234:237], v[218:221], v[0:3]
	v_mfma_f32_16x16x32_bf16 v[52:55], v[230:233], v[152:155], v[52:55]
	v_mfma_f32_16x16x32_bf16 v[48:51], v[238:241], v[152:155], v[48:51]
	v_mfma_f32_16x16x32_bf16 v[36:39], v[230:233], v[180:183], v[36:39]
	v_mfma_f32_16x16x32_bf16 v[32:35], v[238:241], v[180:183], v[32:35]
	v_mfma_f32_16x16x32_bf16 v[20:23], v[230:233], v[214:217], v[20:23]
	v_mfma_f32_16x16x32_bf16 v[16:19], v[238:241], v[214:217], v[16:19]
	v_mfma_f32_16x16x32_bf16 v[4:7], v[230:233], v[222:225], v[4:7]
	v_mfma_f32_16x16x32_bf16 v[0:3], v[238:241], v[222:225], v[0:3]
	s_add_i32 s10, 0, 0x18000
	s_barrier
	s_add_u32 s20, s20, 0x80000
	s_addc_u32 s21, s21, 0
	s_mov_b32 m0, s89
	v_lshl_add_u64 v[226:227], s[20:21], 0, v[174:175]
	ds_read_b128 v[148:151], v209 offset:32768
	ds_read_b128 v[152:155], v209 offset:33792
	ds_read_b128 v[156:159], v209 offset:34816
	ds_read_b128 v[180:183], v209 offset:35840
	ds_read_b128 v[210:213], v209 offset:36864
	ds_read_b128 v[214:217], v209 offset:37888
	ds_read_b128 v[218:221], v209 offset:38912
	ds_read_b128 v[222:225], v209 offset:39936
	global_load_lds_dwordx4 v[226:227], off
	v_lshl_add_u64 v[226:227], s[20:21], 0, v[170:171]
	s_mov_b32 m0, s90
	s_nop 0
	global_load_lds_dwordx4 v[226:227], off
	s_waitcnt lgkmcnt(8)
	s_waitcnt vmcnt(10)
	s_barrier
; #define PG8_STAGE(bufoff, gbase, voff) do { _Pragma("unroll") for (int _i = 0; _i < 2; ++_i) \
;         __builtin_amdgcn_global_load_lds((const unsigned*)((const char*)(gbase) + (voff)[_i]), (LAS unsigned*)(lds + (bufoff) + ldsw + _i * 8192), 16, 0, 0); } while (0)
; #define PG8_STAGE_A(bufoff, ptr, half, rev) do { if (REVA && (rev)) { const char* _p = (ptr) - ((half) ? hstepA : 0); PG8_STAGE(bufoff, _p, voffAr); } else { const char* _p = (ptr) + ((half) ? hstepA : 0); PG8_STAGE(bufoff, _p, voffA); } } while (0)
; #define PG8_LDA(dst, b, h) do { _Pragma("unroll") for (int m = 0; m < 4; ++m) _Pragma("unroll") for (int k = 0; k < 2; ++k) dst[m][k] = *(const LAS bf16x8*)(lds + PG8_SA(b, h) + aoff + m * 2048 + k * 1024); } while (0)
; #define PG8_LDB(dst, b, h) do { _Pragma("unroll") for (int n = 0; n < 2; ++n) _Pragma("unroll") for (int k = 0; k < 2; ++k) dst[n][k] = *(const LAS bf16x8*)(lds + PG8_SB(b, h) + boff + n * 2048 + k * 1024); } while (0)
; #define PG8_MMA(ai, bj, At, Bt) do { __builtin_amdgcn_s_setprio(1); _Pragma("unroll") for (int m = 0; m < 4; ++m) _Pragma("unroll") for (int n = 0; n < 2; ++n) _Pragma("unroll") for (int k = 0; k < 2; ++k) \
;         acc[ai][bj][m][n] = __builtin_amdgcn_mfma_f32_16x16x32_bf16(Bt[n][k], At[m][k], acc[ai][bj][m][n], 0, 0, 0); __builtin_amdgcn_s_setprio(0); } while (0)
; #define PG8_WAIT_L(n) asm volatile("s_waitcnt lgkmcnt(" #n ")" ::: "memory")
; #define PG8_BAR __builtin_amdgcn_s_barrier()
; #define PG8_SCHED __builtin_amdgcn_sched_barrier(0)
;     ...
;             PG8_LDB(B0, 1, 0); PG8_SCHED; PG8_LDA(At, 1, 0); PG8_STAGE_A(PG8_SA(0, 1), a2, 1, r2);
;             PG8_WAIT_L(8); PG8_BAR; PG8_WAIT_L(0); PG8_MMA(0, 0, At, B0); PG8_BAR; PG8_SCHED;
;             PG8_LDB(B1, 1, 1); PG8_STAGE(PG8_SB(1, 0), b3, voffB);
;             PG8_BAR; PG8_WAIT_L(0); PG8_MMA(0, 1, At, B1); PG8_BAR;
;             PG8_LDA(At, 1, 1); PG8_STAGE_A(PG8_SA(1, 0), a3, 0, r3);
;             PG8_BAR; PG8_WAIT_L(0); PG8_MMA(1, 0, At, B0); PG8_BAR; PG8_SCHED;
	s_waitcnt lgkmcnt(0)
	v_mfma_f32_16x16x32_bf16 v[144:147], v[108:111], v[148:151], v[144:147]
	v_mfma_f32_16x16x32_bf16 v[136:139], v[132:135], v[148:151], v[136:139]
	v_mfma_f32_16x16x32_bf16 v[116:119], v[108:111], v[156:159], v[116:119]
	v_mfma_f32_16x16x32_bf16 v[112:115], v[132:135], v[156:159], v[112:115]
	v_mfma_f32_16x16x32_bf16 v[92:95], v[108:111], v[210:213], v[92:95]
	v_mfma_f32_16x16x32_bf16 v[88:91], v[132:135], v[210:213], v[88:91]
	v_mfma_f32_16x16x32_bf16 v[76:79], v[108:111], v[218:221], v[76:79]
	v_mfma_f32_16x16x32_bf16 v[72:75], v[132:135], v[218:221], v[72:75]
	v_mfma_f32_16x16x32_bf16 v[144:147], v[120:123], v[152:155], v[144:147]
	v_mfma_f32_16x16x32_bf16 v[136:139], v[140:143], v[152:155], v[136:139]
	v_mfma_f32_16x16x32_bf16 v[116:119], v[120:123], v[180:183], v[116:119]
	v_mfma_f32_16x16x32_bf16 v[112:115], v[140:143], v[180:183], v[112:115]
	v_mfma_f32_16x16x32_bf16 v[92:95], v[120:123], v[214:217], v[92:95]
	v_mfma_f32_16x16x32_bf16 v[88:91], v[140:143], v[214:217], v[88:91]
	v_mfma_f32_16x16x32_bf16 v[76:79], v[120:123], v[222:225], v[76:79]
	v_mfma_f32_16x16x32_bf16 v[72:75], v[140:143], v[222:225], v[72:75]
	s_barrier
	s_add_i32 s11, 0, 0x1c000
	s_add_i32 s10, s10, s69
	v_add_u32_e32 v238, s11, v205
	v_lshl_add_u64 v[184:185], v[184:185], 0, s[28:29]
	s_mov_b32 m0, s10
	ds_read_b128 v[226:229], v238
	ds_read_b128 v[230:233], v238 offset:1024
	ds_read_b128 v[234:237], v238 offset:2048
	ds_read_b128 v[238:241], v238 offset:3072
	global_load_lds_dwordx4 v[184:185], off
	v_lshl_add_u64 v[184:185], v[190:191], 0, s[28:29]
	s_add_i32 m0, s10, 0x2000
	s_nop 0
	global_load_lds_dwordx4 v[184:185], off
	s_waitcnt vmcnt(10)
	s_barrier
	s_waitcnt lgkmcnt(0)
	v_mfma_f32_16x16x32_bf16 v[128:131], v[226:229], v[148:151], v[128:131]
	v_mfma_f32_16x16x32_bf16 v[124:127], v[234:237], v[148:151], v[124:127]
	v_mfma_f32_16x16x32_bf16 v[104:107], v[226:229], v[156:159], v[104:107]
	v_mfma_f32_16x16x32_bf16 v[100:103], v[234:237], v[156:159], v[100:103]
	v_mfma_f32_16x16x32_bf16 v[84:87], v[226:229], v[210:213], v[84:87]
	v_mfma_f32_16x16x32_bf16 v[80:83], v[234:237], v[210:213], v[80:83]
	v_mfma_f32_16x16x32_bf16 v[68:71], v[226:229], v[218:221], v[68:71]
	v_mfma_f32_16x16x32_bf16 v[64:67], v[234:237], v[218:221], v[64:67]
	v_mfma_f32_16x16x32_bf16 v[128:131], v[230:233], v[152:155], v[128:131]
	v_mfma_f32_16x16x32_bf16 v[124:127], v[238:241], v[152:155], v[124:127]
	v_mfma_f32_16x16x32_bf16 v[104:107], v[230:233], v[180:183], v[104:107]
	v_mfma_f32_16x16x32_bf16 v[100:103], v[238:241], v[180:183], v[100:103]
	v_mfma_f32_16x16x32_bf16 v[84:87], v[230:233], v[214:217], v[84:87]
	v_mfma_f32_16x16x32_bf16 v[80:83], v[238:241], v[214:217], v[80:83]
	v_mfma_f32_16x16x32_bf16 v[68:71], v[230:233], v[222:225], v[68:71]
	v_mfma_f32_16x16x32_bf16 v[64:67], v[238:241], v[222:225], v[64:67]
	s_mov_b32 m0, s97
	v_lshl_add_u64 v[184:185], s[16:17], 0, v[174:175]
	s_barrier
	ds_read_b128 v[148:151], v209 offset:49152
	ds_read_b128 v[152:155], v209 offset:50176
	ds_read_b128 v[156:159], v209 offset:51200
	ds_read_b128 v[180:183], v209 offset:52224
	ds_read_b128 v[210:213], v209 offset:53248
	ds_read_b128 v[214:217], v209 offset:54272
	ds_read_b128 v[218:221], v209 offset:55296
	ds_read_b128 v[222:225], v209 offset:56320
	global_load_lds_dwordx4 v[184:185], off
	v_lshl_add_u64 v[184:185], s[16:17], 0, v[170:171]
	s_mov_b32 m0, s52
	s_nop 0
	global_load_lds_dwordx4 v[184:185], off
	s_waitcnt vmcnt(10)
	s_barrier
; #define PG8_STAGE(bufoff, gbase, voff) do { _Pragma("unroll") for (int _i = 0; _i < 2; ++_i) \
;         __builtin_amdgcn_global_load_lds((const unsigned*)((const char*)(gbase) + (voff)[_i]), (LAS unsigned*)(lds + (bufoff) + ldsw + _i * 8192), 16, 0, 0); } while (0)
; #define PG8_MMA(ai, bj, At, Bt) do { __builtin_amdgcn_s_setprio(1); _Pragma("unroll") for (int m = 0; m < 4; ++m) _Pragma("unroll") for (int n = 0; n < 2; ++n) _Pragma("unroll") for (int k = 0; k < 2; ++k) \
;         acc[ai][bj][m][n] = __builtin_amdgcn_mfma_f32_16x16x32_bf16(Bt[n][k], At[m][k], acc[ai][bj][m][n], 0, 0, 0); __builtin_amdgcn_s_setprio(0); } while (0)
; #define PG8_WAIT_V(n) asm volatile("s_waitcnt vmcnt(" #n ")" ::: "memory")
; #define PG8_WAIT_L(n) asm volatile("s_waitcnt lgkmcnt(" #n ")" ::: "memory")
; #define PG8_BAR __builtin_amdgcn_s_barrier()
; #define PG8_SCHED __builtin_amdgcn_sched_barrier(0)
;     ...
;             PG8_BAR; PG8_WAIT_L(0); PG8_MMA(1, 0, At, B0); PG8_BAR; PG8_SCHED;
;             PG8_STAGE(PG8_SB(1, 1), b3 + hb2, voffB);
;             PG8_WAIT_V(6); PG8_BAR; PG8_MMA(1, 1, At, B1); PG8_BAR;
;         }
;         E(acc, cur, wr, wc, fr, fq, lane);
;     __device__ __forceinline__ void gates(const f32x4 (&acc)[2][2][4][2], const Unit& u, int wr, int wc, int fr, int fq) const {
;         const bool ret = u.pn < 8;
;         const bf16_t* mulp = ret ? (OFp + u.pn * BM) : (Y + (u.pn - 8) * BM);
; #pragma unroll
;         for (int ai = 0; ai < 2; ++ai) {
;             u32x4 yv[4][2]; float rs[4];
; #pragma unroll
;             for (int m = 0; m < 4; ++m) {
;                 const size_t row = (size_t)(u.pm * BM + ai * HALF + wr * 64 + m * 16 + fr);
; #pragma unroll
;                 for (int bj = 0; bj < 2; ++bj) yv[m][bj] = *(const u32x4*)(mulp + row * 2048 + bj * HALF + wc * 32 + 8 * fq);
;                 rs[m] = 1.0f;
;                 if (ret) { const f32x4 sq = *(const f32x4*)(SSp + row * 32 + u.pn * 4); rs[m] = rsqrtf((sq[0] + sq[1] + sq[2] + sq[3]) * (1.0f / 256.0f) + 1e-6f); }
	s_waitcnt lgkmcnt(0)
	v_mfma_f32_16x16x32_bf16 v[60:63], v[108:111], v[148:151], v[60:63]
	v_mfma_f32_16x16x32_bf16 v[56:59], v[132:135], v[148:151], v[56:59]
	v_mfma_f32_16x16x32_bf16 v[44:47], v[108:111], v[156:159], v[44:47]
	v_mfma_f32_16x16x32_bf16 v[40:43], v[132:135], v[156:159], v[40:43]
	v_mfma_f32_16x16x32_bf16 v[28:31], v[108:111], v[210:213], v[28:31]
	v_mfma_f32_16x16x32_bf16 v[24:27], v[132:135], v[210:213], v[24:27]
	v_mfma_f32_16x16x32_bf16 v[12:15], v[108:111], v[218:221], v[12:15]
	v_mfma_f32_16x16x32_bf16 v[8:11], v[132:135], v[218:221], v[8:11]
	v_mfma_f32_16x16x32_bf16 v[60:63], v[120:123], v[152:155], v[60:63]
	v_mfma_f32_16x16x32_bf16 v[56:59], v[140:143], v[152:155], v[56:59]
	v_mfma_f32_16x16x32_bf16 v[44:47], v[120:123], v[180:183], v[44:47]
	v_mfma_f32_16x16x32_bf16 v[40:43], v[140:143], v[180:183], v[40:43]
	v_mfma_f32_16x16x32_bf16 v[28:31], v[120:123], v[214:217], v[28:31]
	v_mfma_f32_16x16x32_bf16 v[24:27], v[140:143], v[214:217], v[24:27]
	v_mfma_f32_16x16x32_bf16 v[12:15], v[120:123], v[222:225], v[12:15]
	v_mfma_f32_16x16x32_bf16 v[8:11], v[140:143], v[222:225], v[8:11]
	s_barrier
	s_add_u32 s14, s14, 0x80080
	s_addc_u32 s15, s15, 0
	s_add_i32 s10, s11, s69
	v_lshl_add_u64 v[108:109], s[14:15], 0, v[172:173]
	s_mov_b32 m0, s10
	s_nop 0
	global_load_lds_dwordx4 v[108:109], off
	v_lshl_add_u64 v[108:109], s[14:15], 0, v[168:169]
	s_add_i32 m0, s10, 0x2000
	s_nop 0
	global_load_lds_dwordx4 v[108:109], off
	v_add_u32_e32 v140, 0x10000, v205
	ds_read_b128 v[108:111], v140
	ds_read_b128 v[120:123], v140 offset:1024
	ds_read_b128 v[132:135], v140 offset:2048
	ds_read_b128 v[140:143], v140 offset:3072
	s_waitcnt vmcnt(10)
	s_barrier
	v_mfma_f32_16x16x32_bf16 v[52:55], v[226:229], v[148:151], v[52:55]
	v_mfma_f32_16x16x32_bf16 v[48:51], v[234:237], v[148:151], v[48:51]
	v_mfma_f32_16x16x32_bf16 v[36:39], v[226:229], v[156:159], v[36:39]
	v_mfma_f32_16x16x32_bf16 v[32:35], v[234:237], v[156:159], v[32:35]
	v_mfma_f32_16x16x32_bf16 v[20:23], v[226:229], v[210:213], v[20:23]
	v_mfma_f32_16x16x32_bf16 v[16:19], v[234:237], v[210:213], v[16:19]
	v_mfma_f32_16x16x32_bf16 v[4:7], v[226:229], v[218:221], v[4:7]
	v_mfma_f32_16x16x32_bf16 v[0:3], v[234:237], v[218:221], v[0:3]
	v_mfma_f32_16x16x32_bf16 v[52:55], v[230:233], v[152:155], v[52:55]
	v_mfma_f32_16x16x32_bf16 v[48:51], v[238:241], v[152:155], v[48:51]
	v_mfma_f32_16x16x32_bf16 v[36:39], v[230:233], v[180:183], v[36:39]
	v_mfma_f32_16x16x32_bf16 v[32:35], v[238:241], v[180:183], v[32:35]
	v_mfma_f32_16x16x32_bf16 v[20:23], v[230:233], v[214:217], v[20:23]
	v_mfma_f32_16x16x32_bf16 v[16:19], v[238:241], v[214:217], v[16:19]
	v_mfma_f32_16x16x32_bf16 v[4:7], v[230:233], v[222:225], v[4:7]
	v_mfma_f32_16x16x32_bf16 v[0:3], v[238:241], v[222:225], v[0:3]
	s_add_i32 s26, s26, 2
	s_add_u32 s2, s2, 0x100
	s_addc_u32 s3, s3, 0
	s_cmp_gt_u32 s26, 29
	s_barrier
	s_cbranch_scc0 .LBB0_1132
	s_waitcnt lgkmcnt(0)
	s_lshl_b32 s0, s4, 8
	s_ashr_i32 s1, s0, 31
	s_lshl_b64 s[26:27], s[0:1], 1
	s_add_u32 s6, s93, s26
	s_addc_u32 s7, s94, s27
	s_addk_i32 s0, 0xf800
	s_mov_b32 s1, s23
	s_lshl_b64 s[0:1], s[0:1], 1
	s_add_u32 s8, s91, s0
	s_addc_u32 s9, s92, s1
	s_cmp_lt_i32 s4, 8
	s_cselect_b64 s[0:1], -1, 0
	s_and_b64 s[2:3], s[0:1], exec
	s_cselect_b32 s3, s6, s8
	s_cselect_b32 s2, s7, s9
	s_add_u32 s6, s3, s22
	s_addc_u32 s7, s2, 0
	s_lshl_b32 s2, s5, 8
	v_add_u32_e32 v180, s2, v204
	v_ashrrev_i32_e32 v181, 31, v180
	v_lshl_add_u64 v[182:183], s[6:7], 0, v[160:161]
	v_lshlrev_b64 v[96:97], 12, v[180:181]
	v_lshl_add_u64 v[96:97], v[182:183], 0, v[96:97]
	global_load_dwordx4 v[156:159], v[96:97], off
	global_load_dwordx4 v[152:155], v[96:97], off offset:256
	s_lshl_b32 s6, s4, 2
	s_ashr_i32 s7, s6, 31
	s_lshl_b64 s[6:7], s[6:7], 2
	s_add_u32 s36, s95, s6
	s_addc_u32 s37, s96, s7
	s_cmp_gt_i32 s4, 7
	v_mov_b32_e32 v212, 1.0
	v_mov_b32_e32 v213, 1.0
	s_cbranch_scc1 .LBB0_1135
	v_lshlrev_b64 v[96:97], 7, v[180:181]
	v_lshl_add_u64 v[96:97], s[36:37], 0, v[96:97]
	global_load_dwordx4 v[96:99], v[96:97], off
	s_waitcnt vmcnt(0)
	v_add_f32_e32 v96, v96, v97
	v_add_f32_e32 v96, v98, v96
	v_add_f32_e32 v96, v99, v96
	v_fmamk_f32 v96, v96, 0x3b800000, v194
	v_mul_f32_e32 v97, 0x4b800000, v96
	v_cmp_gt_f32_e32 vcc, s55, v96
	s_nop 1
	v_cndmask_b32_e32 v96, v96, v97, vcc
	v_rsq_f32_e32 v96, v96
	s_nop 0
	v_mul_f32_e32 v97, 0x45800000, v96
	v_cndmask_b32_e32 v213, v96, v97, vcc

; #define PG8_STAGE(bufoff, gbase, voff) do { _Pragma("unroll") for (int _i = 0; _i < 2; ++_i) \
;         __builtin_amdgcn_global_load_lds((const unsigned*)((const char*)(gbase) + (voff)[_i]), (LAS unsigned*)(lds + (bufoff) + ldsw + _i * 8192), 16, 0, 0); } while (0)
; #define PG8_STAGE_A(bufoff, ptr, half, rev) do { if (REVA && (rev)) { const char* _p = (ptr) - ((half) ? hstepA : 0); PG8_STAGE(bufoff, _p, voffAr); } else { const char* _p = (ptr) + ((half) ? hstepA : 0); PG8_STAGE(bufoff, _p, voffA); } } while (0)
; #define PG8_LDA(dst, b, h) do { _Pragma("unroll") for (int m = 0; m < 4; ++m) _Pragma("unroll") for (int k = 0; k < 2; ++k) dst[m][k] = *(const LAS bf16x8*)(lds + PG8_SA(b, h) + aoff + m * 2048 + k * 1024); } while (0)
; #define PG8_WAIT_L(n) asm volatile("s_waitcnt lgkmcnt(" #n ")" ::: "memory")
; #define PG8_BAR __builtin_amdgcn_s_barrier()
;     ...
;     for (;;) {
;         const bool has_next = next_unit(ui + 1, nM, nN, MP, nxt, rot);
;         const char* nA = has_next ? nxt.a : cA; const char* nB = has_next ? nxt.b : cB; const char* nAr = has_next ? nxt.ar : cAr; const size_t nHb = has_next ? nxt.hb : cHb;
;         for (int t = 0; t < nt; t += 2) {
;             const bool last = (t == nt - 2);
;             const char* a1 = PG8_APTR(cA, cAr, t + 1); const bool r1 = REVA && ((t + 1) & 4);
;             const char* a2 = last ? nA : PG8_APTR(cA, cAr, t + 2); const bool r2 = REVA && !last && ((t + 2) & 4);
;             const char* a3 = last ? nA + kstep : PG8_APTR(cA, cAr, t + 3); const bool r3 = REVA && !last && ((t + 3) & 4);
;             const char* b2 = last ? nB : cB + (size_t)(t + 2) * kstep; const char* b3 = b2 + kstep; const size_t hb2 = last ? nHb : cHb;
;             PG8_LDB(B0, 0, 0); PG8_SCHED; PG8_LDA(At, 0, 0); PG8_STAGE_A(PG8_SA(1, 1), a1, 1, r1);
;             PG8_WAIT_L(8); PG8_BAR; PG8_WAIT_L(0); PG8_MMA(0, 0, At, B0); PG8_BAR; PG8_SCHED;
;             PG8_LDB(B1, 0, 1); PG8_STAGE(PG8_SB(0, 0), b2, voffB);
;             PG8_BAR; PG8_WAIT_L(0); PG8_MMA(0, 1, At, B1); PG8_BAR;
;     ...
;         for (int a = 0; a < 2; ++a)
; #pragma unroll
;             for (int b = 0; b < 2; ++b)
; #pragma unroll
;                 for (int m = 0; m < 4; ++m)
; #pragma unroll
;                     for (int n = 0; n < 2; ++n) acc[a][b][m][n] = (f32x4){0.f, 0.f, 0.f, 0.f};
;         cur = nxt; cA = nA; cB = nB; cAr = nAr; cHb = nHb; ++ui;
.LBB0_1228:
	s_add_u32 s3, s36, 0x80
	s_addc_u32 s27, s37, 0
	s_add_u32 s14, s0, 0x100080
	s_addc_u32 s15, s1, 0
	s_add_u32 s69, s20, 0x100
	v_mov_b32_e32 v0, 0
	v_lshl_add_u64 v[128:129], s[14:15], 0, v[154:155]
	v_lshl_add_u64 v[130:131], s[14:15], 0, v[156:157]
	s_addc_u32 s70, s21, 0
	s_mov_b32 s71, -2
	s_mov_b64 s[42:43], 0
	v_mov_b32_e32 v1, v0
	v_pk_mov_b32 v[2:3], v[0:1], v[0:1]
	v_pk_mov_b32 v[4:5], v[0:1], v[0:1]
	v_pk_mov_b32 v[6:7], v[0:1], v[0:1]
	v_pk_mov_b32 v[8:9], v[0:1], v[0:1]
	v_pk_mov_b32 v[10:11], v[0:1], v[0:1]
	v_pk_mov_b32 v[12:13], v[0:1], v[0:1]
	v_pk_mov_b32 v[14:15], v[0:1], v[0:1]
	v_pk_mov_b32 v[16:17], v[0:1], v[0:1]
	v_pk_mov_b32 v[18:19], v[0:1], v[0:1]
	v_pk_mov_b32 v[20:21], v[0:1], v[0:1]
	v_pk_mov_b32 v[22:23], v[0:1], v[0:1]
	v_pk_mov_b32 v[24:25], v[0:1], v[0:1]
	v_pk_mov_b32 v[26:27], v[0:1], v[0:1]
	v_pk_mov_b32 v[28:29], v[0:1], v[0:1]
	v_pk_mov_b32 v[30:31], v[0:1], v[0:1]
	v_pk_mov_b32 v[32:33], v[0:1], v[0:1]
	v_pk_mov_b32 v[34:35], v[0:1], v[0:1]
	v_pk_mov_b32 v[36:37], v[0:1], v[0:1]
	v_pk_mov_b32 v[38:39], v[0:1], v[0:1]
	v_pk_mov_b32 v[40:41], v[0:1], v[0:1]
	v_pk_mov_b32 v[42:43], v[0:1], v[0:1]
	v_pk_mov_b32 v[44:45], v[0:1], v[0:1]
	v_pk_mov_b32 v[46:47], v[0:1], v[0:1]
	v_pk_mov_b32 v[48:49], v[0:1], v[0:1]
	v_pk_mov_b32 v[50:51], v[0:1], v[0:1]
	v_pk_mov_b32 v[52:53], v[0:1], v[0:1]
	v_pk_mov_b32 v[54:55], v[0:1], v[0:1]
	v_pk_mov_b32 v[56:57], v[0:1], v[0:1]
	v_pk_mov_b32 v[58:59], v[0:1], v[0:1]
	v_pk_mov_b32 v[60:61], v[0:1], v[0:1]
	v_pk_mov_b32 v[62:63], v[0:1], v[0:1]
	v_pk_mov_b32 v[64:65], v[0:1], v[0:1]
	v_pk_mov_b32 v[66:67], v[0:1], v[0:1]
	v_pk_mov_b32 v[68:69], v[0:1], v[0:1]
	v_pk_mov_b32 v[70:71], v[0:1], v[0:1]
	v_pk_mov_b32 v[72:73], v[0:1], v[0:1]
	v_pk_mov_b32 v[74:75], v[0:1], v[0:1]
	v_pk_mov_b32 v[76:77], v[0:1], v[0:1]
	v_pk_mov_b32 v[78:79], v[0:1], v[0:1]
	v_pk_mov_b32 v[80:81], v[0:1], v[0:1]
	v_pk_mov_b32 v[82:83], v[0:1], v[0:1]
	v_pk_mov_b32 v[84:85], v[0:1], v[0:1]
	v_pk_mov_b32 v[86:87], v[0:1], v[0:1]
	v_pk_mov_b32 v[88:89], v[0:1], v[0:1]
	v_pk_mov_b32 v[90:91], v[0:1], v[0:1]
	v_pk_mov_b32 v[92:93], v[0:1], v[0:1]
	v_pk_mov_b32 v[94:95], v[0:1], v[0:1]
	v_pk_mov_b32 v[96:97], v[0:1], v[0:1]
	v_pk_mov_b32 v[98:99], v[0:1], v[0:1]
	v_pk_mov_b32 v[100:101], v[0:1], v[0:1]
	v_pk_mov_b32 v[102:103], v[0:1], v[0:1]
	v_pk_mov_b32 v[104:105], v[0:1], v[0:1]
	v_pk_mov_b32 v[106:107], v[0:1], v[0:1]
	v_pk_mov_b32 v[108:109], v[0:1], v[0:1]
	v_pk_mov_b32 v[110:111], v[0:1], v[0:1]
	v_pk_mov_b32 v[112:113], v[0:1], v[0:1]
	v_pk_mov_b32 v[114:115], v[0:1], v[0:1]
	v_pk_mov_b32 v[116:117], v[0:1], v[0:1]
	v_pk_mov_b32 v[118:119], v[0:1], v[0:1]
	v_pk_mov_b32 v[120:121], v[0:1], v[0:1]
	v_pk_mov_b32 v[122:123], v[0:1], v[0:1]
	v_pk_mov_b32 v[124:125], v[0:1], v[0:1]
	v_pk_mov_b32 v[126:127], v[0:1], v[0:1]
	v_add_u32_e32 v158, 0x10000, v171
	ds_read_b128 v[132:135], v158
	ds_read_b128 v[136:139], v158 offset:1024
	ds_read_b128 v[140:143], v158 offset:2048
	ds_read_b128 v[174:177], v158 offset:3072
.LBB0_1229:
	s_add_u32 s10, s0, s42
	s_addc_u32 s11, s1, s43
	s_add_u32 s16, s10, 0x100
	s_addc_u32 s17, s11, 0
	s_add_u32 s10, s10, 0x180
	s_addc_u32 s11, s11, 0
	s_add_u32 s14, s69, s42
	s_addc_u32 s15, s70, s43
	s_add_i32 s78, 0, 0x10000
	s_cmpk_eq_i32 s42, 0x1f00
	s_cselect_b32 s15, s39, s15
	s_cselect_b32 s14, s38, s14
	s_cselect_b32 s21, s37, s17
	s_cselect_b32 s20, s36, s16
	s_cselect_b32 s17, s27, s11
	s_cselect_b32 s16, s3, s10
	v_lshl_add_u64 v[158:159], v[128:129], 0, s[42:43]
	s_add_i32 m0, s48, 0xc000
	ds_read_b128 v[178:181], v172
	ds_read_b128 v[182:185], v172 offset:1024
	ds_read_b128 v[204:207], v172 offset:2048
	ds_read_b128 v[208:211], v172 offset:3072
	ds_read_b128 v[212:215], v172 offset:4096
	ds_read_b128 v[216:219], v172 offset:5120
	ds_read_b128 v[220:223], v172 offset:6144
	ds_read_b128 v[224:227], v172 offset:7168
	global_load_lds_dwordx4 v[158:159], off
	v_lshl_add_u64 v[158:159], v[130:131], 0, s[42:43]
	s_add_i32 m0, s48, 0xe000
	s_nop 0
	global_load_lds_dwordx4 v[158:159], off
	s_waitcnt lgkmcnt(8)
	s_waitcnt vmcnt(10)
	s_barrier
	s_waitcnt lgkmcnt(0)
	v_mfma_f32_16x16x32_bf16 v[124:127], v[132:135], v[178:181], v[124:127]
	v_mfma_f32_16x16x32_bf16 v[120:123], v[140:143], v[178:181], v[120:123]
	v_mfma_f32_16x16x32_bf16 v[112:115], v[132:135], v[204:207], v[112:115]
	v_mfma_f32_16x16x32_bf16 v[108:111], v[140:143], v[204:207], v[108:111]
	v_mfma_f32_16x16x32_bf16 v[92:95], v[132:135], v[212:215], v[92:95]
	v_mfma_f32_16x16x32_bf16 v[88:91], v[140:143], v[212:215], v[88:91]
	v_mfma_f32_16x16x32_bf16 v[84:87], v[132:135], v[220:223], v[84:87]
	v_mfma_f32_16x16x32_bf16 v[76:79], v[140:143], v[220:223], v[76:79]
	v_mfma_f32_16x16x32_bf16 v[124:127], v[136:139], v[182:185], v[124:127]
	v_mfma_f32_16x16x32_bf16 v[120:123], v[174:177], v[182:185], v[120:123]
	v_mfma_f32_16x16x32_bf16 v[112:115], v[136:139], v[208:211], v[112:115]
	v_mfma_f32_16x16x32_bf16 v[108:111], v[174:177], v[208:211], v[108:111]
	v_mfma_f32_16x16x32_bf16 v[92:95], v[136:139], v[216:219], v[92:95]
	v_mfma_f32_16x16x32_bf16 v[88:91], v[174:177], v[216:219], v[88:91]
	v_mfma_f32_16x16x32_bf16 v[84:87], v[136:139], v[224:227], v[84:87]
	v_mfma_f32_16x16x32_bf16 v[76:79], v[174:177], v[224:227], v[76:79]
	s_barrier
	s_add_i32 s10, 0, 0x14000
	v_add_u32_e32 v158, s10, v171
	s_add_i32 s11, s78, s5
	ds_read_b128 v[228:231], v158
	ds_read_b128 v[232:235], v158 offset:1024
	ds_read_b128 v[236:239], v158 offset:2048
	ds_read_b128 v[240:243], v158 offset:3072
	v_lshl_add_u64 v[158:159], s[14:15], 0, v[150:151]
	s_mov_b32 m0, s11
	v_lshl_add_u64 v[168:169], s[14:15], 0, v[148:149]
	global_load_lds_dwordx4 v[158:159], off
	s_add_i32 m0, s11, 0x2000
	s_nop 0
	global_load_lds_dwordx4 v[168:169], off
	s_waitcnt vmcnt(10)
	s_barrier
; #define PG8_STAGE(bufoff, gbase, voff) do { _Pragma("unroll") for (int _i = 0; _i < 2; ++_i) \
;         __builtin_amdgcn_global_load_lds((const unsigned*)((const char*)(gbase) + (voff)[_i]), (LAS unsigned*)(lds + (bufoff) + ldsw + _i * 8192), 16, 0, 0); } while (0)
; #define PG8_STAGE_A(bufoff, ptr, half, rev) do { if (REVA && (rev)) { const char* _p = (ptr) - ((half) ? hstepA : 0); PG8_STAGE(bufoff, _p, voffAr); } else { const char* _p = (ptr) + ((half) ? hstepA : 0); PG8_STAGE(bufoff, _p, voffA); } } while (0)
; #define PG8_LDA(dst, b, h) do { _Pragma("unroll") for (int m = 0; m < 4; ++m) _Pragma("unroll") for (int k = 0; k < 2; ++k) dst[m][k] = *(const LAS bf16x8*)(lds + PG8_SA(b, h) + aoff + m * 2048 + k * 1024); } while (0)
; #define PG8_LDB(dst, b, h) do { _Pragma("unroll") for (int n = 0; n < 2; ++n) _Pragma("unroll") for (int k = 0; k < 2; ++k) dst[n][k] = *(const LAS bf16x8*)(lds + PG8_SB(b, h) + boff + n * 2048 + k * 1024); } while (0)
; #define PG8_MMA(ai, bj, At, Bt) do { __builtin_amdgcn_s_setprio(1); _Pragma("unroll") for (int m = 0; m < 4; ++m) _Pragma("unroll") for (int n = 0; n < 2; ++n) _Pragma("unroll") for (int k = 0; k < 2; ++k) \
;         acc[ai][bj][m][n] = __builtin_amdgcn_mfma_f32_16x16x32_bf16(Bt[n][k], At[m][k], acc[ai][bj][m][n], 0, 0, 0); __builtin_amdgcn_s_setprio(0); } while (0)
; #define PG8_WAIT_V(n) asm volatile("s_waitcnt vmcnt(" #n ")" ::: "memory")
; #define PG8_WAIT_L(n) asm volatile("s_waitcnt lgkmcnt(" #n ")" ::: "memory")
; #define PG8_BAR __builtin_amdgcn_s_barrier()
; #define PG8_SCHED __builtin_amdgcn_sched_barrier(0)
;     ...
;             PG8_BAR; PG8_WAIT_L(0); PG8_MMA(0, 1, At, B1); PG8_BAR;
;             PG8_LDA(At, 0, 1); PG8_STAGE_A(PG8_SA(0, 0), a2, 0, r2);
;             PG8_BAR; PG8_WAIT_L(0); PG8_MMA(1, 0, At, B0); PG8_BAR; PG8_SCHED;
;             PG8_STAGE(PG8_SB(0, 1), b2 + hb2, voffB);
;             PG8_WAIT_V(6); PG8_BAR; PG8_MMA(1, 1, At, B1); PG8_BAR;
;             PG8_LDB(B0, 1, 0); PG8_SCHED; PG8_LDA(At, 1, 0); PG8_STAGE_A(PG8_SA(0, 1), a2, 1, r2);
;             PG8_WAIT_L(8); PG8_BAR; PG8_WAIT_L(0); PG8_MMA(0, 0, At, B0); PG8_BAR; PG8_SCHED;
;             PG8_LDB(B1, 1, 1); PG8_STAGE(PG8_SB(1, 0), b3, voffB);
;             PG8_BAR; PG8_WAIT_L(0); PG8_MMA(0, 1, At, B1); PG8_BAR;
	s_waitcnt lgkmcnt(0)
	v_mfma_f32_16x16x32_bf16 v[116:119], v[228:231], v[178:181], v[116:119]
	v_mfma_f32_16x16x32_bf16 v[104:107], v[236:239], v[178:181], v[104:107]
	v_mfma_f32_16x16x32_bf16 v[100:103], v[228:231], v[204:207], v[100:103]
	v_mfma_f32_16x16x32_bf16 v[96:99], v[236:239], v[204:207], v[96:99]
	v_mfma_f32_16x16x32_bf16 v[80:83], v[228:231], v[212:215], v[80:83]
	v_mfma_f32_16x16x32_bf16 v[72:75], v[236:239], v[212:215], v[72:75]
	v_mfma_f32_16x16x32_bf16 v[68:71], v[228:231], v[220:223], v[68:71]
	v_mfma_f32_16x16x32_bf16 v[64:67], v[236:239], v[220:223], v[64:67]
	v_mfma_f32_16x16x32_bf16 v[116:119], v[232:235], v[182:185], v[116:119]
	v_mfma_f32_16x16x32_bf16 v[104:107], v[240:243], v[182:185], v[104:107]
	v_mfma_f32_16x16x32_bf16 v[100:103], v[232:235], v[208:211], v[100:103]
	v_mfma_f32_16x16x32_bf16 v[96:99], v[240:243], v[208:211], v[96:99]
	v_mfma_f32_16x16x32_bf16 v[80:83], v[232:235], v[216:219], v[80:83]
	v_mfma_f32_16x16x32_bf16 v[72:75], v[240:243], v[216:219], v[72:75]
	v_mfma_f32_16x16x32_bf16 v[68:71], v[232:235], v[224:227], v[68:71]
	v_mfma_f32_16x16x32_bf16 v[64:67], v[240:243], v[224:227], v[64:67]
	s_mov_b32 m0, s48
	v_lshl_add_u64 v[190:191], s[20:21], 0, v[150:151]
	s_barrier
	ds_read_b128 v[178:181], v172 offset:16384
	ds_read_b128 v[182:185], v172 offset:17408
	ds_read_b128 v[204:207], v172 offset:18432
	ds_read_b128 v[208:211], v172 offset:19456
	ds_read_b128 v[212:215], v172 offset:20480
	ds_read_b128 v[216:219], v172 offset:21504
	ds_read_b128 v[220:223], v172 offset:22528
	ds_read_b128 v[224:227], v172 offset:23552
	global_load_lds_dwordx4 v[190:191], off
	v_lshl_add_u64 v[190:191], s[20:21], 0, v[148:149]
	s_mov_b32 m0, s49
	s_nop 0
	global_load_lds_dwordx4 v[190:191], off
	s_waitcnt vmcnt(10)
	s_barrier
	s_waitcnt lgkmcnt(0)
	v_mfma_f32_16x16x32_bf16 v[60:63], v[132:135], v[178:181], v[60:63]
	v_mfma_f32_16x16x32_bf16 v[56:59], v[140:143], v[178:181], v[56:59]
	v_mfma_f32_16x16x32_bf16 v[52:55], v[132:135], v[204:207], v[52:55]
	v_mfma_f32_16x16x32_bf16 v[40:43], v[140:143], v[204:207], v[40:43]
	v_mfma_f32_16x16x32_bf16 v[28:31], v[132:135], v[212:215], v[28:31]
	v_mfma_f32_16x16x32_bf16 v[24:27], v[140:143], v[212:215], v[24:27]
	v_mfma_f32_16x16x32_bf16 v[20:23], v[132:135], v[220:223], v[20:23]
	v_mfma_f32_16x16x32_bf16 v[8:11], v[140:143], v[220:223], v[8:11]
	v_mfma_f32_16x16x32_bf16 v[60:63], v[136:139], v[182:185], v[60:63]
	v_mfma_f32_16x16x32_bf16 v[56:59], v[174:177], v[182:185], v[56:59]
	v_mfma_f32_16x16x32_bf16 v[52:55], v[136:139], v[208:211], v[52:55]
	v_mfma_f32_16x16x32_bf16 v[40:43], v[174:177], v[208:211], v[40:43]
	v_mfma_f32_16x16x32_bf16 v[28:31], v[136:139], v[216:219], v[28:31]
	v_mfma_f32_16x16x32_bf16 v[24:27], v[174:177], v[216:219], v[24:27]
	v_mfma_f32_16x16x32_bf16 v[20:23], v[136:139], v[224:227], v[20:23]
	v_mfma_f32_16x16x32_bf16 v[8:11], v[174:177], v[224:227], v[8:11]
	s_barrier
	s_add_u32 s78, s14, 0x100000
	s_addc_u32 s79, s15, 0
	s_add_i32 s10, s10, s5
	v_lshl_add_u64 v[132:133], s[78:79], 0, v[150:151]
	s_mov_b32 m0, s10
	s_nop 0
	global_load_lds_dwordx4 v[132:133], off
	v_lshl_add_u64 v[132:133], s[78:79], 0, v[148:149]
	s_add_i32 m0, s10, 0x2000
	s_nop 0
	global_load_lds_dwordx4 v[132:133], off
	v_add_u32_e32 v173, 0x18000, v171
	ds_read_b128 v[132:135], v173
	ds_read_b128 v[136:139], v173 offset:1024
	ds_read_b128 v[140:143], v173 offset:2048
	ds_read_b128 v[174:177], v173 offset:3072
	s_waitcnt vmcnt(10)
	s_barrier
	v_mfma_f32_16x16x32_bf16 v[48:51], v[228:231], v[178:181], v[48:51]
	v_mfma_f32_16x16x32_bf16 v[44:47], v[236:239], v[178:181], v[44:47]
	v_mfma_f32_16x16x32_bf16 v[36:39], v[228:231], v[204:207], v[36:39]
	v_mfma_f32_16x16x32_bf16 v[32:35], v[236:239], v[204:207], v[32:35]
	v_mfma_f32_16x16x32_bf16 v[16:19], v[228:231], v[212:215], v[16:19]
	v_mfma_f32_16x16x32_bf16 v[12:15], v[236:239], v[212:215], v[12:15]
	v_mfma_f32_16x16x32_bf16 v[4:7], v[228:231], v[220:223], v[4:7]
	v_mfma_f32_16x16x32_bf16 v[0:3], v[236:239], v[220:223], v[0:3]
	v_mfma_f32_16x16x32_bf16 v[48:51], v[232:235], v[182:185], v[48:51]
	v_mfma_f32_16x16x32_bf16 v[44:47], v[240:243], v[182:185], v[44:47]
	v_mfma_f32_16x16x32_bf16 v[36:39], v[232:235], v[208:211], v[36:39]
	v_mfma_f32_16x16x32_bf16 v[32:35], v[240:243], v[208:211], v[32:35]
	v_mfma_f32_16x16x32_bf16 v[16:19], v[232:235], v[216:219], v[16:19]
	v_mfma_f32_16x16x32_bf16 v[12:15], v[240:243], v[216:219], v[12:15]
	v_mfma_f32_16x16x32_bf16 v[4:7], v[232:235], v[224:227], v[4:7]
	v_mfma_f32_16x16x32_bf16 v[0:3], v[240:243], v[224:227], v[0:3]
	s_add_i32 s10, 0, 0x18000
	s_barrier
	s_add_u32 s20, s20, 0x100000
	s_addc_u32 s21, s21, 0
	s_mov_b32 m0, s50
	v_lshl_add_u64 v[190:191], s[20:21], 0, v[150:151]
	ds_read_b128 v[178:181], v172 offset:32768
	ds_read_b128 v[182:185], v172 offset:33792
	ds_read_b128 v[204:207], v172 offset:34816
	ds_read_b128 v[208:211], v172 offset:35840
	ds_read_b128 v[212:215], v172 offset:36864
	ds_read_b128 v[216:219], v172 offset:37888
	ds_read_b128 v[220:223], v172 offset:38912
	ds_read_b128 v[224:227], v172 offset:39936
	global_load_lds_dwordx4 v[190:191], off
	v_lshl_add_u64 v[190:191], s[20:21], 0, v[148:149]
	s_mov_b32 m0, s51
	s_nop 0
	global_load_lds_dwordx4 v[190:191], off
	s_waitcnt lgkmcnt(8)
	s_waitcnt vmcnt(10)
	s_barrier
; #define PG8_STAGE(bufoff, gbase, voff) do { _Pragma("unroll") for (int _i = 0; _i < 2; ++_i) \
;         __builtin_amdgcn_global_load_lds((const unsigned*)((const char*)(gbase) + (voff)[_i]), (LAS unsigned*)(lds + (bufoff) + ldsw + _i * 8192), 16, 0, 0); } while (0)
; #define PG8_STAGE_A(bufoff, ptr, half, rev) do { if (REVA && (rev)) { const char* _p = (ptr) - ((half) ? hstepA : 0); PG8_STAGE(bufoff, _p, voffAr); } else { const char* _p = (ptr) + ((half) ? hstepA : 0); PG8_STAGE(bufoff, _p, voffA); } } while (0)
; #define PG8_LDA(dst, b, h) do { _Pragma("unroll") for (int m = 0; m < 4; ++m) _Pragma("unroll") for (int k = 0; k < 2; ++k) dst[m][k] = *(const LAS bf16x8*)(lds + PG8_SA(b, h) + aoff + m * 2048 + k * 1024); } while (0)
; #define PG8_LDB(dst, b, h) do { _Pragma("unroll") for (int n = 0; n < 2; ++n) _Pragma("unroll") for (int k = 0; k < 2; ++k) dst[n][k] = *(const LAS bf16x8*)(lds + PG8_SB(b, h) + boff + n * 2048 + k * 1024); } while (0)
; #define PG8_MMA(ai, bj, At, Bt) do { __builtin_amdgcn_s_setprio(1); _Pragma("unroll") for (int m = 0; m < 4; ++m) _Pragma("unroll") for (int n = 0; n < 2; ++n) _Pragma("unroll") for (int k = 0; k < 2; ++k) \
;         acc[ai][bj][m][n] = __builtin_amdgcn_mfma_f32_16x16x32_bf16(Bt[n][k], At[m][k], acc[ai][bj][m][n], 0, 0, 0); __builtin_amdgcn_s_setprio(0); } while (0)
; #define PG8_WAIT_V(n) asm volatile("s_waitcnt vmcnt(" #n ")" ::: "memory")
; #define PG8_WAIT_L(n) asm volatile("s_waitcnt lgkmcnt(" #n ")" ::: "memory")
; #define PG8_BAR __builtin_amdgcn_s_barrier()
; #define PG8_SCHED __builtin_amdgcn_sched_barrier(0)
;     ...
;             PG8_LDB(B0, 1, 0); PG8_SCHED; PG8_LDA(At, 1, 0); PG8_STAGE_A(PG8_SA(0, 1), a2, 1, r2);
;             PG8_WAIT_L(8); PG8_BAR; PG8_WAIT_L(0); PG8_MMA(0, 0, At, B0); PG8_BAR; PG8_SCHED;
;             PG8_LDB(B1, 1, 1); PG8_STAGE(PG8_SB(1, 0), b3, voffB);
;             PG8_BAR; PG8_WAIT_L(0); PG8_MMA(0, 1, At, B1); PG8_BAR;
;             PG8_LDA(At, 1, 1); PG8_STAGE_A(PG8_SA(1, 0), a3, 0, r3);
;             PG8_BAR; PG8_WAIT_L(0); PG8_MMA(1, 0, At, B0); PG8_BAR; PG8_SCHED;
;             PG8_STAGE(PG8_SB(1, 1), b3 + hb2, voffB);
;             PG8_WAIT_V(6); PG8_BAR; PG8_MMA(1, 1, At, B1); PG8_BAR;
	s_waitcnt lgkmcnt(0)
	v_mfma_f32_16x16x32_bf16 v[124:127], v[132:135], v[178:181], v[124:127]
	v_mfma_f32_16x16x32_bf16 v[120:123], v[140:143], v[178:181], v[120:123]
	v_mfma_f32_16x16x32_bf16 v[112:115], v[132:135], v[204:207], v[112:115]
	v_mfma_f32_16x16x32_bf16 v[108:111], v[140:143], v[204:207], v[108:111]
	v_mfma_f32_16x16x32_bf16 v[92:95], v[132:135], v[212:215], v[92:95]
	v_mfma_f32_16x16x32_bf16 v[88:91], v[140:143], v[212:215], v[88:91]
	v_mfma_f32_16x16x32_bf16 v[84:87], v[132:135], v[220:223], v[84:87]
	v_mfma_f32_16x16x32_bf16 v[76:79], v[140:143], v[220:223], v[76:79]
	v_mfma_f32_16x16x32_bf16 v[124:127], v[136:139], v[182:185], v[124:127]
	v_mfma_f32_16x16x32_bf16 v[120:123], v[174:177], v[182:185], v[120:123]
	v_mfma_f32_16x16x32_bf16 v[112:115], v[136:139], v[208:211], v[112:115]
	v_mfma_f32_16x16x32_bf16 v[108:111], v[174:177], v[208:211], v[108:111]
	v_mfma_f32_16x16x32_bf16 v[92:95], v[136:139], v[216:219], v[92:95]
	v_mfma_f32_16x16x32_bf16 v[88:91], v[174:177], v[216:219], v[88:91]
	v_mfma_f32_16x16x32_bf16 v[84:87], v[136:139], v[224:227], v[84:87]
	v_mfma_f32_16x16x32_bf16 v[76:79], v[174:177], v[224:227], v[76:79]
	s_barrier
	s_add_i32 s11, 0, 0x1c000
	s_add_i32 s10, s10, s5
	v_add_u32_e32 v173, s11, v171
	v_lshl_add_u64 v[158:159], v[158:159], 0, s[28:29]
	s_mov_b32 m0, s10
	ds_read_b128 v[228:231], v173
	ds_read_b128 v[232:235], v173 offset:1024
	ds_read_b128 v[236:239], v173 offset:2048
	ds_read_b128 v[240:243], v173 offset:3072
	global_load_lds_dwordx4 v[158:159], off
	v_lshl_add_u64 v[158:159], v[168:169], 0, s[28:29]
	s_add_i32 m0, s10, 0x2000
	s_nop 0
	global_load_lds_dwordx4 v[158:159], off
	s_waitcnt vmcnt(10)
	s_barrier
	s_waitcnt lgkmcnt(0)
	v_mfma_f32_16x16x32_bf16 v[116:119], v[228:231], v[178:181], v[116:119]
	v_mfma_f32_16x16x32_bf16 v[104:107], v[236:239], v[178:181], v[104:107]
	v_mfma_f32_16x16x32_bf16 v[100:103], v[228:231], v[204:207], v[100:103]
	v_mfma_f32_16x16x32_bf16 v[96:99], v[236:239], v[204:207], v[96:99]
	v_mfma_f32_16x16x32_bf16 v[80:83], v[228:231], v[212:215], v[80:83]
	v_mfma_f32_16x16x32_bf16 v[72:75], v[236:239], v[212:215], v[72:75]
	v_mfma_f32_16x16x32_bf16 v[68:71], v[228:231], v[220:223], v[68:71]
	v_mfma_f32_16x16x32_bf16 v[64:67], v[236:239], v[220:223], v[64:67]
	v_mfma_f32_16x16x32_bf16 v[116:119], v[232:235], v[182:185], v[116:119]
	v_mfma_f32_16x16x32_bf16 v[104:107], v[240:243], v[182:185], v[104:107]
	v_mfma_f32_16x16x32_bf16 v[100:103], v[232:235], v[208:211], v[100:103]
	v_mfma_f32_16x16x32_bf16 v[96:99], v[240:243], v[208:211], v[96:99]
	v_mfma_f32_16x16x32_bf16 v[80:83], v[232:235], v[216:219], v[80:83]
	v_mfma_f32_16x16x32_bf16 v[72:75], v[240:243], v[216:219], v[72:75]
	v_mfma_f32_16x16x32_bf16 v[68:71], v[232:235], v[224:227], v[68:71]
	v_mfma_f32_16x16x32_bf16 v[64:67], v[240:243], v[224:227], v[64:67]
	s_mov_b32 m0, s66
	v_lshl_add_u64 v[158:159], s[16:17], 0, v[150:151]
	s_barrier
	ds_read_b128 v[178:181], v172 offset:49152
	ds_read_b128 v[182:185], v172 offset:50176
	ds_read_b128 v[204:207], v172 offset:51200
	ds_read_b128 v[208:211], v172 offset:52224
	ds_read_b128 v[212:215], v172 offset:53248
	ds_read_b128 v[216:219], v172 offset:54272
	ds_read_b128 v[220:223], v172 offset:55296
	ds_read_b128 v[224:227], v172 offset:56320
	global_load_lds_dwordx4 v[158:159], off
	v_lshl_add_u64 v[158:159], s[16:17], 0, v[148:149]
	s_mov_b32 m0, s67
	s_nop 0
	global_load_lds_dwordx4 v[158:159], off
	s_waitcnt vmcnt(10)
	s_barrier
	s_waitcnt lgkmcnt(0)
	v_mfma_f32_16x16x32_bf16 v[60:63], v[132:135], v[178:181], v[60:63]
	v_mfma_f32_16x16x32_bf16 v[56:59], v[140:143], v[178:181], v[56:59]
	v_mfma_f32_16x16x32_bf16 v[52:55], v[132:135], v[204:207], v[52:55]
	v_mfma_f32_16x16x32_bf16 v[40:43], v[140:143], v[204:207], v[40:43]
	v_mfma_f32_16x16x32_bf16 v[28:31], v[132:135], v[212:215], v[28:31]
	v_mfma_f32_16x16x32_bf16 v[24:27], v[140:143], v[212:215], v[24:27]
	v_mfma_f32_16x16x32_bf16 v[20:23], v[132:135], v[220:223], v[20:23]
	v_mfma_f32_16x16x32_bf16 v[8:11], v[140:143], v[220:223], v[8:11]
	v_mfma_f32_16x16x32_bf16 v[60:63], v[136:139], v[182:185], v[60:63]
	v_mfma_f32_16x16x32_bf16 v[56:59], v[174:177], v[182:185], v[56:59]
	v_mfma_f32_16x16x32_bf16 v[52:55], v[136:139], v[208:211], v[52:55]
	v_mfma_f32_16x16x32_bf16 v[40:43], v[174:177], v[208:211], v[40:43]
	v_mfma_f32_16x16x32_bf16 v[28:31], v[136:139], v[216:219], v[28:31]
	v_mfma_f32_16x16x32_bf16 v[24:27], v[174:177], v[216:219], v[24:27]
	v_mfma_f32_16x16x32_bf16 v[20:23], v[136:139], v[224:227], v[20:23]
	v_mfma_f32_16x16x32_bf16 v[8:11], v[174:177], v[224:227], v[8:11]
	s_barrier
	s_add_u32 s14, s14, 0x100080
	s_addc_u32 s15, s15, 0
	s_add_i32 s10, s11, s5
	v_lshl_add_u64 v[132:133], s[14:15], 0, v[150:151]
	s_mov_b32 m0, s10
	s_nop 0
	global_load_lds_dwordx4 v[132:133], off
	v_lshl_add_u64 v[132:133], s[14:15], 0, v[148:149]
	s_add_i32 m0, s10, 0x2000
	s_nop 0
	global_load_lds_dwordx4 v[132:133], off
	v_add_u32_e32 v158, 0x10000, v171
	ds_read_b128 v[132:135], v158
	ds_read_b128 v[136:139], v158 offset:1024
	ds_read_b128 v[140:143], v158 offset:2048
	ds_read_b128 v[174:177], v158 offset:3072
	s_waitcnt vmcnt(10)
	s_barrier
; #define PG8_MMA(ai, bj, At, Bt) do { __builtin_amdgcn_s_setprio(1); _Pragma("unroll") for (int m = 0; m < 4; ++m) _Pragma("unroll") for (int n = 0; n < 2; ++n) _Pragma("unroll") for (int k = 0; k < 2; ++k) \
;         acc[ai][bj][m][n] = __builtin_amdgcn_mfma_f32_16x16x32_bf16(Bt[n][k], At[m][k], acc[ai][bj][m][n], 0, 0, 0); __builtin_amdgcn_s_setprio(0); } while (0)
; #define PG8_WAIT_V(n) asm volatile("s_waitcnt vmcnt(" #n ")" ::: "memory")
; #define PG8_BAR __builtin_amdgcn_s_barrier()
;     ...
;             PG8_WAIT_V(6); PG8_BAR; PG8_MMA(1, 1, At, B1); PG8_BAR;
;         }
;         E(acc, cur, wr, wc, fr, fq, lane);
;     __device__ __forceinline__ void operator()(const f32x4 (&acc)[2][2][4][2], const Unit& u, int wr, int wc, int fr, int fq, int lane) const {
;         const bool lat = u.pm < 128;
;         const int s = lat ? (u.pm >> 4) : 8;
;         const float* gate = modi + s * 6144 + 4096 + u.pn * BM + wc * 32 + 4 * fq;
;         const size_t r0 = lat ? (size_t)u.pm * BM : (size_t)(u.pm - 128) * BM;
;         const float* base = (lat ? baseL : baseC) + u.pn * BM + wc * 32 + 4 * fq;
;         float* out = (lat ? outL : outC) + u.pn * BM + wc * 32 + 4 * fq;
;         f32x4 gv[2][2];
; #pragma unroll
;         for (int bj = 0; bj < 2; ++bj)
; #pragma unroll
;             for (int n = 0; n < 2; ++n) gv[bj][n] = *(const f32x4*)(gate + bj * HALF + n * 16);
; #pragma unroll
;         for (int ai = 0; ai < 2; ++ai)
; #pragma unroll
;           for (int mh = 0; mh < 2; ++mh) {
;             f32x4 bs[2][2][2];
; #pragma unroll
;             for (int m2 = 0; m2 < 2; ++m2) {
;                 const size_t ro = (r0 + ai * HALF + wr * 64 + (mh * 2 + m2) * 16 + fr) * (size_t)D;
; #pragma unroll
;                 for (int bj = 0; bj < 2; ++bj)
; #pragma unroll
;                     for (int n = 0; n < 2; ++n) bs[m2][bj][n] = *(const f32x4*)(base + ro + bj * HALF + n * 16);
;             }
;             __builtin_amdgcn_sched_barrier(0);
; #pragma unroll
;             for (int m2 = 0; m2 < 2; ++m2) {
;                 const size_t ro = (r0 + ai * HALF + wr * 64 + (mh * 2 + m2) * 16 + fr) * (size_t)D;
; #pragma unroll
;                 for (int bj = 0; bj < 2; ++bj)
; #pragma unroll
;                     for (int n = 0; n < 2; ++n) *(f32x4*)(out + ro + bj * HALF + n * 16) = bs[m2][bj][n] + gv[bj][n] * acc[ai][bj][mh * 2 + m2][n];
	v_mfma_f32_16x16x32_bf16 v[48:51], v[228:231], v[178:181], v[48:51]
	v_mfma_f32_16x16x32_bf16 v[44:47], v[236:239], v[178:181], v[44:47]
	v_mfma_f32_16x16x32_bf16 v[36:39], v[228:231], v[204:207], v[36:39]
	v_mfma_f32_16x16x32_bf16 v[32:35], v[236:239], v[204:207], v[32:35]
	v_mfma_f32_16x16x32_bf16 v[16:19], v[228:231], v[212:215], v[16:19]
	v_mfma_f32_16x16x32_bf16 v[12:15], v[236:239], v[212:215], v[12:15]
	v_mfma_f32_16x16x32_bf16 v[4:7], v[228:231], v[220:223], v[4:7]
	v_mfma_f32_16x16x32_bf16 v[0:3], v[236:239], v[220:223], v[0:3]
	v_mfma_f32_16x16x32_bf16 v[48:51], v[232:235], v[182:185], v[48:51]
	v_mfma_f32_16x16x32_bf16 v[44:47], v[240:243], v[182:185], v[44:47]
	v_mfma_f32_16x16x32_bf16 v[36:39], v[232:235], v[208:211], v[36:39]
	v_mfma_f32_16x16x32_bf16 v[32:35], v[240:243], v[208:211], v[32:35]
	v_mfma_f32_16x16x32_bf16 v[16:19], v[232:235], v[216:219], v[16:19]
	v_mfma_f32_16x16x32_bf16 v[12:15], v[240:243], v[216:219], v[12:15]
	v_mfma_f32_16x16x32_bf16 v[4:7], v[232:235], v[224:227], v[4:7]
	v_mfma_f32_16x16x32_bf16 v[0:3], v[240:243], v[224:227], v[0:3]
	s_add_i32 s71, s71, 2
	s_add_u32 s42, s42, 0x100
	s_addc_u32 s43, s43, 0
	s_cmp_gt_u32 s71, 61
	s_barrier
	s_cbranch_scc0 .LBB0_1229
	s_waitcnt lgkmcnt(0)
	s_cmpk_lt_i32 s9, 0x80
	s_cselect_b64 vcc, -1, 0
	s_cselect_b32 s3, s61, s53
	s_cselect_b32 s10, s60, s52
	s_add_i32 s0, s9, 0xffffff80
	s_cmpk_lt_i32 s9, 0x80
	s_cselect_b32 s0, s9, s0
	s_lshr_b32 s1, s9, 4
	s_cmpk_lt_i32 s9, 0x80
	s_mulk_i32 s1, 0x1800
	s_cselect_b32 s14, s1, 0xc000
	s_ashr_i32 s15, s14, 31
	s_lshl_b64 s[14:15], s[14:15], 2
	s_add_u32 s1, s6, s14
	s_addc_u32 s11, s7, s15
	s_lshl_b32 s8, s8, 8
	s_ashr_i32 s9, s8, 31
	s_lshl_b64 s[8:9], s[8:9], 2
	s_add_u32 s1, s1, s8
	s_addc_u32 s11, s11, s9
	s_add_u32 s14, s1, s22
	s_waitcnt vmcnt(0)
	v_cndmask_b32_e32 v129, v147, v145, vcc
	v_cndmask_b32_e32 v128, v146, v144, vcc
	s_addc_u32 s15, s11, 0
	s_ashr_i32 s1, s0, 31
	v_lshl_add_u64 v[128:129], v[128:129], 0, s[8:9]
	s_add_u32 s8, s10, s8
	s_addc_u32 s3, s3, s9
	s_add_u32 s8, s8, s22
	v_lshl_add_u64 v[130:131], s[14:15], 0, v[160:161]
	s_addc_u32 s9, s3, 0
	s_mov_b32 s3, 0x704000
	s_lshl_b64 s[0:1], s[0:1], 21
	s_mov_b64 s[14:15], 0x704000
	v_lshl_add_u64 v[168:169], v[128:129], 0, s[22:23]
	v_add_co_u32_e32 v128, vcc, s3, v130
	v_lshl_add_u64 v[224:225], s[0:1], 0, v[152:153]
	v_lshl_add_u64 v[158:159], v[130:131], 0, s[14:15]
	v_addc_co_u32_e32 v129, vcc, 0, v131, vcc
	v_lshl_add_u64 v[190:191], v[168:169], 0, v[160:161]
	v_or_b32_e32 v226, 0x20000, v224
	v_mov_b32_e32 v227, v225
	global_load_dwordx4 v[136:139], v[158:159], off offset:64
	global_load_dwordx4 v[132:135], v[158:159], off offset:512
	global_load_dwordx4 v[140:143], v[128:129], off
	s_nop 0
	global_load_dwordx4 v[128:131], v[158:159], off offset:576
	v_lshl_add_u64 v[168:169], v[190:191], 0, v[224:225]
	v_lshl_add_u64 v[158:159], v[190:191], 0, v[226:227]
	global_load_dwordx4 v[174:177], v[168:169], off
	global_load_dwordx4 v[178:181], v[168:169], off offset:64
	global_load_dwordx4 v[182:185], v[168:169], off offset:512
	global_load_dwordx4 v[204:207], v[168:169], off offset:576
	global_load_dwordx4 v[208:211], v[158:159], off
	global_load_dwordx4 v[212:215], v[158:159], off offset:64
	global_load_dwordx4 v[216:219], v[158:159], off offset:512
	global_load_dwordx4 v[220:223], v[158:159], off offset:576
	v_lshl_add_u64 v[228:229], s[8:9], 0, v[160:161]
	v_lshl_add_u64 v[158:159], v[228:229], 0, v[224:225]
	s_waitcnt vmcnt(0)
	v_pk_fma_f32 v[118:119], v[118:119], v[134:135], v[184:185]
	v_pk_fma_f32 v[116:117], v[116:117], v[132:133], v[182:183]
	v_pk_fma_f32 v[106:107], v[106:107], v[130:131], v[206:207]
	v_pk_fma_f32 v[104:105], v[104:105], v[128:129], v[204:205]
	global_store_dwordx4 v[158:159], v[116:119], off offset:512
	global_store_dwordx4 v[158:159], v[104:107], off offset:576
	v_pk_fma_f32 v[126:127], v[126:127], v[142:143], v[176:177]
	v_lshl_add_u64 v[116:117], v[228:229], 0, v[226:227]
	v_pk_fma_f32 v[106:107], v[114:115], v[142:143], v[210:211]
	v_pk_fma_f32 v[104:105], v[112:113], v[140:141], v[208:209]
	v_pk_fma_f32 v[124:125], v[124:125], v[140:141], v[174:175]
	v_pk_fma_f32 v[122:123], v[122:123], v[138:139], v[180:181]
	v_pk_fma_f32 v[120:121], v[120:121], v[136:137], v[178:179]
	global_store_dwordx4 v[116:117], v[104:107], off
	v_pk_fma_f32 v[102:103], v[102:103], v[134:135], v[218:219]
	v_pk_fma_f32 v[100:101], v[100:101], v[132:133], v[216:217]
	v_pk_fma_f32 v[106:107], v[110:111], v[138:139], v[214:215]
	v_pk_fma_f32 v[104:105], v[108:109], v[136:137], v[212:213]
	v_pk_fma_f32 v[98:99], v[98:99], v[130:131], v[222:223]
	v_pk_fma_f32 v[96:97], v[96:97], v[128:129], v[220:221]
	global_store_dwordx4 v[158:159], v[124:127], off
	global_store_dwordx4 v[158:159], v[120:123], off offset:64
	global_store_dwordx4 v[116:117], v[104:107], off offset:64
	global_store_dwordx4 v[116:117], v[100:103], off offset:512
	global_store_dwordx4 v[116:117], v[96:99], off offset:576
	v_or_b32_e32 v174, 0x40000, v224
	v_mov_b32_e32 v175, v225
	v_or_b32_e32 v224, 0x60000, v224
	v_lshl_add_u64 v[108:109], v[190:191], 0, v[174:175]
	v_lshl_add_u64 v[124:125], v[190:191], 0, v[224:225]
	global_load_dwordx4 v[96:99], v[108:109], off
	global_load_dwordx4 v[100:103], v[108:109], off offset:64
	global_load_dwordx4 v[104:107], v[108:109], off offset:512
	s_nop 0
	global_load_dwordx4 v[108:111], v[108:109], off offset:576
	s_nop 0
	global_load_dwordx4 v[112:115], v[124:125], off
	global_load_dwordx4 v[116:119], v[124:125], off offset:64
	global_load_dwordx4 v[120:123], v[124:125], off offset:512
	s_nop 0
	global_load_dwordx4 v[124:127], v[124:125], off offset:576
	v_lshl_add_u64 v[174:175], v[228:229], 0, v[174:175]
	s_waitcnt vmcnt(0)
;     __device__ __forceinline__ void operator()(const f32x4 (&acc)[2][2][4][2], const Unit& u, int wr, int wc, int fr, int fq, int lane) const {
;     ...
; #pragma unroll
;         for (int ai = 0; ai < 2; ++ai)
; #pragma unroll
;           for (int mh = 0; mh < 2; ++mh) {
;             f32x4 bs[2][2][2];
; #pragma unroll
;             for (int m2 = 0; m2 < 2; ++m2) {
;                 const size_t ro = (r0 + ai * HALF + wr * 64 + (mh * 2 + m2) * 16 + fr) * (size_t)D;
; #pragma unroll
;                 for (int bj = 0; bj < 2; ++bj)
; #pragma unroll
;                     for (int n = 0; n < 2; ++n) bs[m2][bj][n] = *(const f32x4*)(base + ro + bj * HALF + n * 16);
;             }
;             __builtin_amdgcn_sched_barrier(0);
; #pragma unroll
;             for (int m2 = 0; m2 < 2; ++m2) {
;                 const size_t ro = (r0 + ai * HALF + wr * 64 + (mh * 2 + m2) * 16 + fr) * (size_t)D;
; #pragma unroll
;                 for (int bj = 0; bj < 2; ++bj)
; #pragma unroll
;                     for (int n = 0; n < 2; ++n) *(f32x4*)(out + ro + bj * HALF + n * 16) = bs[m2][bj][n] + gv[bj][n] * acc[ai][bj][mh * 2 + m2][n];
;             }
;             __builtin_amdgcn_sched_barrier(0);
;           }
	v_pk_fma_f32 v[82:83], v[82:83], v[134:135], v[106:107]
	v_pk_fma_f32 v[80:81], v[80:81], v[132:133], v[104:105]
	v_pk_fma_f32 v[74:75], v[74:75], v[130:131], v[110:111]
	v_pk_fma_f32 v[72:73], v[72:73], v[128:129], v[108:109]
	global_store_dwordx4 v[174:175], v[80:83], off offset:512
	global_store_dwordx4 v[174:175], v[72:75], off offset:576
	v_pk_fma_f32 v[94:95], v[94:95], v[142:143], v[98:99]
	v_lshl_add_u64 v[80:81], v[228:229], 0, v[224:225]
	v_pk_fma_f32 v[74:75], v[86:87], v[142:143], v[114:115]
	v_pk_fma_f32 v[72:73], v[84:85], v[140:141], v[112:113]
	v_pk_fma_f32 v[92:93], v[92:93], v[140:141], v[96:97]
	v_pk_fma_f32 v[90:91], v[90:91], v[138:139], v[102:103]
	v_pk_fma_f32 v[88:89], v[88:89], v[136:137], v[100:101]
	global_store_dwordx4 v[80:81], v[72:75], off
	v_pk_fma_f32 v[70:71], v[70:71], v[134:135], v[122:123]
	v_pk_fma_f32 v[68:69], v[68:69], v[132:133], v[120:121]
	v_pk_fma_f32 v[74:75], v[78:79], v[138:139], v[118:119]
	v_pk_fma_f32 v[72:73], v[76:77], v[136:137], v[116:117]
	v_pk_fma_f32 v[66:67], v[66:67], v[130:131], v[126:127]
	v_pk_fma_f32 v[64:65], v[64:65], v[128:129], v[124:125]
	global_store_dwordx4 v[174:175], v[92:95], off
	global_store_dwordx4 v[174:175], v[88:91], off offset:64
	global_store_dwordx4 v[80:81], v[72:75], off offset:64
	global_store_dwordx4 v[80:81], v[68:71], off offset:512
	global_store_dwordx4 v[80:81], v[64:67], off offset:576
	s_mov_b32 s3, 0x100000
	v_add_co_u32_e32 v72, vcc, s3, v168
	s_mov_b32 s8, 0x120000
	s_nop 0
	v_addc_co_u32_e32 v73, vcc, 0, v169, vcc
	s_mov_b64 s[0:1], 0x100000
	s_mov_b64 s[10:11], 0x120000
	v_add_co_u32_e32 v88, vcc, s8, v168
	v_lshl_add_u64 v[76:77], v[168:169], 0, s[0:1]
	v_lshl_add_u64 v[92:93], v[168:169], 0, s[10:11]
	v_addc_co_u32_e32 v89, vcc, 0, v169, vcc
	global_load_dwordx4 v[64:67], v[76:77], off offset:64
	global_load_dwordx4 v[68:71], v[76:77], off offset:512
	s_nop 0
	global_load_dwordx4 v[72:75], v[72:73], off
	s_nop 0
	global_load_dwordx4 v[76:79], v[76:77], off offset:576
	s_nop 0
	global_load_dwordx4 v[80:83], v[92:93], off offset:64
	global_load_dwordx4 v[84:87], v[92:93], off offset:512
	s_nop 0
	global_load_dwordx4 v[88:91], v[88:89], off
	s_nop 0
	global_load_dwordx4 v[92:95], v[92:93], off offset:576
	s_waitcnt vmcnt(0)
	v_pk_fma_f32 v[60:61], v[60:61], v[140:141], v[72:73]
	v_add_co_u32_e32 v72, vcc, s3, v158
	v_lshl_add_u64 v[96:97], v[158:159], 0, s[0:1]
	s_nop 0
	v_addc_co_u32_e32 v73, vcc, 0, v159, vcc
	v_pk_fma_f32 v[50:51], v[50:51], v[134:135], v[70:71]
	v_pk_fma_f32 v[48:49], v[48:49], v[132:133], v[68:69]
	global_store_dwordx4 v[96:97], v[48:51], off offset:512
	v_pk_fma_f32 v[46:47], v[46:47], v[130:131], v[78:79]
	v_pk_fma_f32 v[44:45], v[44:45], v[128:129], v[76:77]
	v_add_co_u32_e32 v50, vcc, s8, v158
	s_mov_b64 s[74:75], 0x100000
	v_pk_fma_f32 v[62:63], v[62:63], v[142:143], v[74:75]
	s_mov_b32 s76, 0x100000
	v_pk_fma_f32 v[58:59], v[58:59], v[138:139], v[66:67]
	v_pk_fma_f32 v[56:57], v[56:57], v[136:137], v[64:65]
	global_store_dwordx4 v[96:97], v[44:47], off offset:576
	v_lshl_add_u64 v[48:49], v[158:159], 0, s[10:11]
	s_mov_b32 s77, 0x120000
	v_pk_fma_f32 v[46:47], v[54:55], v[142:143], v[90:91]
	v_pk_fma_f32 v[44:45], v[52:53], v[140:141], v[88:89]
	v_addc_co_u32_e32 v51, vcc, 0, v159, vcc
	v_pk_fma_f32 v[42:43], v[42:43], v[138:139], v[82:83]
	v_pk_fma_f32 v[40:41], v[40:41], v[136:137], v[80:81]
	v_pk_fma_f32 v[38:39], v[38:39], v[134:135], v[86:87]
	v_pk_fma_f32 v[36:37], v[36:37], v[132:133], v[84:85]
	v_pk_fma_f32 v[34:35], v[34:35], v[130:131], v[94:95]
	v_pk_fma_f32 v[32:33], v[32:33], v[128:129], v[92:93]
	global_store_dwordx4 v[72:73], v[60:63], off
	global_store_dwordx4 v[96:97], v[56:59], off offset:64
	global_store_dwordx4 v[50:51], v[44:47], off
	global_store_dwordx4 v[48:49], v[40:43], off offset:64
	global_store_dwordx4 v[48:49], v[36:39], off offset:512
	global_store_dwordx4 v[48:49], v[32:35], off offset:576
	s_mov_b32 s0, 0x140000
	v_add_co_u32_e32 v40, vcc, s0, v168
	s_mov_b32 s1, 0x160000
	s_nop 0
	v_addc_co_u32_e32 v41, vcc, 0, v169, vcc
	s_mov_b64 s[8:9], 0x140000
	s_mov_b64 s[10:11], 0x160000
	v_add_co_u32_e32 v56, vcc, s1, v168
	v_lshl_add_u64 v[44:45], v[168:169], 0, s[8:9]
	v_lshl_add_u64 v[60:61], v[168:169], 0, s[10:11]
	v_addc_co_u32_e32 v57, vcc, 0, v169, vcc
	global_load_dwordx4 v[32:35], v[44:45], off offset:64
	global_load_dwordx4 v[36:39], v[44:45], off offset:512
	s_nop 0
	global_load_dwordx4 v[40:43], v[40:41], off
	s_nop 0
	global_load_dwordx4 v[44:47], v[44:45], off offset:576
	s_nop 0
	global_load_dwordx4 v[48:51], v[60:61], off offset:64
	global_load_dwordx4 v[52:55], v[60:61], off offset:512
	s_nop 0
	global_load_dwordx4 v[56:59], v[56:57], off
	s_nop 0
	global_load_dwordx4 v[60:63], v[60:61], off offset:576
	s_waitcnt vmcnt(0)
	v_pk_fma_f32 v[28:29], v[28:29], v[140:141], v[40:41]
	v_add_co_u32_e32 v40, vcc, s0, v158
	v_lshl_add_u64 v[64:65], v[158:159], 0, s[8:9]
	s_nop 0
	v_addc_co_u32_e32 v41, vcc, 0, v159, vcc
	v_pk_fma_f32 v[18:19], v[18:19], v[134:135], v[38:39]
	v_pk_fma_f32 v[16:17], v[16:17], v[132:133], v[36:37]
	global_store_dwordx4 v[64:65], v[16:19], off offset:512
	v_pk_fma_f32 v[14:15], v[14:15], v[130:131], v[46:47]
	v_pk_fma_f32 v[12:13], v[12:13], v[128:129], v[44:45]
	v_add_co_u32_e32 v18, vcc, s1, v158
	v_pk_fma_f32 v[30:31], v[30:31], v[142:143], v[42:43]
	s_mov_b32 s18, 0x140000
	v_pk_fma_f32 v[26:27], v[26:27], v[138:139], v[34:35]
	v_pk_fma_f32 v[24:25], v[24:25], v[136:137], v[32:33]
	global_store_dwordx4 v[64:65], v[12:15], off offset:576
	v_lshl_add_u64 v[16:17], v[158:159], 0, s[10:11]
	s_mov_b32 s54, 0x160000
	v_pk_fma_f32 v[14:15], v[22:23], v[142:143], v[58:59]
	v_pk_fma_f32 v[12:13], v[20:21], v[140:141], v[56:57]
	v_addc_co_u32_e32 v19, vcc, 0, v159, vcc
	v_pk_fma_f32 v[10:11], v[10:11], v[138:139], v[50:51]
	v_pk_fma_f32 v[8:9], v[8:9], v[136:137], v[48:49]
	v_pk_fma_f32 v[6:7], v[6:7], v[134:135], v[54:55]
	v_pk_fma_f32 v[4:5], v[4:5], v[132:133], v[52:53]
	v_pk_fma_f32 v[2:3], v[2:3], v[130:131], v[62:63]
	v_pk_fma_f32 v[0:1], v[0:1], v[128:129], v[60:61]
	global_store_dwordx4 v[40:41], v[28:31], off
	global_store_dwordx4 v[64:65], v[24:27], off offset:64
	global_store_dwordx4 v[18:19], v[12:15], off
	global_store_dwordx4 v[16:17], v[8:11], off offset:64
	global_store_dwordx4 v[16:17], v[4:7], off offset:512
	global_store_dwordx4 v[16:17], v[0:3], off offset:576
	s_and_b64 vcc, exec, s[40:41]
	s_mov_b32 s8, s2
	s_mov_b32 s9, s26
	s_mov_b64 s[20:21], s[38:39]
	s_mov_b64 s[0:1], s[36:37]
	s_cbranch_vccz .LBB0_1226
	s_waitcnt vmcnt(0)
	v_readlane_b32 s52, v255, 4
	s_cmpk_gt_u32 s4, 0xff
	v_readlane_b32 s53, v255, 5
	s_cbranch_scc1 .LBB0_1233
	s_barrier
